# LP1 + remaining 32 kernel-arg pointer reload sites converted to v251 lane reads (q_norm/k_norm gain-load chains no longer serialized on LDS round trips)
# baseline (speedup 1.0000x reference)
; #define LAS __attribute__((address_space(3)))
; #define PIN(i) ((const float*)ldq_(L, (i)))
; __device__ __forceinline__ unsigned pk2(float lo, float hi) { f32x2 v = {lo, hi}; bf16x2_t b = __builtin_convertvector(v, bf16x2_t); return __builtin_bit_cast(unsigned, b); }
; #define PREP_CONV(bit, SRC, Kd, Nd, DST, GK, MODE) if (mask & (bit)) { for (int it = gw; it < ((Kd) / 64) * ((Nd) / 64); it += NGW) transpose_item((SRC), (Kd), (Nd), (bf16_t*)(wl + (DST)), (GK), (MODE), scr, it, lane); }
; __device__ __forceinline__ void transpose_item(const float* W, int K, int N, bf16_t* WT, const float* gk, int mode, LAS float* scr_, int item, int lane) {
;     LAS unsigned* scr = (LAS unsigned*)scr_;
;     const int nblk = N / 64, kb = item / nblk, nb = item % nblk, k0 = 64 * kb, n0 = 64 * nb;
;     const int sc = (mode == 1) ? (((n0 >> 7) & 1) * DFF + (n0 >> 8) * 128 + (n0 & 127)) : n0;
;     const float* src = W + (size_t)k0 * N + sc + lane;
;     float va[32], vb[32];
; #pragma unroll
;     for (int kp = 0; kp < 32; ++kp) { va[kp] = src[(size_t)(2 * kp) * N]; vb[kp] = src[(size_t)(2 * kp + 1) * N]; }
; #pragma unroll
;     for (int kp = 0; kp < 32; ++kp) {
;         float a = va[kp], b = vb[kp];
;         if (gk) { a *= gk[k0 + 2 * kp]; b *= gk[k0 + 2 * kp + 1]; }
;         scr[kp * 65 + lane] = pk2(a, b);
; __device__ __forceinline__ void prep(const Params& p, LAS unsigned char* L, int wv, int vb, int nvb, int l, int mask) {
;     ...
;     PREP_CONV(PM_FFA_IN, PIN(I_WFFA_IN) + (size_t)l * DM * NFF2, DM, NFF2, WL_FFA_IN, PIN(I_NFFA) + l * DM, 1)
.LBB0_15:
	v_mov_b32_e32 v6, 0
	s_mul_hi_i32 s0, s88, 0x2e8ba2e9
	v_add_u32_e32 v6, 0, v6
	v_add_u32_e32 v6, 0x20140, v6
	s_lshr_b32 s6, s0, 31
	s_ashr_i32 s0, s0, 4
	s_nop 0
	s_add_i32 s13, s0, s6
	s_mul_i32 s0, s13, 0xffffea00
	s_mul_i32 s7, s13, 0xfffff500
	s_add_i32 s89, s16, s0
	s_bfe_i32 s0, s88, 0x10001
	s_add_i32 s7, s18, s7
	s_and_b32 s0, s0, 0xb00
	s_and_b32 s7, s7, 0xffffff80
	s_lshl_b32 s6, s13, 6
	s_add_i32 s0, s0, s7
	s_and_b32 s7, s89, 64
	s_waitcnt lgkmcnt(0)
	v_readlane_b32 s12, v251, 16
	s_or_b32 s0, s0, s7
	s_ashr_i32 s7, s6, 31
	s_mul_i32 s13, s13, 0x160000
	v_readlane_b32 s1, v251, 17
	s_mul_hi_i32 s14, s6, 0x5800
	s_add_u32 s12, s12, s13
	v_mov_b32_e32 v8, 0
	s_addc_u32 s13, s1, s14
	s_ashr_i32 s1, s0, 31
	s_lshl_b64 s[0:1], s[0:1], 2
	v_add_u32_e32 v8, 0, v8
	s_add_u32 s0, s12, s0
	v_add_u32_e32 v6, 0x20138, v8
	s_addc_u32 s1, s13, s1
	s_nop 0
	v_lshl_add_u64 v[6:7], s[0:1], 0, v[2:3]
	v_add_co_u32_e32 v8, vcc, s23, v6
	s_waitcnt lgkmcnt(0)
	v_readlane_b32 s13, v251, 15
	v_addc_co_u32_e32 v9, vcc, 0, v7, vcc
	v_add_co_u32_e32 v10, vcc, s24, v6
	v_readlane_b32 s12, v251, 14
	s_nop 0
	v_addc_co_u32_e32 v11, vcc, 0, v7, vcc
	v_add_co_u32_e32 v12, vcc, s25, v6
	s_cmp_lg_u64 s[12:13], 0
	s_nop 0
	v_addc_co_u32_e32 v13, vcc, 0, v7, vcc
	v_add_co_u32_e32 v14, vcc, s26, v6
	s_cselect_b64 s[14:15], -1, 0
	s_nop 0
	v_addc_co_u32_e32 v15, vcc, 0, v7, vcc
	v_add_co_u32_e32 v16, vcc, s27, v6
	s_cmp_eq_u64 s[12:13], 0
	s_nop 0
	v_addc_co_u32_e32 v17, vcc, 0, v7, vcc
	v_add_co_u32_e32 v18, vcc, s28, v6
	s_nop 1
	v_addc_co_u32_e32 v19, vcc, 0, v7, vcc
	v_add_co_u32_e32 v20, vcc, s29, v6
	s_nop 1
	v_addc_co_u32_e32 v21, vcc, 0, v7, vcc
	v_add_co_u32_e32 v22, vcc, s30, v6
	s_nop 1
	v_addc_co_u32_e32 v23, vcc, 0, v7, vcc
	global_load_dword v73, v[8:9], off offset:2048
	global_load_dword v70, v[10:11], off
	global_load_dword v71, v[12:13], off offset:2048
	global_load_dword v64, v[14:15], off
	global_load_dword v65, v[16:17], off offset:2048
	global_load_dword v66, v[18:19], off
	global_load_dword v67, v[20:21], off offset:2048
	global_load_dword v60, v[22:23], off
	v_add_co_u32_e32 v8, vcc, s31, v6
	s_nop 1
	v_addc_co_u32_e32 v9, vcc, 0, v7, vcc
	v_add_co_u32_e32 v10, vcc, s34, v6
	s_nop 1
	v_addc_co_u32_e32 v11, vcc, 0, v7, vcc
	v_add_co_u32_e32 v12, vcc, s35, v6
	s_nop 1
	v_addc_co_u32_e32 v13, vcc, 0, v7, vcc
	v_add_co_u32_e32 v14, vcc, s36, v6
	s_nop 1
	v_addc_co_u32_e32 v15, vcc, 0, v7, vcc
	v_add_co_u32_e32 v16, vcc, s37, v6
	s_nop 1
	v_addc_co_u32_e32 v17, vcc, 0, v7, vcc
	v_add_co_u32_e32 v18, vcc, s38, v6
	s_nop 1
	v_addc_co_u32_e32 v19, vcc, 0, v7, vcc
	v_add_co_u32_e32 v20, vcc, s39, v6
	s_nop 1
	v_addc_co_u32_e32 v21, vcc, 0, v7, vcc
	v_add_co_u32_e32 v22, vcc, s40, v6
	s_nop 1
	v_addc_co_u32_e32 v23, vcc, 0, v7, vcc
	global_load_dword v61, v[8:9], off offset:2048
	global_load_dword v62, v[10:11], off
	global_load_dword v63, v[12:13], off offset:2048
	global_load_dword v56, v[14:15], off
	global_load_dword v57, v[16:17], off offset:2048
	global_load_dword v58, v[18:19], off
	global_load_dword v59, v[20:21], off offset:2048
	global_load_dword v52, v[22:23], off
	v_add_co_u32_e32 v8, vcc, s41, v6
	s_nop 1
	v_addc_co_u32_e32 v9, vcc, 0, v7, vcc
	v_add_co_u32_e32 v10, vcc, s42, v6
	s_nop 1
	v_addc_co_u32_e32 v11, vcc, 0, v7, vcc
	v_add_co_u32_e32 v12, vcc, s43, v6
	s_nop 1
	v_addc_co_u32_e32 v13, vcc, 0, v7, vcc
	v_add_co_u32_e32 v14, vcc, s44, v6
	s_nop 1
	v_addc_co_u32_e32 v15, vcc, 0, v7, vcc
	v_add_co_u32_e32 v16, vcc, s45, v6
	s_nop 1
	v_addc_co_u32_e32 v17, vcc, 0, v7, vcc
	v_add_co_u32_e32 v18, vcc, s46, v6
	s_nop 1
	v_addc_co_u32_e32 v19, vcc, 0, v7, vcc
	v_add_co_u32_e32 v20, vcc, s47, v6
	s_nop 1
	v_addc_co_u32_e32 v21, vcc, 0, v7, vcc
	v_add_co_u32_e32 v22, vcc, s48, v6
	s_nop 1
	v_addc_co_u32_e32 v23, vcc, 0, v7, vcc
	global_load_dword v53, v[8:9], off offset:2048
	global_load_dword v54, v[10:11], off
	global_load_dword v55, v[12:13], off offset:2048
	global_load_dword v48, v[14:15], off
	global_load_dword v49, v[16:17], off offset:2048
	global_load_dword v50, v[18:19], off
	global_load_dword v51, v[20:21], off offset:2048
	global_load_dword v44, v[22:23], off
	v_add_co_u32_e32 v8, vcc, s49, v6
	s_nop 1
	v_addc_co_u32_e32 v9, vcc, 0, v7, vcc
	v_add_co_u32_e32 v10, vcc, s50, v6
	s_nop 1
	v_addc_co_u32_e32 v11, vcc, 0, v7, vcc
	v_add_co_u32_e32 v12, vcc, s51, v6
	s_nop 1
	v_addc_co_u32_e32 v13, vcc, 0, v7, vcc
	v_add_co_u32_e32 v14, vcc, s52, v6
	s_nop 1
	v_addc_co_u32_e32 v15, vcc, 0, v7, vcc
	v_add_co_u32_e32 v16, vcc, s53, v6
	s_nop 1
	v_addc_co_u32_e32 v17, vcc, 0, v7, vcc
	v_add_co_u32_e32 v18, vcc, s54, v6
	s_nop 1
	v_addc_co_u32_e32 v19, vcc, 0, v7, vcc
	v_add_co_u32_e32 v20, vcc, s55, v6
	s_nop 1
	v_addc_co_u32_e32 v21, vcc, 0, v7, vcc
	v_add_co_u32_e32 v22, vcc, s56, v6
; __device__ __forceinline__ void transpose_item(const float* W, int K, int N, bf16_t* WT, const float* gk, int mode, LAS float* scr_, int item, int lane) {
;     ...
;     for (int kp = 0; kp < 32; ++kp) { va[kp] = src[(size_t)(2 * kp) * N]; vb[kp] = src[(size_t)(2 * kp + 1) * N]; }
; #pragma unroll
;     for (int kp = 0; kp < 32; ++kp) {
;         float a = va[kp], b = vb[kp];
;         if (gk) { a *= gk[k0 + 2 * kp]; b *= gk[k0 + 2 * kp + 1]; }
	s_nop 1
	v_addc_co_u32_e32 v23, vcc, 0, v7, vcc
	global_load_dword v45, v[8:9], off offset:2048
	global_load_dword v46, v[10:11], off
	global_load_dword v47, v[12:13], off offset:2048
	global_load_dword v40, v[14:15], off
	global_load_dword v41, v[16:17], off offset:2048
	global_load_dword v42, v[18:19], off
	global_load_dword v43, v[20:21], off offset:2048
	global_load_dword v36, v[22:23], off
	v_add_co_u32_e32 v8, vcc, s57, v6
	s_nop 1
	v_addc_co_u32_e32 v9, vcc, 0, v7, vcc
	v_add_co_u32_e32 v10, vcc, s58, v6
	s_nop 1
	v_addc_co_u32_e32 v11, vcc, 0, v7, vcc
	v_add_co_u32_e32 v12, vcc, s59, v6
	s_nop 1
	v_addc_co_u32_e32 v13, vcc, 0, v7, vcc
	v_add_co_u32_e32 v14, vcc, s61, v6
	s_nop 1
	v_addc_co_u32_e32 v15, vcc, 0, v7, vcc
	v_add_co_u32_e32 v16, vcc, s62, v6
	s_nop 1
	v_addc_co_u32_e32 v17, vcc, 0, v7, vcc
	v_add_co_u32_e32 v18, vcc, s63, v6
	s_nop 1
	v_addc_co_u32_e32 v19, vcc, 0, v7, vcc
	v_add_co_u32_e32 v20, vcc, s65, v6
	s_nop 1
	v_addc_co_u32_e32 v21, vcc, 0, v7, vcc
	v_add_co_u32_e32 v22, vcc, s66, v6
	s_nop 1
	v_addc_co_u32_e32 v23, vcc, 0, v7, vcc
	global_load_dword v37, v[8:9], off offset:2048
	global_load_dword v38, v[10:11], off
	global_load_dword v39, v[12:13], off offset:2048
	global_load_dword v32, v[14:15], off
	global_load_dword v33, v[16:17], off offset:2048
	global_load_dword v34, v[18:19], off
	global_load_dword v35, v[20:21], off offset:2048
	global_load_dword v28, v[22:23], off
	v_add_co_u32_e32 v8, vcc, s67, v6
	s_nop 1
	v_addc_co_u32_e32 v9, vcc, 0, v7, vcc
	v_add_co_u32_e32 v10, vcc, s68, v6
	s_nop 1
	v_addc_co_u32_e32 v11, vcc, 0, v7, vcc
	v_add_co_u32_e32 v12, vcc, s69, v6
	s_nop 1
	v_addc_co_u32_e32 v13, vcc, 0, v7, vcc
	v_add_co_u32_e32 v14, vcc, s70, v6
	s_nop 1
	v_addc_co_u32_e32 v15, vcc, 0, v7, vcc
	v_add_co_u32_e32 v16, vcc, s71, v6
	s_nop 1
	v_addc_co_u32_e32 v17, vcc, 0, v7, vcc
	v_add_co_u32_e32 v18, vcc, s72, v6
	s_nop 1
	v_addc_co_u32_e32 v19, vcc, 0, v7, vcc
	v_add_co_u32_e32 v20, vcc, s73, v6
	s_nop 1
	v_addc_co_u32_e32 v21, vcc, 0, v7, vcc
	v_add_co_u32_e32 v74, vcc, s74, v6
	s_nop 1
	v_addc_co_u32_e32 v75, vcc, 0, v7, vcc
	global_load_dword v29, v[8:9], off offset:2048
	global_load_dword v30, v[10:11], off
	global_load_dword v31, v[12:13], off offset:2048
	global_load_dword v22, v[14:15], off
	global_load_dword v23, v[16:17], off offset:2048
	global_load_dword v24, v[18:19], off
	global_load_dword v25, v[20:21], off offset:2048
	s_nop 0
	global_load_dword v18, v[74:75], off
	v_add_co_u32_e32 v8, vcc, s75, v6
	s_nop 1
	v_addc_co_u32_e32 v9, vcc, 0, v7, vcc
	v_add_co_u32_e32 v10, vcc, s76, v6
	s_nop 1
	v_addc_co_u32_e32 v11, vcc, 0, v7, vcc
	v_add_co_u32_e32 v12, vcc, s77, v6
	s_nop 1
	v_addc_co_u32_e32 v13, vcc, 0, v7, vcc
	v_add_co_u32_e32 v14, vcc, s78, v6
	s_nop 1
	v_addc_co_u32_e32 v15, vcc, 0, v7, vcc
	v_add_co_u32_e32 v16, vcc, s79, v6
	s_nop 1
	v_addc_co_u32_e32 v17, vcc, 0, v7, vcc
	v_add_co_u32_e32 v74, vcc, s80, v6
	s_nop 1
	v_addc_co_u32_e32 v75, vcc, 0, v7, vcc
	v_add_co_u32_e32 v80, vcc, s81, v6
	s_nop 1
	v_addc_co_u32_e32 v81, vcc, 0, v7, vcc
	v_add_co_u32_e32 v82, vcc, s82, v6
	s_nop 1
	v_addc_co_u32_e32 v83, vcc, 0, v7, vcc
	global_load_dword v19, v[8:9], off offset:2048
	global_load_dword v20, v[10:11], off
	global_load_dword v21, v[12:13], off offset:2048
	s_nop 0
	global_load_dword v14, v[14:15], off
	s_nop 0
	global_load_dword v15, v[16:17], off offset:2048
	s_nop 0
	global_load_dword v16, v[74:75], off
	global_load_dword v17, v[80:81], off offset:2048
	global_load_dword v10, v[82:83], off
	v_add_co_u32_e32 v8, vcc, s83, v6
	s_nop 1
	v_addc_co_u32_e32 v9, vcc, 0, v7, vcc
	v_add_co_u32_e32 v12, vcc, s84, v6
	s_nop 1
	v_addc_co_u32_e32 v13, vcc, 0, v7, vcc
	v_add_co_u32_e32 v74, vcc, s85, v6
	s_nop 1
	v_addc_co_u32_e32 v75, vcc, 0, v7, vcc
	v_add_co_u32_e32 v80, vcc, s86, v6
	s_nop 1
	v_addc_co_u32_e32 v81, vcc, 0, v7, vcc
	v_add_co_u32_e32 v82, vcc, s87, v6
	s_nop 1
	v_addc_co_u32_e32 v83, vcc, 0, v7, vcc
	v_add_co_u32_e32 v84, vcc, 0x155000, v6
	s_nop 1
	v_addc_co_u32_e32 v85, vcc, 0, v7, vcc
	v_add_co_u32_e32 v86, vcc, 0x15a000, v6
	s_nop 1
	v_addc_co_u32_e32 v87, vcc, 0, v7, vcc
	global_load_dword v72, v2, s[0:1]
	global_load_dword v11, v[8:9], off offset:2048
	s_nop 0
	global_load_dword v12, v[12:13], off
	s_nop 0
	global_load_dword v13, v[74:75], off offset:2048
	global_load_dword v6, v[80:81], off
	global_load_dword v7, v[82:83], off offset:2048
	global_load_dword v8, v[84:85], off
	global_load_dword v9, v[86:87], off offset:2048
	s_mov_b64 s[0:1], -1
	s_cbranch_scc1 .LBB0_17
	s_lshl_b64 s[0:1], s[6:7], 2
	s_add_u32 s0, s12, s0
	s_addc_u32 s1, s13, s1
	global_load_dwordx4 v[80:83], v3, s[0:1]
	s_mov_b64 s[0:1], 0
	s_waitcnt vmcnt(0)
	v_pk_mul_f32 v[68:69], v[72:73], v[80:81]
	v_pk_mul_f32 v[74:75], v[70:71], v[82:83]

; #define LAS __attribute__((address_space(3)))
; #define PIN(i) ((const float*)ldq_(L, (i)))
; __device__ __forceinline__ unsigned pk2(float lo, float hi) { f32x2 v = {lo, hi}; bf16x2_t b = __builtin_convertvector(v, bf16x2_t); return __builtin_bit_cast(unsigned, b); }
; #define PREP_CONV(bit, SRC, Kd, Nd, DST, GK, MODE) if (mask & (bit)) { for (int it = gw; it < ((Kd) / 64) * ((Nd) / 64); it += NGW) transpose_item((SRC), (Kd), (Nd), (bf16_t*)(wl + (DST)), (GK), (MODE), scr, it, lane); }
; __device__ __forceinline__ void transpose_item(const float* W, int K, int N, bf16_t* WT, const float* gk, int mode, LAS float* scr_, int item, int lane) {
;     LAS unsigned* scr = (LAS unsigned*)scr_;
;     const int nblk = N / 64, kb = item / nblk, nb = item % nblk, k0 = 64 * kb, n0 = 64 * nb;
;     const int sc = (mode == 1) ? (((n0 >> 7) & 1) * DFF + (n0 >> 8) * 128 + (n0 & 127)) : n0;
;     const float* src = W + (size_t)k0 * N + sc + lane;
;     float va[32], vb[32];
; #pragma unroll
;     for (int kp = 0; kp < 32; ++kp) { va[kp] = src[(size_t)(2 * kp) * N]; vb[kp] = src[(size_t)(2 * kp + 1) * N]; }
; #pragma unroll
;     for (int kp = 0; kp < 32; ++kp) {
;         float a = va[kp], b = vb[kp];
;         if (gk) { a *= gk[k0 + 2 * kp]; b *= gk[k0 + 2 * kp + 1]; }
;         scr[kp * 65 + lane] = pk2(a, b);
; __device__ __forceinline__ void prep(const Params& p, LAS unsigned char* L, int wv, int vb, int nvb, int l, int mask) {
;     ...
;     PREP_CONV(PM_WIN, PIN(I_WIN) + (size_t)l * DM * NIN, DM, NIN, WL_IN, PIN(I_NMIX) + l * DM, 0)
.LBB0_85:
	v_mov_b32_e32 v6, 0
	s_mul_hi_i32 s12, s92, 0x66666667
	v_add_u32_e32 v6, 0, v6
	v_add_u32_e32 v6, 0x20158, v6
	s_nop 0
	s_lshr_b32 s13, s12, 31
	s_ashr_i32 s12, s12, 3
	s_add_i32 s13, s12, s13
	s_lshl_b32 s14, s13, 6
	s_mul_i32 s12, s13, 0xfffffb00
	s_waitcnt lgkmcnt(0)
	v_readlane_b32 s1, v251, 22
	s_add_i32 s12, s24, s12
	s_ashr_i32 s15, s14, 31
	s_mul_i32 s13, s13, 0x50000
	v_readlane_b32 s0, v251, 23
	s_mul_hi_i32 s16, s14, 0x1400
	s_add_u32 s17, s1, s13
	v_mov_b32_e32 v8, 0
	s_addc_u32 s16, s0, s16
	s_ashr_i32 s13, s12, 31
	s_lshl_b64 s[0:1], s[12:13], 2
	v_add_u32_e32 v8, 0, v8
	s_add_u32 s0, s17, s0
	v_add_u32_e32 v6, 0x20150, v8
	s_addc_u32 s1, s16, s1
	s_nop 0
	v_lshl_add_u64 v[6:7], s[0:1], 0, v[2:3]
	v_add_co_u32_e32 v8, vcc, s26, v6
	s_waitcnt lgkmcnt(0)
	v_readlane_b32 s17, v251, 21
	v_addc_co_u32_e32 v9, vcc, 0, v7, vcc
	v_add_co_u32_e32 v10, vcc, s27, v6
	v_readlane_b32 s16, v251, 20
	s_nop 0
	v_addc_co_u32_e32 v11, vcc, 0, v7, vcc
	v_add_co_u32_e32 v12, vcc, s28, v6
	s_cmp_lg_u64 s[16:17], 0
	s_nop 0
	v_addc_co_u32_e32 v13, vcc, 0, v7, vcc
	v_add_co_u32_e32 v14, vcc, s29, v6
	s_cselect_b64 s[18:19], -1, 0
	s_nop 0
	v_addc_co_u32_e32 v15, vcc, 0, v7, vcc
	v_add_co_u32_e32 v16, vcc, s30, v6
	s_cmp_eq_u64 s[16:17], 0
	s_nop 0
	v_addc_co_u32_e32 v17, vcc, 0, v7, vcc
	v_add_co_u32_e32 v18, vcc, s31, v6
	s_nop 1
	v_addc_co_u32_e32 v19, vcc, 0, v7, vcc
	v_add_co_u32_e32 v20, vcc, s34, v6
	s_nop 1
	v_addc_co_u32_e32 v21, vcc, 0, v7, vcc
	v_add_co_u32_e32 v22, vcc, s35, v6
	s_nop 1
	v_addc_co_u32_e32 v23, vcc, 0, v7, vcc
	global_load_dword v73, v[8:9], off offset:1024
	global_load_dword v70, v[10:11], off offset:2048
	global_load_dword v71, v[12:13], off offset:3072
	global_load_dword v64, v[14:15], off
	global_load_dword v65, v[16:17], off offset:1024
	global_load_dword v66, v[18:19], off offset:2048
	global_load_dword v67, v[20:21], off offset:3072
	global_load_dword v60, v[22:23], off
	v_add_co_u32_e32 v8, vcc, s36, v6
	s_nop 1
	v_addc_co_u32_e32 v9, vcc, 0, v7, vcc
	v_add_co_u32_e32 v10, vcc, s37, v6
	s_nop 1
	v_addc_co_u32_e32 v11, vcc, 0, v7, vcc
	v_add_co_u32_e32 v12, vcc, s38, v6
	s_nop 1
	v_addc_co_u32_e32 v13, vcc, 0, v7, vcc
	v_add_co_u32_e32 v14, vcc, s39, v6
	s_nop 1
	v_addc_co_u32_e32 v15, vcc, 0, v7, vcc
	v_add_co_u32_e32 v16, vcc, s40, v6
	s_nop 1
	v_addc_co_u32_e32 v17, vcc, 0, v7, vcc
	v_add_co_u32_e32 v18, vcc, s41, v6
	s_nop 1
	v_addc_co_u32_e32 v19, vcc, 0, v7, vcc
	v_add_co_u32_e32 v20, vcc, s42, v6
	s_nop 1
	v_addc_co_u32_e32 v21, vcc, 0, v7, vcc
	v_add_co_u32_e32 v22, vcc, s43, v6
	s_nop 1
	v_addc_co_u32_e32 v23, vcc, 0, v7, vcc
	global_load_dword v61, v[8:9], off offset:1024
	global_load_dword v62, v[10:11], off offset:2048
	global_load_dword v63, v[12:13], off offset:3072
	global_load_dword v56, v[14:15], off
	global_load_dword v57, v[16:17], off offset:1024
	global_load_dword v58, v[18:19], off offset:2048
	global_load_dword v59, v[20:21], off offset:3072
	global_load_dword v52, v[22:23], off
	v_add_co_u32_e32 v8, vcc, s44, v6
	s_nop 1
	v_addc_co_u32_e32 v9, vcc, 0, v7, vcc
	v_add_co_u32_e32 v10, vcc, s45, v6
	s_nop 1
	v_addc_co_u32_e32 v11, vcc, 0, v7, vcc
	v_add_co_u32_e32 v12, vcc, s46, v6
	s_nop 1
	v_addc_co_u32_e32 v13, vcc, 0, v7, vcc
	v_add_co_u32_e32 v14, vcc, s47, v6
	s_nop 1
	v_addc_co_u32_e32 v15, vcc, 0, v7, vcc
	v_add_co_u32_e32 v16, vcc, s48, v6
	s_nop 1
	v_addc_co_u32_e32 v17, vcc, 0, v7, vcc
	v_add_co_u32_e32 v18, vcc, s49, v6
	s_nop 1
	v_addc_co_u32_e32 v19, vcc, 0, v7, vcc
	v_add_co_u32_e32 v20, vcc, s50, v6
	s_nop 1
	v_addc_co_u32_e32 v21, vcc, 0, v7, vcc
	v_add_co_u32_e32 v22, vcc, s51, v6
	s_nop 1
	v_addc_co_u32_e32 v23, vcc, 0, v7, vcc
	global_load_dword v53, v[8:9], off offset:1024
	global_load_dword v54, v[10:11], off offset:2048
	global_load_dword v55, v[12:13], off offset:3072
	global_load_dword v48, v[14:15], off
	global_load_dword v49, v[16:17], off offset:1024
	global_load_dword v50, v[18:19], off offset:2048
	global_load_dword v51, v[20:21], off offset:3072
	global_load_dword v44, v[22:23], off
	v_add_co_u32_e32 v8, vcc, s52, v6
	s_nop 1
	v_addc_co_u32_e32 v9, vcc, 0, v7, vcc
	v_add_co_u32_e32 v10, vcc, s53, v6
	s_nop 1
	v_addc_co_u32_e32 v11, vcc, 0, v7, vcc
	v_add_co_u32_e32 v12, vcc, s54, v6
	s_nop 1
	v_addc_co_u32_e32 v13, vcc, 0, v7, vcc
	v_add_co_u32_e32 v14, vcc, s55, v6
	s_nop 1
	v_addc_co_u32_e32 v15, vcc, 0, v7, vcc
	v_add_co_u32_e32 v16, vcc, s56, v6
	s_nop 1
	v_addc_co_u32_e32 v17, vcc, 0, v7, vcc
	v_add_co_u32_e32 v18, vcc, s57, v6
	s_nop 1
	v_addc_co_u32_e32 v19, vcc, 0, v7, vcc
	v_add_co_u32_e32 v20, vcc, s58, v6
	s_nop 1
	v_addc_co_u32_e32 v21, vcc, 0, v7, vcc
	v_add_co_u32_e32 v22, vcc, s59, v6
	s_nop 1
	v_addc_co_u32_e32 v23, vcc, 0, v7, vcc
	global_load_dword v45, v[8:9], off offset:1024
; __device__ __forceinline__ void transpose_item(const float* W, int K, int N, bf16_t* WT, const float* gk, int mode, LAS float* scr_, int item, int lane) {
;     ...
;     for (int kp = 0; kp < 32; ++kp) { va[kp] = src[(size_t)(2 * kp) * N]; vb[kp] = src[(size_t)(2 * kp + 1) * N]; }
; #pragma unroll
;     for (int kp = 0; kp < 32; ++kp) {
;         float a = va[kp], b = vb[kp];
;         if (gk) { a *= gk[k0 + 2 * kp]; b *= gk[k0 + 2 * kp + 1]; }
	global_load_dword v46, v[10:11], off offset:2048
	global_load_dword v47, v[12:13], off offset:3072
	global_load_dword v40, v[14:15], off
	global_load_dword v41, v[16:17], off offset:1024
	global_load_dword v42, v[18:19], off offset:2048
	global_load_dword v43, v[20:21], off offset:3072
	global_load_dword v36, v[22:23], off
	v_add_co_u32_e32 v8, vcc, s62, v6
	s_nop 1
	v_addc_co_u32_e32 v9, vcc, 0, v7, vcc
	v_add_co_u32_e32 v10, vcc, s63, v6
	s_nop 1
	v_addc_co_u32_e32 v11, vcc, 0, v7, vcc
	v_add_co_u32_e32 v12, vcc, s65, v6
	s_nop 1
	v_addc_co_u32_e32 v13, vcc, 0, v7, vcc
	v_add_co_u32_e32 v14, vcc, s66, v6
	s_nop 1
	v_addc_co_u32_e32 v15, vcc, 0, v7, vcc
	v_add_co_u32_e32 v16, vcc, s67, v6
	s_nop 1
	v_addc_co_u32_e32 v17, vcc, 0, v7, vcc
	v_add_co_u32_e32 v18, vcc, s68, v6
	s_nop 1
	v_addc_co_u32_e32 v19, vcc, 0, v7, vcc
	v_add_co_u32_e32 v20, vcc, s69, v6
	s_nop 1
	v_addc_co_u32_e32 v21, vcc, 0, v7, vcc
	v_add_co_u32_e32 v22, vcc, s70, v6
	s_nop 1
	v_addc_co_u32_e32 v23, vcc, 0, v7, vcc
	global_load_dword v37, v[8:9], off offset:1024
	global_load_dword v38, v[10:11], off offset:2048
	global_load_dword v39, v[12:13], off offset:3072
	global_load_dword v32, v[14:15], off
	global_load_dword v33, v[16:17], off offset:1024
	global_load_dword v34, v[18:19], off offset:2048
	global_load_dword v35, v[20:21], off offset:3072
	global_load_dword v28, v[22:23], off
	v_add_co_u32_e32 v8, vcc, s71, v6
	s_nop 1
	v_addc_co_u32_e32 v9, vcc, 0, v7, vcc
	v_add_co_u32_e32 v10, vcc, s72, v6
	s_nop 1
	v_addc_co_u32_e32 v11, vcc, 0, v7, vcc
	v_add_co_u32_e32 v12, vcc, s73, v6
	s_nop 1
	v_addc_co_u32_e32 v13, vcc, 0, v7, vcc
	v_add_co_u32_e32 v14, vcc, s74, v6
	s_nop 1
	v_addc_co_u32_e32 v15, vcc, 0, v7, vcc
	v_add_co_u32_e32 v16, vcc, s75, v6
	s_nop 1
	v_addc_co_u32_e32 v17, vcc, 0, v7, vcc
	v_add_co_u32_e32 v18, vcc, s76, v6
	s_nop 1
	v_addc_co_u32_e32 v19, vcc, 0, v7, vcc
	v_add_co_u32_e32 v20, vcc, s77, v6
	s_nop 1
	v_addc_co_u32_e32 v21, vcc, 0, v7, vcc
	v_add_co_u32_e32 v74, vcc, s78, v6
	s_nop 1
	v_addc_co_u32_e32 v75, vcc, 0, v7, vcc
	global_load_dword v29, v[8:9], off offset:1024
	global_load_dword v30, v[10:11], off offset:2048
	global_load_dword v31, v[12:13], off offset:3072
	global_load_dword v22, v[14:15], off
	global_load_dword v23, v[16:17], off offset:1024
	global_load_dword v24, v[18:19], off offset:2048
	global_load_dword v25, v[20:21], off offset:3072
	s_nop 0
	global_load_dword v18, v[74:75], off
	v_add_co_u32_e32 v8, vcc, s79, v6
	s_nop 1
	v_addc_co_u32_e32 v9, vcc, 0, v7, vcc
	v_add_co_u32_e32 v10, vcc, s80, v6
	s_nop 1
	v_addc_co_u32_e32 v11, vcc, 0, v7, vcc
	v_add_co_u32_e32 v12, vcc, s81, v6
	s_nop 1
	v_addc_co_u32_e32 v13, vcc, 0, v7, vcc
	v_add_co_u32_e32 v14, vcc, s82, v6
	s_nop 1
	v_addc_co_u32_e32 v15, vcc, 0, v7, vcc
	v_add_co_u32_e32 v16, vcc, s83, v6
	s_nop 1
	v_addc_co_u32_e32 v17, vcc, 0, v7, vcc
	v_add_co_u32_e32 v74, vcc, s84, v6
	s_nop 1
	v_addc_co_u32_e32 v75, vcc, 0, v7, vcc
	v_add_co_u32_e32 v80, vcc, s85, v6
	s_nop 1
	v_addc_co_u32_e32 v81, vcc, 0, v7, vcc
	v_add_co_u32_e32 v82, vcc, s86, v6
	s_nop 1
	v_addc_co_u32_e32 v83, vcc, 0, v7, vcc
	global_load_dword v19, v[8:9], off offset:1024
	global_load_dword v20, v[10:11], off offset:2048
	global_load_dword v21, v[12:13], off offset:3072
	s_nop 0
	global_load_dword v14, v[14:15], off
	s_nop 0
	global_load_dword v15, v[16:17], off offset:1024
	s_nop 0
	global_load_dword v16, v[74:75], off offset:2048
	global_load_dword v17, v[80:81], off offset:3072
	global_load_dword v10, v[82:83], off
	v_add_co_u32_e32 v8, vcc, s87, v6
	s_nop 1
	v_addc_co_u32_e32 v9, vcc, 0, v7, vcc
	v_add_co_u32_e32 v12, vcc, s88, v6
	s_nop 1
	v_addc_co_u32_e32 v13, vcc, 0, v7, vcc
	v_add_co_u32_e32 v74, vcc, s89, v6
	s_nop 1
	v_addc_co_u32_e32 v75, vcc, 0, v7, vcc
	v_add_co_u32_e32 v80, vcc, s90, v6
	s_nop 1
	v_addc_co_u32_e32 v81, vcc, 0, v7, vcc
	v_add_co_u32_e32 v82, vcc, s91, v6
	s_nop 1
	v_addc_co_u32_e32 v83, vcc, 0, v7, vcc
	v_add_co_u32_e32 v84, vcc, 0x4d000, v6
	s_nop 1
	v_addc_co_u32_e32 v85, vcc, 0, v7, vcc
	v_add_co_u32_e32 v86, vcc, 0x4e000, v6
	s_nop 1
	v_addc_co_u32_e32 v87, vcc, 0, v7, vcc
	global_load_dword v72, v2, s[0:1]
	global_load_dword v11, v[8:9], off offset:1024
	s_nop 0
	global_load_dword v12, v[12:13], off offset:2048
	s_nop 0
	global_load_dword v13, v[74:75], off offset:3072
	global_load_dword v6, v[80:81], off
	global_load_dword v7, v[82:83], off offset:1024
	global_load_dword v8, v[84:85], off offset:2048
	global_load_dword v9, v[86:87], off offset:3072
	s_mov_b64 s[0:1], -1
	s_cbranch_scc1 .LBB0_87
	s_lshl_b64 s[0:1], s[14:15], 2
	s_add_u32 s0, s16, s0
	s_addc_u32 s1, s17, s1
	global_load_dwordx4 v[80:83], v3, s[0:1]
	s_mov_b64 s[0:1], 0
	s_waitcnt vmcnt(0)
	v_pk_mul_f32 v[68:69], v[72:73], v[80:81]
	v_pk_mul_f32 v[74:75], v[70:71], v[82:83]

; #define LAS __attribute__((address_space(3)))
; #define PIN(i) ((const float*)ldq_(L, (i)))
; __device__ __forceinline__ unsigned pk2(float lo, float hi) { f32x2 v = {lo, hi}; bf16x2_t b = __builtin_convertvector(v, bf16x2_t); return __builtin_bit_cast(unsigned, b); }
; #define PREP_CONV(bit, SRC, Kd, Nd, DST, GK, MODE) if (mask & (bit)) { for (int it = gw; it < ((Kd) / 64) * ((Nd) / 64); it += NGW) transpose_item((SRC), (Kd), (Nd), (bf16_t*)(wl + (DST)), (GK), (MODE), scr, it, lane); }
; __device__ __forceinline__ void transpose_item(const float* W, int K, int N, bf16_t* WT, const float* gk, int mode, LAS float* scr_, int item, int lane) {
;     LAS unsigned* scr = (LAS unsigned*)scr_;
;     const int nblk = N / 64, kb = item / nblk, nb = item % nblk, k0 = 64 * kb, n0 = 64 * nb;
;     const int sc = (mode == 1) ? (((n0 >> 7) & 1) * DFF + (n0 >> 8) * 128 + (n0 & 127)) : n0;
;     const float* src = W + (size_t)k0 * N + sc + lane;
;     float va[32], vb[32];
; #pragma unroll
;     for (int kp = 0; kp < 32; ++kp) { va[kp] = src[(size_t)(2 * kp) * N]; vb[kp] = src[(size_t)(2 * kp + 1) * N]; }
; #pragma unroll
;     for (int kp = 0; kp < 32; ++kp) {
;         float a = va[kp], b = vb[kp];
;         if (gk) { a *= gk[k0 + 2 * kp]; b *= gk[k0 + 2 * kp + 1]; }
;         scr[kp * 65 + lane] = pk2(a, b);
; __device__ __forceinline__ void prep(const Params& p, LAS unsigned char* L, int wv, int vb, int nvb, int l, int mask) {
;     ...
;     PREP_CONV(PM_FFB_IN, PIN(I_WFFB_IN) + (size_t)l * DM * NFF2, DM, NFF2, WL_FFB_IN, PIN(I_NFFB) + l * DM, 1)
.LBB0_155:
	v_mov_b32_e32 v6, 0
	s_mul_hi_i32 s0, s92, 0x2e8ba2e9
	v_add_u32_e32 v6, 0, v6
	v_add_u32_e32 v6, 0x20198, v6
	s_lshr_b32 s10, s0, 31
	s_ashr_i32 s0, s0, 4
	s_nop 0
	s_add_i32 s15, s0, s10
	s_mul_i32 s0, s15, 0xffffea00
	s_mul_i32 s11, s15, 0xfffff500
	s_add_i32 s93, s18, s0
	s_bfe_i32 s0, s92, 0x10001
	s_add_i32 s11, s24, s11
	s_and_b32 s0, s0, 0xb00
	s_and_b32 s11, s11, 0xffffff80
	s_lshl_b32 s10, s15, 6
	s_add_i32 s0, s0, s11
	s_and_b32 s11, s93, 64
	s_waitcnt lgkmcnt(0)
	v_readlane_b32 s14, v251, 38
	s_or_b32 s0, s0, s11
	s_ashr_i32 s11, s10, 31
	s_mul_i32 s15, s15, 0x160000
	v_readlane_b32 s1, v251, 39
	s_mul_hi_i32 s16, s10, 0x5800
	s_add_u32 s14, s14, s15
	v_mov_b32_e32 v8, 0
	s_addc_u32 s15, s1, s16
	s_ashr_i32 s1, s0, 31
	s_lshl_b64 s[0:1], s[0:1], 2
	v_add_u32_e32 v8, 0, v8
	s_add_u32 s0, s14, s0
	v_add_u32_e32 v6, 0x20190, v8
	s_addc_u32 s1, s15, s1
	s_nop 0
	v_lshl_add_u64 v[6:7], s[0:1], 0, v[2:3]
	v_add_co_u32_e32 v8, vcc, s26, v6
	s_waitcnt lgkmcnt(0)
	v_readlane_b32 s15, v251, 37
	v_addc_co_u32_e32 v9, vcc, 0, v7, vcc
	v_add_co_u32_e32 v10, vcc, s27, v6
	v_readlane_b32 s14, v251, 36
	s_nop 0
	v_addc_co_u32_e32 v11, vcc, 0, v7, vcc
	v_add_co_u32_e32 v12, vcc, s28, v6
	s_cmp_lg_u64 s[14:15], 0
	s_nop 0
	v_addc_co_u32_e32 v13, vcc, 0, v7, vcc
	v_add_co_u32_e32 v14, vcc, s29, v6
	s_cselect_b64 s[16:17], -1, 0
	s_nop 0
	v_addc_co_u32_e32 v15, vcc, 0, v7, vcc
	v_add_co_u32_e32 v16, vcc, s30, v6
	s_cmp_eq_u64 s[14:15], 0
	s_nop 0
	v_addc_co_u32_e32 v17, vcc, 0, v7, vcc
	v_add_co_u32_e32 v18, vcc, s31, v6
	s_nop 1
	v_addc_co_u32_e32 v19, vcc, 0, v7, vcc
	v_add_co_u32_e32 v20, vcc, s34, v6
	s_nop 1
	v_addc_co_u32_e32 v21, vcc, 0, v7, vcc
	v_add_co_u32_e32 v22, vcc, s35, v6
	s_nop 1
	v_addc_co_u32_e32 v23, vcc, 0, v7, vcc
	global_load_dword v73, v[8:9], off offset:2048
	global_load_dword v70, v[10:11], off
	global_load_dword v71, v[12:13], off offset:2048
	global_load_dword v64, v[14:15], off
	global_load_dword v65, v[16:17], off offset:2048
	global_load_dword v66, v[18:19], off
	global_load_dword v67, v[20:21], off offset:2048
	global_load_dword v60, v[22:23], off
	v_add_co_u32_e32 v8, vcc, s36, v6
	s_nop 1
	v_addc_co_u32_e32 v9, vcc, 0, v7, vcc
	v_add_co_u32_e32 v10, vcc, s37, v6
	s_nop 1
	v_addc_co_u32_e32 v11, vcc, 0, v7, vcc
	v_add_co_u32_e32 v12, vcc, s38, v6
	s_nop 1
	v_addc_co_u32_e32 v13, vcc, 0, v7, vcc
	v_add_co_u32_e32 v14, vcc, s39, v6
	s_nop 1
	v_addc_co_u32_e32 v15, vcc, 0, v7, vcc
	v_add_co_u32_e32 v16, vcc, s40, v6
	s_nop 1
	v_addc_co_u32_e32 v17, vcc, 0, v7, vcc
	v_add_co_u32_e32 v18, vcc, s41, v6
	s_nop 1
	v_addc_co_u32_e32 v19, vcc, 0, v7, vcc
	v_add_co_u32_e32 v20, vcc, s42, v6
	s_nop 1
	v_addc_co_u32_e32 v21, vcc, 0, v7, vcc
	v_add_co_u32_e32 v22, vcc, s43, v6
	s_nop 1
	v_addc_co_u32_e32 v23, vcc, 0, v7, vcc
	global_load_dword v61, v[8:9], off offset:2048
	global_load_dword v62, v[10:11], off
	global_load_dword v63, v[12:13], off offset:2048
	global_load_dword v56, v[14:15], off
	global_load_dword v57, v[16:17], off offset:2048
	global_load_dword v58, v[18:19], off
	global_load_dword v59, v[20:21], off offset:2048
	global_load_dword v52, v[22:23], off
	v_add_co_u32_e32 v8, vcc, s44, v6
	s_nop 1
	v_addc_co_u32_e32 v9, vcc, 0, v7, vcc
	v_add_co_u32_e32 v10, vcc, s45, v6
	s_nop 1
	v_addc_co_u32_e32 v11, vcc, 0, v7, vcc
	v_add_co_u32_e32 v12, vcc, s46, v6
	s_nop 1
	v_addc_co_u32_e32 v13, vcc, 0, v7, vcc
	v_add_co_u32_e32 v14, vcc, s47, v6
	s_nop 1
	v_addc_co_u32_e32 v15, vcc, 0, v7, vcc
	v_add_co_u32_e32 v16, vcc, s48, v6
	s_nop 1
	v_addc_co_u32_e32 v17, vcc, 0, v7, vcc
	v_add_co_u32_e32 v18, vcc, s49, v6
	s_nop 1
	v_addc_co_u32_e32 v19, vcc, 0, v7, vcc
	v_add_co_u32_e32 v20, vcc, s50, v6
	s_nop 1
	v_addc_co_u32_e32 v21, vcc, 0, v7, vcc
	v_add_co_u32_e32 v22, vcc, s51, v6
	s_nop 1
	v_addc_co_u32_e32 v23, vcc, 0, v7, vcc
	global_load_dword v53, v[8:9], off offset:2048
	global_load_dword v54, v[10:11], off
	global_load_dword v55, v[12:13], off offset:2048
	global_load_dword v48, v[14:15], off
	global_load_dword v49, v[16:17], off offset:2048
	global_load_dword v50, v[18:19], off
	global_load_dword v51, v[20:21], off offset:2048
	global_load_dword v44, v[22:23], off
	v_add_co_u32_e32 v8, vcc, s52, v6
	s_nop 1
	v_addc_co_u32_e32 v9, vcc, 0, v7, vcc
	v_add_co_u32_e32 v10, vcc, s53, v6
	s_nop 1
	v_addc_co_u32_e32 v11, vcc, 0, v7, vcc
	v_add_co_u32_e32 v12, vcc, s54, v6
	s_nop 1
	v_addc_co_u32_e32 v13, vcc, 0, v7, vcc
	v_add_co_u32_e32 v14, vcc, s55, v6
	s_nop 1
	v_addc_co_u32_e32 v15, vcc, 0, v7, vcc
	v_add_co_u32_e32 v16, vcc, s56, v6
	s_nop 1
	v_addc_co_u32_e32 v17, vcc, 0, v7, vcc
	v_add_co_u32_e32 v18, vcc, s57, v6
	s_nop 1
	v_addc_co_u32_e32 v19, vcc, 0, v7, vcc
	v_add_co_u32_e32 v20, vcc, s58, v6
	s_nop 1
	v_addc_co_u32_e32 v21, vcc, 0, v7, vcc
	v_add_co_u32_e32 v22, vcc, s59, v6
; __device__ __forceinline__ void transpose_item(const float* W, int K, int N, bf16_t* WT, const float* gk, int mode, LAS float* scr_, int item, int lane) {
;     ...
;     for (int kp = 0; kp < 32; ++kp) { va[kp] = src[(size_t)(2 * kp) * N]; vb[kp] = src[(size_t)(2 * kp + 1) * N]; }
; #pragma unroll
;     for (int kp = 0; kp < 32; ++kp) {
;         float a = va[kp], b = vb[kp];
;         if (gk) { a *= gk[k0 + 2 * kp]; b *= gk[k0 + 2 * kp + 1]; }
	s_nop 1
	v_addc_co_u32_e32 v23, vcc, 0, v7, vcc
	global_load_dword v45, v[8:9], off offset:2048
	global_load_dword v46, v[10:11], off
	global_load_dword v47, v[12:13], off offset:2048
	global_load_dword v40, v[14:15], off
	global_load_dword v41, v[16:17], off offset:2048
	global_load_dword v42, v[18:19], off
	global_load_dword v43, v[20:21], off offset:2048
	global_load_dword v36, v[22:23], off
	v_add_co_u32_e32 v8, vcc, s62, v6
	s_nop 1
	v_addc_co_u32_e32 v9, vcc, 0, v7, vcc
	v_add_co_u32_e32 v10, vcc, s63, v6
	s_nop 1
	v_addc_co_u32_e32 v11, vcc, 0, v7, vcc
	v_add_co_u32_e32 v12, vcc, s65, v6
	s_nop 1
	v_addc_co_u32_e32 v13, vcc, 0, v7, vcc
	v_add_co_u32_e32 v14, vcc, s66, v6
	s_nop 1
	v_addc_co_u32_e32 v15, vcc, 0, v7, vcc
	v_add_co_u32_e32 v16, vcc, s67, v6
	s_nop 1
	v_addc_co_u32_e32 v17, vcc, 0, v7, vcc
	v_add_co_u32_e32 v18, vcc, s68, v6
	s_nop 1
	v_addc_co_u32_e32 v19, vcc, 0, v7, vcc
	v_add_co_u32_e32 v20, vcc, s69, v6
	s_nop 1
	v_addc_co_u32_e32 v21, vcc, 0, v7, vcc
	v_add_co_u32_e32 v22, vcc, s70, v6
	s_nop 1
	v_addc_co_u32_e32 v23, vcc, 0, v7, vcc
	global_load_dword v37, v[8:9], off offset:2048
	global_load_dword v38, v[10:11], off
	global_load_dword v39, v[12:13], off offset:2048
	global_load_dword v32, v[14:15], off
	global_load_dword v33, v[16:17], off offset:2048
	global_load_dword v34, v[18:19], off
	global_load_dword v35, v[20:21], off offset:2048
	global_load_dword v28, v[22:23], off
	v_add_co_u32_e32 v8, vcc, s71, v6
	s_nop 1
	v_addc_co_u32_e32 v9, vcc, 0, v7, vcc
	v_add_co_u32_e32 v10, vcc, s72, v6
	s_nop 1
	v_addc_co_u32_e32 v11, vcc, 0, v7, vcc
	v_add_co_u32_e32 v12, vcc, s73, v6
	s_nop 1
	v_addc_co_u32_e32 v13, vcc, 0, v7, vcc
	v_add_co_u32_e32 v14, vcc, s74, v6
	s_nop 1
	v_addc_co_u32_e32 v15, vcc, 0, v7, vcc
	v_add_co_u32_e32 v16, vcc, s75, v6
	s_nop 1
	v_addc_co_u32_e32 v17, vcc, 0, v7, vcc
	v_add_co_u32_e32 v18, vcc, s76, v6
	s_nop 1
	v_addc_co_u32_e32 v19, vcc, 0, v7, vcc
	v_add_co_u32_e32 v20, vcc, s77, v6
	s_nop 1
	v_addc_co_u32_e32 v21, vcc, 0, v7, vcc
	v_add_co_u32_e32 v74, vcc, s78, v6
	s_nop 1
	v_addc_co_u32_e32 v75, vcc, 0, v7, vcc
	global_load_dword v29, v[8:9], off offset:2048
	global_load_dword v30, v[10:11], off
	global_load_dword v31, v[12:13], off offset:2048
	global_load_dword v22, v[14:15], off
	global_load_dword v23, v[16:17], off offset:2048
	global_load_dword v24, v[18:19], off
	global_load_dword v25, v[20:21], off offset:2048
	s_nop 0
	global_load_dword v18, v[74:75], off
	v_add_co_u32_e32 v8, vcc, s79, v6
	s_nop 1
	v_addc_co_u32_e32 v9, vcc, 0, v7, vcc
	v_add_co_u32_e32 v10, vcc, s80, v6
	s_nop 1
	v_addc_co_u32_e32 v11, vcc, 0, v7, vcc
	v_add_co_u32_e32 v12, vcc, s81, v6
	s_nop 1
	v_addc_co_u32_e32 v13, vcc, 0, v7, vcc
	v_add_co_u32_e32 v14, vcc, s82, v6
	s_nop 1
	v_addc_co_u32_e32 v15, vcc, 0, v7, vcc
	v_add_co_u32_e32 v16, vcc, s83, v6
	s_nop 1
	v_addc_co_u32_e32 v17, vcc, 0, v7, vcc
	v_add_co_u32_e32 v74, vcc, s84, v6
	s_nop 1
	v_addc_co_u32_e32 v75, vcc, 0, v7, vcc
	v_add_co_u32_e32 v80, vcc, s85, v6
	s_nop 1
	v_addc_co_u32_e32 v81, vcc, 0, v7, vcc
	v_add_co_u32_e32 v82, vcc, s86, v6
	s_nop 1
	v_addc_co_u32_e32 v83, vcc, 0, v7, vcc
	global_load_dword v19, v[8:9], off offset:2048
	global_load_dword v20, v[10:11], off
	global_load_dword v21, v[12:13], off offset:2048
	s_nop 0
	global_load_dword v14, v[14:15], off
	s_nop 0
	global_load_dword v15, v[16:17], off offset:2048
	s_nop 0
	global_load_dword v16, v[74:75], off
	global_load_dword v17, v[80:81], off offset:2048
	global_load_dword v10, v[82:83], off
	v_add_co_u32_e32 v8, vcc, s87, v6
	s_nop 1
	v_addc_co_u32_e32 v9, vcc, 0, v7, vcc
	v_add_co_u32_e32 v12, vcc, s88, v6
	s_nop 1
	v_addc_co_u32_e32 v13, vcc, 0, v7, vcc
	v_add_co_u32_e32 v74, vcc, s89, v6
	s_nop 1
	v_addc_co_u32_e32 v75, vcc, 0, v7, vcc
	v_add_co_u32_e32 v80, vcc, s90, v6
	s_nop 1
	v_addc_co_u32_e32 v81, vcc, 0, v7, vcc
	v_add_co_u32_e32 v82, vcc, s91, v6
	s_nop 1
	v_addc_co_u32_e32 v83, vcc, 0, v7, vcc
	v_add_co_u32_e32 v84, vcc, 0x155000, v6
	s_nop 1
	v_addc_co_u32_e32 v85, vcc, 0, v7, vcc
	v_add_co_u32_e32 v86, vcc, 0x15a000, v6
	s_nop 1
	v_addc_co_u32_e32 v87, vcc, 0, v7, vcc
	global_load_dword v72, v2, s[0:1]
	global_load_dword v11, v[8:9], off offset:2048
	s_nop 0
	global_load_dword v12, v[12:13], off
	s_nop 0
	global_load_dword v13, v[74:75], off offset:2048
	global_load_dword v6, v[80:81], off
	global_load_dword v7, v[82:83], off offset:2048
	global_load_dword v8, v[84:85], off
	global_load_dword v9, v[86:87], off offset:2048
	s_mov_b64 s[0:1], -1
	s_cbranch_scc1 .LBB0_157
	s_lshl_b64 s[0:1], s[10:11], 2
	s_add_u32 s0, s14, s0
	s_addc_u32 s1, s15, s1
	global_load_dwordx4 v[80:83], v3, s[0:1]
	s_mov_b64 s[0:1], 0
	s_waitcnt vmcnt(0)
	v_pk_mul_f32 v[68:69], v[72:73], v[80:81]
	v_pk_mul_f32 v[74:75], v[70:71], v[82:83]

; #define LAS __attribute__((address_space(3)))
; #define PIN(i) ((const float*)ldq_(L, (i)))
; __device__ __forceinline__ unsigned pk2(float lo, float hi) { f32x2 v = {lo, hi}; bf16x2_t b = __builtin_convertvector(v, bf16x2_t); return __builtin_bit_cast(unsigned, b); }
; #define PREP_CONV(bit, SRC, Kd, Nd, DST, GK, MODE) if (mask & (bit)) { for (int it = gw; it < ((Kd) / 64) * ((Nd) / 64); it += NGW) transpose_item((SRC), (Kd), (Nd), (bf16_t*)(wl + (DST)), (GK), (MODE), scr, it, lane); }
; __device__ __forceinline__ void transpose_item(const float* W, int K, int N, bf16_t* WT, const float* gk, int mode, LAS float* scr_, int item, int lane) {
;     LAS unsigned* scr = (LAS unsigned*)scr_;
;     const int nblk = N / 64, kb = item / nblk, nb = item % nblk, k0 = 64 * kb, n0 = 64 * nb;
;     const int sc = (mode == 1) ? (((n0 >> 7) & 1) * DFF + (n0 >> 8) * 128 + (n0 & 127)) : n0;
;     const float* src = W + (size_t)k0 * N + sc + lane;
;     float va[32], vb[32];
; #pragma unroll
;     for (int kp = 0; kp < 32; ++kp) { va[kp] = src[(size_t)(2 * kp) * N]; vb[kp] = src[(size_t)(2 * kp + 1) * N]; }
; #pragma unroll
;     for (int kp = 0; kp < 32; ++kp) {
;         float a = va[kp], b = vb[kp];
;         if (gk) { a *= gk[k0 + 2 * kp]; b *= gk[k0 + 2 * kp + 1]; }
;         scr[kp * 65 + lane] = pk2(a, b);
; __device__ __forceinline__ void prep(const Params& p, LAS unsigned char* L, int wv, int vb, int nvb, int l, int mask) {
;     ...
;     PREP_CONV(PM_PEG, PIN(I_WPEG) + (size_t)l * DM * DM, DM, DM, WL_PEG, PIN(I_NPE) + l * DM, 0)
.LBB0_225:
	v_mov_b32_e32 v6, 0
	s_ashr_i32 s0, s52, 31
	v_add_u32_e32 v6, 0, v6
	v_add_u32_e32 v6, 0x201b0, v6
	s_nop 0
	s_lshr_b32 s0, s0, 28
	s_add_i32 s0, s52, s0
	s_ashr_i32 s0, s0, 4
	s_lshl_b32 s6, s0, 6
	s_lshl_b32 s53, s0, 10
	s_ashr_i32 s7, s6, 31
	s_waitcnt lgkmcnt(0)
	v_readlane_b32 s12, v251, 44
	s_sub_i32 s0, s14, s53
	s_lshl_b64 s[10:11], s[6:7], 12
	v_readlane_b32 s1, v251, 45
	s_add_u32 s10, s12, s10
	s_addc_u32 s11, s1, s11
	s_ashr_i32 s1, s0, 31
	v_mov_b32_e32 v8, 0
	s_lshl_b64 s[0:1], s[0:1], 2
	s_add_u32 s0, s10, s0
	v_add_u32_e32 v8, 0, v8
	s_addc_u32 s1, s11, s1
	v_add_u32_e32 v6, 0x201a8, v8
	v_lshl_add_u64 v[8:9], s[0:1], 0, v[2:3]
	v_add_co_u32_e32 v72, vcc, s16, v8
	s_nop 0
	s_nop 0
	v_addc_co_u32_e32 v73, vcc, 0, v9, vcc
	v_add_co_u32_e32 v74, vcc, s17, v8
	s_waitcnt lgkmcnt(0)
	v_readlane_b32 s11, v251, 43
	v_addc_co_u32_e32 v75, vcc, 0, v9, vcc
	v_add_co_u32_e32 v6, vcc, s18, v8
	v_readlane_b32 s10, v251, 42
	s_nop 0
	v_addc_co_u32_e32 v7, vcc, 0, v9, vcc
	v_add_co_u32_e32 v10, vcc, s19, v8
	s_cmp_lg_u64 s[10:11], 0
	s_nop 0
	v_addc_co_u32_e32 v11, vcc, 0, v9, vcc
	v_add_co_u32_e32 v12, vcc, s23, v8
	s_cselect_b64 s[12:13], -1, 0
	s_nop 0
	v_addc_co_u32_e32 v13, vcc, 0, v9, vcc
	v_add_co_u32_e32 v14, vcc, s24, v8
	s_cmp_eq_u64 s[10:11], 0
	s_nop 0
	v_addc_co_u32_e32 v15, vcc, 0, v9, vcc
	global_load_dword v67, v[6:7], off offset:-4096
	global_load_dword v64, v[6:7], off
	global_load_dword v65, v[10:11], off offset:-4096
	global_load_dword v60, v[10:11], off
	global_load_dword v61, v[12:13], off offset:-4096
	global_load_dword v62, v[12:13], off
	global_load_dword v63, v[14:15], off offset:-4096
	global_load_dword v56, v[14:15], off
	v_add_co_u32_e32 v6, vcc, s25, v8
	s_nop 1
	v_addc_co_u32_e32 v7, vcc, 0, v9, vcc
	v_add_co_u32_e32 v10, vcc, s26, v8
	s_nop 1
	v_addc_co_u32_e32 v11, vcc, 0, v9, vcc
	v_add_co_u32_e32 v12, vcc, s27, v8
	s_nop 1
	v_addc_co_u32_e32 v13, vcc, 0, v9, vcc
	v_add_co_u32_e32 v14, vcc, s28, v8
	s_nop 1
	v_addc_co_u32_e32 v15, vcc, 0, v9, vcc
	global_load_dword v57, v[6:7], off offset:-4096
	global_load_dword v58, v[6:7], off
	global_load_dword v59, v[10:11], off offset:-4096
	global_load_dword v52, v[10:11], off
	global_load_dword v53, v[12:13], off offset:-4096
	global_load_dword v54, v[12:13], off
	global_load_dword v55, v[14:15], off offset:-4096
	global_load_dword v48, v[14:15], off
	v_add_co_u32_e32 v6, vcc, s29, v8
	s_nop 1
	v_addc_co_u32_e32 v7, vcc, 0, v9, vcc
	v_add_co_u32_e32 v10, vcc, s30, v8
	s_nop 1
	v_addc_co_u32_e32 v11, vcc, 0, v9, vcc
	v_add_co_u32_e32 v12, vcc, s31, v8
	s_nop 1
	v_addc_co_u32_e32 v13, vcc, 0, v9, vcc
	v_add_co_u32_e32 v14, vcc, s34, v8
	s_nop 1
	v_addc_co_u32_e32 v15, vcc, 0, v9, vcc
	global_load_dword v49, v[6:7], off offset:-4096
	global_load_dword v50, v[6:7], off
	global_load_dword v51, v[10:11], off offset:-4096
	global_load_dword v44, v[10:11], off
	global_load_dword v45, v[12:13], off offset:-4096
	global_load_dword v46, v[12:13], off
	global_load_dword v47, v[14:15], off offset:-4096
	global_load_dword v40, v[14:15], off
	v_add_co_u32_e32 v6, vcc, s35, v8
	s_nop 1
	v_addc_co_u32_e32 v7, vcc, 0, v9, vcc
	v_add_co_u32_e32 v10, vcc, s36, v8
	s_nop 1
	v_addc_co_u32_e32 v11, vcc, 0, v9, vcc
	v_add_co_u32_e32 v12, vcc, s37, v8
	s_nop 1
	v_addc_co_u32_e32 v13, vcc, 0, v9, vcc
	v_add_co_u32_e32 v14, vcc, s38, v8
	s_nop 1
	v_addc_co_u32_e32 v15, vcc, 0, v9, vcc
	global_load_dword v41, v[6:7], off offset:-4096
	global_load_dword v42, v[6:7], off
	global_load_dword v43, v[10:11], off offset:-4096
	global_load_dword v36, v[10:11], off
	global_load_dword v37, v[12:13], off offset:-4096
	global_load_dword v38, v[12:13], off
	global_load_dword v39, v[14:15], off offset:-4096
	global_load_dword v32, v[14:15], off
	v_add_co_u32_e32 v6, vcc, s39, v8
	s_nop 1
	v_addc_co_u32_e32 v7, vcc, 0, v9, vcc
	v_add_co_u32_e32 v10, vcc, s40, v8
	s_nop 1
	v_addc_co_u32_e32 v11, vcc, 0, v9, vcc
	v_add_co_u32_e32 v12, vcc, s41, v8
	s_nop 1
	v_addc_co_u32_e32 v13, vcc, 0, v9, vcc
	v_add_co_u32_e32 v14, vcc, s42, v8
	s_nop 1
	v_addc_co_u32_e32 v15, vcc, 0, v9, vcc
	global_load_dword v33, v[6:7], off offset:-4096
	global_load_dword v34, v[6:7], off
	global_load_dword v35, v[10:11], off offset:-4096
	global_load_dword v28, v[10:11], off
	global_load_dword v29, v[12:13], off offset:-4096
	global_load_dword v30, v[12:13], off
	global_load_dword v31, v[14:15], off offset:-4096
	global_load_dword v22, v[14:15], off
	v_add_co_u32_e32 v6, vcc, s43, v8
	s_nop 1
	v_addc_co_u32_e32 v7, vcc, 0, v9, vcc
	v_add_co_u32_e32 v10, vcc, s44, v8
	s_nop 1
	v_addc_co_u32_e32 v11, vcc, 0, v9, vcc
	v_add_co_u32_e32 v12, vcc, s45, v8
	s_nop 1
	v_addc_co_u32_e32 v13, vcc, 0, v9, vcc
	v_add_co_u32_e32 v14, vcc, s46, v8
	s_nop 1
	v_addc_co_u32_e32 v15, vcc, 0, v9, vcc
	global_load_dword v23, v[6:7], off offset:-4096
	global_load_dword v24, v[6:7], off
	global_load_dword v25, v[10:11], off offset:-4096
	global_load_dword v18, v[10:11], off
	global_load_dword v19, v[12:13], off offset:-4096
	global_load_dword v20, v[12:13], off
	global_load_dword v21, v[14:15], off offset:-4096
	s_nop 0
	global_load_dword v14, v[14:15], off
	v_add_co_u32_e32 v6, vcc, s47, v8
	s_nop 1
	v_addc_co_u32_e32 v7, vcc, 0, v9, vcc
	v_add_co_u32_e32 v10, vcc, s48, v8
	s_nop 1
	v_addc_co_u32_e32 v11, vcc, 0, v9, vcc
	v_add_co_u32_e32 v12, vcc, s49, v8
	s_nop 1
	v_addc_co_u32_e32 v13, vcc, 0, v9, vcc
	v_add_co_u32_e32 v70, vcc, s50, v8
	s_nop 1
	v_addc_co_u32_e32 v71, vcc, 0, v9, vcc
	v_add_co_u32_e32 v80, vcc, s51, v8
	global_load_dword v15, v[6:7], off offset:-4096
	global_load_dword v16, v[6:7], off
	global_load_dword v17, v[10:11], off offset:-4096
	s_nop 0
	global_load_dword v10, v[10:11], off
	s_nop 0
	global_load_dword v11, v[12:13], off offset:-4096
	s_nop 0
	global_load_dword v12, v[12:13], off
	s_nop 0
	global_load_dword v13, v[70:71], off offset:-4096
	global_load_dword v6, v[70:71], off
	v_addc_co_u32_e32 v81, vcc, 0, v9, vcc
	v_add_co_u32_e32 v82, vcc, 0x3e000, v8
	s_nop 1
	v_addc_co_u32_e32 v83, vcc, 0, v9, vcc
	v_add_co_u32_e32 v84, vcc, 0x3f000, v8
	s_nop 1
	v_addc_co_u32_e32 v85, vcc, 0, v9, vcc
	global_load_dword v70, v2, s[0:1]
	global_load_dword v71, v[72:73], off offset:-4096
	s_nop 0
	global_load_dword v72, v[72:73], off
	s_nop 0
	global_load_dword v73, v[74:75], off offset:-4096
	global_load_dword v66, v[74:75], off
	global_load_dword v7, v[80:81], off
	global_load_dword v8, v[82:83], off
	global_load_dword v9, v[84:85], off
	s_mov_b64 s[0:1], -1
	s_cbranch_scc1 .LBB0_227
	s_lshl_b64 s[0:1], s[6:7], 2
	s_add_u32 s0, s10, s0
	s_addc_u32 s1, s11, s1
	global_load_dwordx4 v[80:83], v3, s[0:1]
	s_mov_b64 s[0:1], 0
	s_waitcnt vmcnt(0)
	v_pk_mul_f32 v[68:69], v[70:71], v[80:81]
	v_pk_mul_f32 v[74:75], v[72:73], v[82:83]

; #define PG8_STAGE(bufoff, gbase, voff) do { _Pragma("unroll") for (int _i = 0; _i < 2; ++_i) \
;         __builtin_amdgcn_global_load_lds((const unsigned*)((const char*)(gbase) + (voff)[_i]), (PG8_LAS unsigned*)(lds + (bufoff) + ldsw + _i * 8192), 16, 0, 0); } while (0)
; #define PG8_WAIT_V(n) asm volatile("s_waitcnt vmcnt(" #n ")" ::: "memory")
; #define PG8_BAR __builtin_amdgcn_s_barrier()
; template <class Epi, class Sched, bool ALIGN_EPI = false, bool SP2 = false>
; __device__ __forceinline__ void gemm_phase(PG8_LAS unsigned char* lds, const Gemm g, const Sched& S, const Epi& E, int wv) {
;     ...
;     const int tid = tid_, wid = __builtin_amdgcn_readfirstlane(tid >> 6), lane = tid & 63, wr = wid >> 2, wc = wid & 3, fr = lane & 15, fq = lane >> 4;
;     const int K = g.K, nt = K / BK;
;     unsigned voffA[2], voffB[2];
; #pragma unroll
;     for (int i = 0; i < 2; ++i) { int R, C; stage_rc(tid * 16 + i * 8192, R, C); const int Rb = Epi::PERM ? ((R & ~31) + perm32(R & 31)) : R;
;         voffA[i] = (unsigned)(R * K + C) * 2u; voffB[i] = (unsigned)(Rb * K + C) * 2u; }
;     const size_t kstep = (size_t)(BK * 2);
;     const size_t hstep = (size_t)HALF * K * 2;
;     const size_t tstep = 2 * hstep;
;     const unsigned ldsw = (unsigned)wid * 1024u;
;     const int aoff = lds_byte(wr * 64 + fr, fq * 8), boff = lds_byte(wc * 32 + fr, fq * 8);
;     ...
;     Unit cur, nxt; int ui = 0;
;     if (!S.next(0, cur)) return;
;     f32x4 acc[2][2][4][2];
; #pragma unroll
;     for (int a = 0; a < 2; ++a)
; #pragma unroll
;         for (int b = 0; b < 2; ++b)
; #pragma unroll
;             for (int m = 0; m < 4; ++m)
; #pragma unroll
;                 for (int n = 0; n < 2; ++n) acc[a][b][m][n] = (f32x4){0.f, 0.f, 0.f, 0.f};
;     bf16x8 At[4][2], B0[2][2], B1[2][2];
;     const char* cA = (const char*)g.A + (size_t)cur.pm * tstep; const char* cB = (const char*)g.Bt + (size_t)cur.pn * tstep;
;     S.a_ready(cur);
;     if constexpr (SP2) {
;         PG8_STAGE(PG8_SB(0, 0), cB, voffB); PG8_STAGE(PG8_SB(0, 1), cB + hstep, voffB); PG8_STAGE(PG8_SA(0, 0), cA, voffA); PG8_STAGE(PG8_SA(0, 1), cA + hstep, voffA);
;         if (wr == 1) PG8_BAR;
;         PG8_WAIT_V(2); PG8_BAR;
;         PG8_STAGE(PG8_SB(1, 0), cB + kstep, voffB); PG8_STAGE(PG8_SA(1, 0), cA + kstep, voffA); PG8_STAGE(PG8_SB(1, 1), cB + hstep + kstep, voffB);
.LBB0_764:
	s_mov_b64 s[4:5], 0
	s_mov_b32 s8, s12
	v_mov_b32_e32 v0, v161
	v_writelane_b32 v250, s12, 0
	v_add_u32_e32 v0, 0, v0
	v_add_u32_e32 v0, 0x201c0, v0
	s_waitcnt lgkmcnt(0)
	s_nop 0
	v_readlane_b32 s10, v250, 33
	v_mov_b32_e32 v8, v183
	v_readlane_b32 s11, v250, 34
	s_and_b64 vcc, exec, s[10:11]
	s_waitcnt lgkmcnt(0)
	v_readlane_b32 s7, v251, 48
	v_mov_b32_e32 v0, v161
	v_readlane_b32 s6, v251, 49
	v_add_u32_e32 v0, 0, v0
	v_add_u32_e32 v0, 0x201c8, v0
	ds_read_b64 v[0:1], v0
	s_nop 0
	v_readfirstlane_b32 s10, v8
	s_cbranch_vccnz .LBB0_780
	s_waitcnt lgkmcnt(0)
	v_lshlrev_b32_e32 v0, 4, v8
	v_add_u32_e32 v1, 0x2000, v0
	v_ashrrev_i32_e32 v2, 31, v1
	v_lshrrev_b32_e32 v2, 22, v2
	v_add_u32_e32 v2, v1, v2
	v_ashrrev_i32_e32 v9, 10, v2
	v_mul_i32_i24_e32 v2, 0x400, v9
	v_sub_u32_e32 v1, v1, v2
	v_lshrrev_b32_e32 v2, 4, v1
	s_add_u32 s9, s7, s4
	v_bitop3_b32 v1, v2, v1, 32 bitop3:0x6c
	s_addc_u32 s12, s6, s5
	s_mul_i32 s5, s8, 0x2900000
	v_ashrrev_i32_e32 v2, 31, v1
	s_mul_hi_i32 s4, s8, 0x2900000
	s_add_u32 s16, s9, s5
	v_lshrrev_b32_e32 v2, 26, v2
	s_addc_u32 s29, s12, s4
	v_add_u32_e32 v2, v1, v2
	v_lshlrev_b32_e32 v3, 3, v9
	s_cmp_eq_u32 s8, 0
	s_mov_b32 s4, 0x5200000
	v_ashrrev_i32_e32 v10, 6, v2
	v_and_b32_e32 v3, -16, v3
	s_cselect_b32 s4, s4, 0x28700000
	v_add_u32_e32 v3, v10, v3
	s_add_u32 s30, s9, s4
	v_and_b32_e32 v4, 3, v10
	s_mov_b32 s4, 0x1fffe0
	v_lshrrev_b32_e32 v5, 2, v3
	v_lshlrev_b32_e32 v6, 1, v3
	v_and_b32_e32 v2, 0xc0, v2
	v_and_or_b32 v4, v3, s4, v4
	v_and_b32_e32 v5, 4, v5
	v_and_b32_e32 v6, 24, v6
	v_sub_u32_e32 v1, v1, v2
	v_or3_b32 v4, v4, v5, v6
	v_lshlrev_b32_e32 v5, 5, v9
	v_ashrrev_i16_sdwa v1, v193, sext(v1) dst_sel:DWORD dst_unused:UNUSED_PAD src0_sel:DWORD src1_sel:BYTE_0
	v_and_b32_e32 v5, 32, v5
	v_bfe_i32 v11, v1, 0, 16
	v_add_lshl_u32 v1, v5, v11, 1
	v_lshl_add_u32 v128, v4, 11, v1
	v_lshl_add_u32 v130, v3, 11, v1
	v_bfe_i32 v1, v8, 27, 1
	v_lshrrev_b32_e32 v1, 22, v1
	v_add_u32_e32 v1, v0, v1
	v_and_b32_e32 v1, 0xfffffc00, v1
	v_sub_u32_e32 v0, v0, v1
	v_lshrrev_b32_e32 v1, 4, v0
	v_ashrrev_i32_e32 v2, 31, v8
	v_bitop3_b32 v0, v1, v0, 32 bitop3:0x6c
	v_lshrrev_b32_e32 v2, 26, v2
	v_ashrrev_i32_e32 v1, 31, v0
	v_add_u32_e32 v2, v8, v2
	v_lshrrev_b32_e32 v1, 26, v1
	v_ashrrev_i32_e32 v13, 6, v2
	v_add_u32_e32 v1, v0, v1
	v_lshlrev_b32_e32 v2, 3, v13
	v_ashrrev_i32_e32 v12, 6, v1
	v_and_b32_e32 v2, -16, v2
	v_add_u32_e32 v2, v12, v2
	v_and_b32_e32 v3, 3, v12
	v_lshrrev_b32_e32 v4, 2, v2
	v_lshlrev_b32_e32 v5, 1, v2
	v_and_b32_e32 v1, 0xc0, v1
	s_addc_u32 s31, s12, 0
	s_ashr_i32 s11, s10, 6
	v_and_or_b32 v3, v2, s4, v3
	v_and_b32_e32 v4, 4, v4
	v_and_b32_e32 v5, 24, v5
	v_sub_u32_e32 v0, v0, v1
	s_ashr_i32 s13, s10, 8
	s_lshl_b32 s50, s11, 10
	v_or3_b32 v3, v3, v4, v5
	v_lshlrev_b32_e32 v4, 5, v13
	v_ashrrev_i16_sdwa v0, v193, sext(v0) dst_sel:DWORD dst_unused:UNUSED_PAD src0_sel:DWORD src1_sel:BYTE_0
	v_readlane_b32 s4, v250, 5
	v_and_b32_e32 v4, 32, v4
	v_bfe_i32 v14, v0, 0, 16
	v_readlane_b32 s5, v250, 6
	s_add_u32 s44, s16, s4
	v_add_lshl_u32 v0, v4, v14, 1
	s_addc_u32 s45, s29, s5
	s_add_i32 s51, s50, 0
	v_lshl_add_u32 v160, v3, 11, v0
	s_add_i32 m0, s51, 0x10000
	v_lshl_add_u32 v132, v2, 11, v0
	global_load_lds_dwordx4 v160, s[44:45]
	s_add_i32 m0, s51, 0x12000
	s_add_u32 s4, s44, 0x40000
	global_load_lds_dwordx4 v128, s[44:45]
	s_addc_u32 s5, s45, 0
	s_add_i32 m0, s51, 0x14000
	v_mov_b32_e32 v129, v161
	global_load_lds_dwordx4 v160, s[4:5]
	s_add_i32 m0, s51, 0x16000
	v_mov_b32_e32 v133, v161
	global_load_lds_dwordx4 v128, s[4:5]
	v_readlane_b32 s4, v250, 21
	v_readlane_b32 s5, v250, 22
	s_add_u32 s42, s30, s4
	s_addc_u32 s43, s31, s5
	s_add_i32 s52, s51, 0x2000
	s_mov_b32 m0, s51
	s_add_u32 s4, s42, 0x40000
	global_load_lds_dwordx4 v132, s[42:43]
	s_mov_b32 m0, s52
	s_addc_u32 s5, s43, 0
	s_add_i32 s53, s51, 0x4000
	global_load_lds_dwordx4 v130, s[42:43]
	s_mov_b32 m0, s53
	s_add_i32 s54, s51, 0x6000
	global_load_lds_dwordx4 v132, s[4:5]
	s_mov_b32 m0, s54
	v_mov_b32_e32 v131, v161
	global_load_lds_dwordx4 v130, s[4:5]
	s_cmp_eq_u32 s13, 1
	v_lshl_add_u64 v[6:7], s[44:45], 0, v[160:161]
	v_lshl_add_u64 v[4:5], s[44:45], 0, v[128:129]
	v_lshl_add_u64 v[0:1], s[42:43], 0, v[132:133]
	s_cselect_b64 s[4:5], -1, 0
	s_cmp_lg_u32 s13, 1
	v_lshl_add_u64 v[2:3], s[42:43], 0, v[130:131]
	s_cbranch_scc1 .LBB0_767
	s_barrier

; #define PG8_STAGE(bufoff, gbase, voff) do { _Pragma("unroll") for (int _i = 0; _i < 2; ++_i) \
;         __builtin_amdgcn_global_load_lds((const unsigned*)((const char*)(gbase) + (voff)[_i]), (PG8_LAS unsigned*)(lds + (bufoff) + ldsw + _i * 8192), 16, 0, 0); } while (0)
; #define PG8_WAIT_V(n) asm volatile("s_waitcnt vmcnt(" #n ")" ::: "memory")
; #define PG8_BAR __builtin_amdgcn_s_barrier()
; template <class Epi, class Sched, bool ALIGN_EPI = false, bool SP2 = false>
; __device__ __forceinline__ void gemm_phase(PG8_LAS unsigned char* lds, const Gemm g, const Sched& S, const Epi& E, int wv) {
;     ...
;     const int tid = tid_, wid = __builtin_amdgcn_readfirstlane(tid >> 6), lane = tid & 63, wr = wid >> 2, wc = wid & 3, fr = lane & 15, fq = lane >> 4;
;     const int K = g.K, nt = K / BK;
;     unsigned voffA[2], voffB[2];
; #pragma unroll
;     for (int i = 0; i < 2; ++i) { int R, C; stage_rc(tid * 16 + i * 8192, R, C); const int Rb = Epi::PERM ? ((R & ~31) + perm32(R & 31)) : R;
;         voffA[i] = (unsigned)(R * K + C) * 2u; voffB[i] = (unsigned)(Rb * K + C) * 2u; }
;     const size_t kstep = (size_t)(BK * 2);
;     const size_t hstep = (size_t)HALF * K * 2;
;     const size_t tstep = 2 * hstep;
;     const unsigned ldsw = (unsigned)wid * 1024u;
;     const int aoff = lds_byte(wr * 64 + fr, fq * 8), boff = lds_byte(wc * 32 + fr, fq * 8);
;     ...
;     Unit cur, nxt; int ui = 0;
;     if (!S.next(0, cur)) return;
;     f32x4 acc[2][2][4][2];
; #pragma unroll
;     for (int a = 0; a < 2; ++a)
; #pragma unroll
;         for (int b = 0; b < 2; ++b)
; #pragma unroll
;             for (int m = 0; m < 4; ++m)
; #pragma unroll
;                 for (int n = 0; n < 2; ++n) acc[a][b][m][n] = (f32x4){0.f, 0.f, 0.f, 0.f};
;     bf16x8 At[4][2], B0[2][2], B1[2][2];
;     const char* cA = (const char*)g.A + (size_t)cur.pm * tstep; const char* cB = (const char*)g.Bt + (size_t)cur.pn * tstep;
;     S.a_ready(cur);
;     if constexpr (SP2) {
;         PG8_STAGE(PG8_SB(0, 0), cB, voffB); PG8_STAGE(PG8_SB(0, 1), cB + hstep, voffB); PG8_STAGE(PG8_SA(0, 0), cA, voffA); PG8_STAGE(PG8_SA(0, 1), cA + hstep, voffA);
;         if (wr == 1) PG8_BAR;
;         PG8_WAIT_V(2); PG8_BAR;
;         PG8_STAGE(PG8_SB(1, 0), cB + kstep, voffB); PG8_STAGE(PG8_SA(1, 0), cA + kstep, voffA); PG8_STAGE(PG8_SB(1, 1), cB + hstep + kstep, voffB);
.LBB0_832:
	s_or_b64 exec, exec, s[4:5]
	s_mov_b64 s[4:5], 0
	v_readlane_b32 s12, v250, 0
	s_waitcnt lgkmcnt(0)
	v_mov_b32_e32 v0, v161
	s_barrier
	v_readlane_b32 s8, v250, 1
	v_add_u32_e32 v0, 0, v0
	v_add_u32_e32 v0, 0x201c0, v0
	s_nop 0
	v_readlane_b32 s9, v250, 2
	v_mov_b32_e32 v16, v183
	s_andn2_b64 vcc, exec, s[8:9]
	s_waitcnt lgkmcnt(0)
	v_readlane_b32 s7, v251, 48
	v_mov_b32_e32 v0, v161
	v_readlane_b32 s6, v251, 49
	v_add_u32_e32 v0, 0, v0
	v_add_u32_e32 v0, 0x201c8, v0
	ds_read_b64 v[0:1], v0
	s_waitcnt lgkmcnt(0)
	v_cndmask_b32_e64 v0, 0, 1, s[8:9]
	v_cmp_ne_u32_e64 s[10:11], 1, v0
	s_nop 0
	v_readfirstlane_b32 s24, v16
	v_writelane_b32 v250, s10, 42
	s_nop 1
	v_writelane_b32 v250, s11, 43
	s_cbranch_vccnz .LBB0_868
	v_lshlrev_b32_e32 v0, 4, v16
	v_add_u32_e32 v1, 0x2000, v0
	v_ashrrev_i32_e32 v2, 31, v1
	v_lshrrev_b32_e32 v2, 22, v2
	v_add_u32_e32 v2, v1, v2
	v_ashrrev_i32_e32 v8, 10, v2
	v_mul_i32_i24_e32 v2, 0x400, v8
	v_sub_u32_e32 v1, v1, v2
	v_lshrrev_b32_e32 v2, 4, v1
	v_bitop3_b32 v1, v2, v1, 32 bitop3:0x6c
	v_ashrrev_i32_e32 v2, 31, v1
	v_lshrrev_b32_e32 v2, 26, v2
	v_add_u32_e32 v2, v1, v2
	v_lshlrev_b32_e32 v3, 3, v8
	v_ashrrev_i32_e32 v9, 6, v2
	v_and_b32_e32 v3, -16, v3
	s_add_u32 s13, s7, s4
	v_add_u32_e32 v3, v9, v3
	s_addc_u32 s18, s6, s5
	v_and_b32_e32 v4, 3, v9
	s_mov_b32 s6, 0xffffe0
	v_lshrrev_b32_e32 v5, 2, v3
	v_lshlrev_b32_e32 v6, 1, v3
	v_and_b32_e32 v2, 0xc0, v2
	v_and_or_b32 v4, v3, s6, v4
	v_and_b32_e32 v5, 4, v5
	v_and_b32_e32 v6, 24, v6
	v_sub_u32_e32 v1, v1, v2
	v_or3_b32 v4, v4, v5, v6
	v_lshlrev_b32_e32 v5, 5, v8
	v_ashrrev_i16_sdwa v1, v193, sext(v1) dst_sel:DWORD dst_unused:UNUSED_PAD src0_sel:DWORD src1_sel:BYTE_0
	v_and_b32_e32 v10, 32, v5
	v_bfe_i32 v11, v1, 0, 16
	s_movk_i32 s7, 0xb00
	v_mul_u32_u24_e32 v4, 0xb00, v4
	v_add_u32_e32 v1, v10, v11
	v_mul_lo_u32 v2, v3, s7
	v_add_lshl_u32 v152, v4, v1, 1
	v_add_lshl_u32 v154, v1, v2, 1
	v_bfe_i32 v1, v16, 27, 1
	v_lshrrev_b32_e32 v1, 22, v1
	v_add_u32_e32 v1, v0, v1
	v_and_b32_e32 v1, 0xfffffc00, v1
	v_sub_u32_e32 v0, v0, v1
	v_lshrrev_b32_e32 v1, 4, v0
	v_ashrrev_i32_e32 v2, 31, v16
	v_bitop3_b32 v0, v1, v0, 32 bitop3:0x6c
	v_lshrrev_b32_e32 v2, 26, v2
	v_ashrrev_i32_e32 v1, 31, v0
	v_add_u32_e32 v2, v16, v2
	s_add_u32 s14, s13, 0xd600000
	v_lshrrev_b32_e32 v1, 26, v1
	v_ashrrev_i32_e32 v13, 6, v2
	s_addc_u32 s15, s18, 0
	s_mul_i32 s5, s12, 0x2900000
	v_add_u32_e32 v1, v0, v1
	v_lshlrev_b32_e32 v2, 3, v13
	s_mul_hi_i32 s4, s12, 0x2900000
	s_add_u32 s19, s13, s5
	v_ashrrev_i32_e32 v12, 6, v1
	v_and_b32_e32 v2, -16, v2
	s_addc_u32 s21, s18, s4
	v_add_u32_e32 v2, v12, v2
	s_add_u32 s16, s19, 0xb00000
	v_and_b32_e32 v3, 3, v12
	v_lshrrev_b32_e32 v4, 2, v2
	v_lshlrev_b32_e32 v5, 1, v2
	v_and_b32_e32 v1, 0xc0, v1
	s_addc_u32 s29, s21, 0
	s_ashr_i32 s4, s24, 6
	v_and_or_b32 v3, v2, s6, v3
	v_and_b32_e32 v4, 4, v4
	v_and_b32_e32 v5, 24, v5
	v_sub_u32_e32 v0, v0, v1
	s_ashr_i32 s5, s24, 8
	s_lshl_b32 s30, s4, 10
	v_or3_b32 v3, v3, v4, v5
	v_lshlrev_b32_e32 v4, 5, v13
	v_ashrrev_i16_sdwa v0, v193, sext(v0) dst_sel:DWORD dst_unused:UNUSED_PAD src0_sel:DWORD src1_sel:BYTE_0
	v_readlane_b32 s6, v250, 14
	v_and_b32_e32 v14, 32, v4
	v_bfe_i32 v15, v0, 0, 16
	s_add_u32 s44, s16, s6
	v_readlane_b32 s6, v250, 12
	v_mul_u32_u24_e32 v3, 0xb00, v3
	v_add_u32_e32 v0, v14, v15
	s_addc_u32 s45, s29, s6
	s_add_i32 s31, s30, 0
	v_add_lshl_u32 v160, v3, v0, 1
	s_add_i32 m0, s31, 0x10000
	v_mul_lo_u32 v1, v2, s7
	global_load_lds_dwordx4 v160, s[44:45]
	s_add_i32 m0, s31, 0x12000
	s_add_u32 s6, s44, 0xb0000
	global_load_lds_dwordx4 v152, s[44:45]
	s_addc_u32 s7, s45, 0
	s_add_i32 m0, s31, 0x14000
	v_add_lshl_u32 v156, v0, v1, 1
	global_load_lds_dwordx4 v160, s[6:7]
	s_add_i32 m0, s31, 0x16000
	v_mov_b32_e32 v153, v161
	global_load_lds_dwordx4 v152, s[6:7]
	v_readlane_b32 s6, v250, 11
	s_add_u32 s6, s14, s6
	v_readlane_b32 s7, v250, 10
	s_addc_u32 s7, s15, s7
	s_add_i32 s52, s31, 0x2000
	s_mov_b32 m0, s31
	s_add_u32 s8, s6, 0xb0000
	s_addc_u32 s9, s7, 0
	global_load_lds_dwordx4 v156, s[6:7]
	s_mov_b32 m0, s52
	s_add_i32 s53, s31, 0x4000
	global_load_lds_dwordx4 v154, s[6:7]
	s_mov_b32 m0, s53
	s_add_i32 s54, s31, 0x6000
	global_load_lds_dwordx4 v156, s[8:9]
	s_mov_b32 m0, s54
	v_mov_b32_e32 v157, v161
	global_load_lds_dwordx4 v154, s[8:9]
	v_mov_b32_e32 v155, v161
	s_cmp_eq_u32 s5, 1
	v_lshl_add_u64 v[6:7], s[44:45], 0, v[160:161]
	v_lshl_add_u64 v[4:5], s[44:45], 0, v[152:153]
	v_lshl_add_u64 v[0:1], s[6:7], 0, v[156:157]
	s_cselect_b64 s[8:9], -1, 0
	s_cmp_lg_u32 s5, 1
	v_lshl_add_u64 v[2:3], s[6:7], 0, v[154:155]
	s_cbranch_scc1 .LBB0_835
	s_barrier

; #define PIN(i) ((const float*)ldq_(L, (i)))
; #define PREP_CONV(bit, SRC, Kd, Nd, DST, GK, MODE) if (mask & (bit)) { for (int it = gw; it < ((Kd) / 64) * ((Nd) / 64); it += NGW) transpose_item((SRC), (Kd), (Nd), (bf16_t*)(wl + (DST)), (GK), (MODE), scr, it, lane); }
; __device__ __forceinline__ void transpose_item(const float* W, int K, int N, bf16_t* WT, const float* gk, int mode, LAS float* scr_, int item, int lane) {
;     ...
;     const int nblk = N / 64, kb = item / nblk, nb = item % nblk, k0 = 64 * kb, n0 = 64 * nb;
;     const int sc = (mode == 1) ? (((n0 >> 7) & 1) * DFF + (n0 >> 8) * 128 + (n0 & 127)) : n0;
;     const float* src = W + (size_t)k0 * N + sc + lane;
;     float va[32], vb[32];
; #pragma unroll
;     for (int kp = 0; kp < 32; ++kp) { va[kp] = src[(size_t)(2 * kp) * N]; vb[kp] = src[(size_t)(2 * kp + 1) * N]; }
; #pragma unroll
;     for (int kp = 0; kp < 32; ++kp) {
;         float a = va[kp], b = vb[kp];
;         if (gk) { a *= gk[k0 + 2 * kp]; b *= gk[k0 + 2 * kp + 1]; }
; __device__ __forceinline__ void prep(const Params& p, LAS unsigned char* L, int wv, int vb, int nvb, int l, int mask) {
;     ...
;     PREP_CONV(PM_WIN, PIN(I_WIN) + (size_t)l * DM * NIN, DM, NIN, WL_IN, PIN(I_NMIX) + l * DM, 0)
.LBB0_872:
	v_mov_b32_e32 v6, v161
	s_mul_i32 s12, s6, 0x500000
	v_add_u32_e32 v6, 0, v6
	v_add_u32_e32 v6, 0x20158, v6
	s_nop 0
	s_mov_b64 s[30:31], -1
	s_waitcnt lgkmcnt(0)
	v_readlane_b32 s5, v251, 22
	v_mov_b32_e32 v6, v161
	v_readlane_b32 s4, v251, 23
	v_add_u32_e32 v6, 0, v6
	v_add_u32_e32 v6, 0x20150, v6
	s_nop 0
	s_add_u32 s13, s5, s12
	s_mul_hi_i32 s5, s6, 0x500000
	s_addc_u32 s21, s4, s5
	s_mul_hi_i32 s12, s29, 0x66666667
	s_waitcnt lgkmcnt(0)
	v_readlane_b32 s4, v251, 20
	v_readlane_b32 s5, v251, 21
	s_add_u32 s42, s4, s10
	s_addc_u32 s43, s5, s11
	s_lshr_b32 s18, s12, 31
	s_ashr_i32 s12, s12, 3
	s_add_i32 s24, s12, s18
	s_lshl_b32 s18, s24, 6
	s_mul_i32 s12, s24, 0xfffffb00
	s_add_i32 s12, s15, s12
	s_ashr_i32 s19, s18, 31
	s_mul_i32 s24, s24, 0x50000
	s_mul_hi_i32 s25, s18, 0x1400
	s_add_u32 s26, s13, s24
	s_addc_u32 s21, s21, s25
	s_ashr_i32 s13, s12, 31
	s_lshl_b64 s[24:25], s[12:13], 2
	s_add_u32 s24, s26, s24
	s_addc_u32 s25, s21, s25
	v_lshl_add_u64 v[70:71], s[24:25], 0, v[160:161]
	s_movk_i32 s13, 0x1000
	v_add_co_u32_e32 v6, vcc, s13, v70
	s_movk_i32 s13, 0x3000
	s_nop 0
	v_addc_co_u32_e32 v7, vcc, 0, v71, vcc
	global_load_dword v67, v[6:7], off offset:1024
	v_add_co_u32_e32 v6, vcc, s79, v70
	global_load_dword v66, v160, s[24:25]
	s_nop 0
	v_addc_co_u32_e32 v7, vcc, 0, v71, vcc
	global_load_dword v68, v[6:7], off offset:2048
	v_add_co_u32_e32 v6, vcc, s13, v70
	s_movk_i32 s13, 0x5000
	s_nop 0
	v_addc_co_u32_e32 v7, vcc, 0, v71, vcc
	global_load_dword v69, v[6:7], off offset:3072
	v_add_co_u32_e32 v6, vcc, s13, v70
	s_movk_i32 s13, 0x7000
	s_nop 0
	v_addc_co_u32_e32 v7, vcc, 0, v71, vcc
	global_load_dword v58, v[6:7], off
	v_add_co_u32_e32 v6, vcc, s80, v70
	s_cmp_lg_u64 s[4:5], 0
	s_nop 0
	v_addc_co_u32_e32 v7, vcc, 0, v71, vcc
	global_load_dword v59, v[6:7], off offset:1024
	v_add_co_u32_e32 v6, vcc, s13, v70
	s_mov_b32 s13, 0xb000
	s_nop 0
	v_addc_co_u32_e32 v7, vcc, 0, v71, vcc
	global_load_dword v64, v[6:7], off offset:2048
	v_add_co_u32_e32 v6, vcc, s70, v70
	s_cselect_b64 s[24:25], -1, 0
	s_nop 0
	v_addc_co_u32_e32 v7, vcc, 0, v71, vcc
	global_load_dword v65, v[6:7], off offset:3072
	v_add_co_u32_e32 v6, vcc, s71, v70
	s_cmp_eq_u64 s[4:5], 0
	s_nop 0
	v_addc_co_u32_e32 v7, vcc, 0, v71, vcc
	global_load_dword v60, v[6:7], off
	v_add_co_u32_e32 v6, vcc, s13, v70
	s_mov_b32 s13, 0xd000
	s_nop 0
	v_addc_co_u32_e32 v7, vcc, 0, v71, vcc
	global_load_dword v61, v[6:7], off offset:1024
	v_add_co_u32_e32 v6, vcc, s91, v70
	s_nop 1
	v_addc_co_u32_e32 v7, vcc, 0, v71, vcc
	global_load_dword v62, v[6:7], off offset:2048
	v_add_co_u32_e32 v6, vcc, s13, v70
	s_mov_b32 s13, 0xf000
	s_nop 0
	v_addc_co_u32_e32 v7, vcc, 0, v71, vcc
	global_load_dword v63, v[6:7], off offset:3072
	v_add_co_u32_e32 v6, vcc, s13, v70
	s_mov_b32 s13, 0x11000
	s_nop 0
	v_addc_co_u32_e32 v7, vcc, 0, v71, vcc
	global_load_dword v50, v[6:7], off
	v_add_co_u32_e32 v6, vcc, s37, v70
	s_nop 1
	v_addc_co_u32_e32 v7, vcc, 0, v71, vcc
	global_load_dword v51, v[6:7], off offset:1024
	v_add_co_u32_e32 v6, vcc, s13, v70
	s_mov_b32 s13, 0x15000
	s_nop 0
	v_addc_co_u32_e32 v7, vcc, 0, v71, vcc
	global_load_dword v56, v[6:7], off offset:2048
	v_add_co_u32_e32 v6, vcc, s94, v70
	s_nop 1
	v_addc_co_u32_e32 v7, vcc, 0, v71, vcc
	global_load_dword v57, v[6:7], off offset:3072
	v_add_co_u32_e32 v6, vcc, s46, v70
	s_nop 1
	v_addc_co_u32_e32 v7, vcc, 0, v71, vcc
	global_load_dword v52, v[6:7], off
	v_add_co_u32_e32 v6, vcc, s13, v70
	s_mov_b32 s13, 0x17000
	s_nop 0
	v_addc_co_u32_e32 v7, vcc, 0, v71, vcc
	global_load_dword v53, v[6:7], off offset:1024
	v_add_co_u32_e32 v6, vcc, s47, v70
	s_nop 1
	v_addc_co_u32_e32 v7, vcc, 0, v71, vcc
	global_load_dword v54, v[6:7], off offset:2048
	v_add_co_u32_e32 v6, vcc, s13, v70
	s_mov_b32 s13, 0x19000
	s_nop 0
	v_addc_co_u32_e32 v7, vcc, 0, v71, vcc
	global_load_dword v55, v[6:7], off offset:3072
	v_add_co_u32_e32 v6, vcc, s13, v70
	s_mov_b32 s13, 0x1b000
	s_nop 0
	v_addc_co_u32_e32 v7, vcc, 0, v71, vcc
	global_load_dword v42, v[6:7], off
	v_add_co_u32_e32 v6, vcc, s81, v70
	s_nop 1
	v_addc_co_u32_e32 v7, vcc, 0, v71, vcc
	global_load_dword v43, v[6:7], off offset:1024
	v_add_co_u32_e32 v6, vcc, s13, v70
	s_mov_b32 s13, 0x1f000
	s_nop 0
	v_addc_co_u32_e32 v7, vcc, 0, v71, vcc
	global_load_dword v48, v[6:7], off offset:2048
	v_add_co_u32_e32 v6, vcc, s83, v70
	s_nop 1
	v_addc_co_u32_e32 v7, vcc, 0, v71, vcc
	global_load_dword v49, v[6:7], off offset:3072
	v_add_co_u32_e32 v6, vcc, s27, v70
	s_nop 1
	v_addc_co_u32_e32 v7, vcc, 0, v71, vcc
	global_load_dword v44, v[6:7], off
	v_add_co_u32_e32 v6, vcc, s13, v70
	s_mov_b32 s13, 0x21000
	s_nop 0
	v_addc_co_u32_e32 v7, vcc, 0, v71, vcc
	global_load_dword v45, v[6:7], off offset:1024
	v_add_co_u32_e32 v6, vcc, s50, v70
	s_nop 1
	v_addc_co_u32_e32 v7, vcc, 0, v71, vcc
	global_load_dword v46, v[6:7], off offset:2048
	v_add_co_u32_e32 v6, vcc, s13, v70
	s_mov_b32 s13, 0x23000
	s_nop 0
	v_addc_co_u32_e32 v7, vcc, 0, v71, vcc
	global_load_dword v47, v[6:7], off offset:3072
	v_add_co_u32_e32 v6, vcc, s13, v70
	s_mov_b32 s13, 0x25000
	s_nop 0
	v_addc_co_u32_e32 v7, vcc, 0, v71, vcc
	global_load_dword v34, v[6:7], off
	v_add_co_u32_e32 v6, vcc, s0, v70
	s_nop 1
; __device__ __forceinline__ void transpose_item(const float* W, int K, int N, bf16_t* WT, const float* gk, int mode, LAS float* scr_, int item, int lane) {
;     ...
;     float va[32], vb[32];
; #pragma unroll
;     for (int kp = 0; kp < 32; ++kp) { va[kp] = src[(size_t)(2 * kp) * N]; vb[kp] = src[(size_t)(2 * kp + 1) * N]; }
; #pragma unroll
;     for (int kp = 0; kp < 32; ++kp) {
;         float a = va[kp], b = vb[kp];
;         if (gk) { a *= gk[k0 + 2 * kp]; b *= gk[k0 + 2 * kp + 1]; }
	v_addc_co_u32_e32 v7, vcc, 0, v71, vcc
	global_load_dword v35, v[6:7], off offset:1024
	v_add_co_u32_e32 v6, vcc, s13, v70
	s_mov_b32 s13, 0x29000
	s_nop 0
	v_addc_co_u32_e32 v7, vcc, 0, v71, vcc
	global_load_dword v40, v[6:7], off offset:2048
	v_add_co_u32_e32 v6, vcc, s73, v70
	s_nop 1
	v_addc_co_u32_e32 v7, vcc, 0, v71, vcc
	global_load_dword v41, v[6:7], off offset:3072
	v_add_co_u32_e32 v6, vcc, s1, v70
	s_nop 1
	v_addc_co_u32_e32 v7, vcc, 0, v71, vcc
	global_load_dword v36, v[6:7], off
	v_add_co_u32_e32 v6, vcc, s13, v70
	s_mov_b32 s13, 0x2b000
	s_nop 0
	v_addc_co_u32_e32 v7, vcc, 0, v71, vcc
	global_load_dword v37, v[6:7], off offset:1024
	v_add_co_u32_e32 v6, vcc, s72, v70
	s_nop 1
	v_addc_co_u32_e32 v7, vcc, 0, v71, vcc
	global_load_dword v38, v[6:7], off offset:2048
	v_add_co_u32_e32 v6, vcc, s13, v70
	s_mov_b32 s13, 0x2d000
	s_nop 0
	v_addc_co_u32_e32 v7, vcc, 0, v71, vcc
	global_load_dword v39, v[6:7], off offset:3072
	v_add_co_u32_e32 v6, vcc, s13, v70
	s_mov_b32 s13, 0x2f000
	s_nop 0
	v_addc_co_u32_e32 v7, vcc, 0, v71, vcc
	global_load_dword v26, v[6:7], off
	v_add_co_u32_e32 v6, vcc, s33, v70
	s_nop 1
	v_addc_co_u32_e32 v7, vcc, 0, v71, vcc
	global_load_dword v27, v[6:7], off offset:1024
	v_add_co_u32_e32 v6, vcc, s13, v70
	s_mov_b32 s13, 0x33000
	s_nop 0
	v_addc_co_u32_e32 v7, vcc, 0, v71, vcc
	global_load_dword v32, v[6:7], off offset:2048
	v_add_co_u32_e32 v6, vcc, s22, v70
	s_nop 1
	v_addc_co_u32_e32 v7, vcc, 0, v71, vcc
	global_load_dword v33, v[6:7], off offset:3072
	v_add_co_u32_e32 v6, vcc, s38, v70
	s_nop 1
	v_addc_co_u32_e32 v7, vcc, 0, v71, vcc
	global_load_dword v28, v[6:7], off
	v_add_co_u32_e32 v6, vcc, s13, v70
	s_mov_b32 s13, 0x35000
	s_nop 0
	v_addc_co_u32_e32 v7, vcc, 0, v71, vcc
	global_load_dword v29, v[6:7], off offset:1024
	v_add_co_u32_e32 v6, vcc, s39, v70
	s_nop 1
	v_addc_co_u32_e32 v7, vcc, 0, v71, vcc
	global_load_dword v30, v[6:7], off offset:2048
	v_add_co_u32_e32 v6, vcc, s13, v70
	s_mov_b32 s13, 0x37000
	s_nop 0
	v_addc_co_u32_e32 v7, vcc, 0, v71, vcc
	global_load_dword v31, v[6:7], off offset:3072
	v_add_co_u32_e32 v6, vcc, s13, v70
	s_mov_b32 s13, 0x39000
	s_nop 0
	v_addc_co_u32_e32 v7, vcc, 0, v71, vcc
	global_load_dword v18, v[6:7], off
	v_add_co_u32_e32 v6, vcc, s69, v70
	s_nop 1
	v_addc_co_u32_e32 v7, vcc, 0, v71, vcc
	global_load_dword v19, v[6:7], off offset:1024
	v_add_co_u32_e32 v6, vcc, s13, v70
	s_mov_b32 s13, 0x3d000
	s_nop 0
	v_addc_co_u32_e32 v7, vcc, 0, v71, vcc
	global_load_dword v24, v[6:7], off offset:2048
	v_add_co_u32_e32 v6, vcc, s87, v70
	s_nop 1
	v_addc_co_u32_e32 v7, vcc, 0, v71, vcc
	global_load_dword v25, v[6:7], off offset:3072
	v_add_co_u32_e32 v6, vcc, s90, v70
	s_nop 1
	v_addc_co_u32_e32 v7, vcc, 0, v71, vcc
	global_load_dword v20, v[6:7], off
	v_add_co_u32_e32 v6, vcc, s13, v70
	s_mov_b32 s13, 0x41000
	s_nop 0
	v_addc_co_u32_e32 v7, vcc, 0, v71, vcc
	global_load_dword v21, v[6:7], off offset:1024
	v_add_co_u32_e32 v6, vcc, s51, v70
	s_nop 1
	v_addc_co_u32_e32 v7, vcc, 0, v71, vcc
	global_load_dword v22, v[6:7], off offset:2048
	v_add_co_u32_e32 v6, vcc, s52, v70
	s_nop 1
	v_addc_co_u32_e32 v7, vcc, 0, v71, vcc
	global_load_dword v23, v[6:7], off offset:3072
	v_add_co_u32_e32 v6, vcc, s13, v70
	s_mov_b32 s13, 0x43000
	s_nop 0
	v_addc_co_u32_e32 v7, vcc, 0, v71, vcc
	global_load_dword v8, v[6:7], off
	v_add_co_u32_e32 v6, vcc, s93, v70
	s_nop 1
	v_addc_co_u32_e32 v7, vcc, 0, v71, vcc
	global_load_dword v9, v[6:7], off offset:1024
	v_add_co_u32_e32 v6, vcc, s13, v70
	s_mov_b32 s13, 0x44000
	s_nop 0
	v_addc_co_u32_e32 v7, vcc, 0, v71, vcc
	global_load_dword v14, v[6:7], off offset:2048
	v_add_co_u32_e32 v6, vcc, s13, v70
	s_mov_b32 s13, 0x46000
	s_nop 0
	v_addc_co_u32_e32 v7, vcc, 0, v71, vcc
	global_load_dword v15, v[6:7], off offset:3072
	v_add_co_u32_e32 v6, vcc, s13, v70
	s_mov_b32 s13, 0x47000
	s_nop 0
	v_addc_co_u32_e32 v7, vcc, 0, v71, vcc
	global_load_dword v10, v[6:7], off
	v_add_co_u32_e32 v6, vcc, s13, v70
	s_mov_b32 s13, 0x48000
	s_nop 0
	v_addc_co_u32_e32 v7, vcc, 0, v71, vcc
	global_load_dword v11, v[6:7], off offset:1024
	v_add_co_u32_e32 v6, vcc, s13, v70
	s_mov_b32 s13, 0x49000
	s_nop 0
	v_addc_co_u32_e32 v7, vcc, 0, v71, vcc
	global_load_dword v16, v[6:7], off offset:2048
	v_add_co_u32_e32 v6, vcc, s13, v70
	s_mov_b32 s13, 0x4b000
	s_nop 0
	v_addc_co_u32_e32 v7, vcc, 0, v71, vcc
	global_load_dword v17, v[6:7], off offset:3072
	v_add_co_u32_e32 v6, vcc, s13, v70
	s_mov_b32 s13, 0x4c000
	s_nop 0
	v_addc_co_u32_e32 v7, vcc, 0, v71, vcc
	v_add_co_u32_e32 v12, vcc, s13, v70
	global_load_dword v6, v[6:7], off
	s_nop 0
	v_addc_co_u32_e32 v13, vcc, 0, v71, vcc
	global_load_dword v7, v[12:13], off offset:1024
	v_add_co_u32_e32 v12, vcc, 0x4d000, v70
	s_nop 1
	v_addc_co_u32_e32 v13, vcc, 0, v71, vcc
	v_add_co_u32_e32 v70, vcc, 0x4e000, v70
	global_load_dword v12, v[12:13], off offset:2048
	s_nop 0
	v_addc_co_u32_e32 v71, vcc, 0, v71, vcc
	global_load_dword v13, v[70:71], off offset:3072
	s_cbranch_scc1 .LBB0_874
	s_lshl_b64 s[4:5], s[18:19], 2
	s_add_u32 s4, s42, s4
	s_addc_u32 s5, s43, s5
	global_load_dwordx4 v[70:73], v161, s[4:5]
	s_mov_b64 s[30:31], 0
	s_waitcnt vmcnt(0)
	v_pk_mul_f32 v[70:71], v[66:67], v[70:71]
	v_pk_mul_f32 v[72:73], v[68:69], v[72:73]

; #define PIN(i) ((const float*)ldq_(L, (i)))
; #define PREP_CONV(bit, SRC, Kd, Nd, DST, GK, MODE) if (mask & (bit)) { for (int it = gw; it < ((Kd) / 64) * ((Nd) / 64); it += NGW) transpose_item((SRC), (Kd), (Nd), (bf16_t*)(wl + (DST)), (GK), (MODE), scr, it, lane); }
; __device__ __forceinline__ void transpose_item(const float* W, int K, int N, bf16_t* WT, const float* gk, int mode, LAS float* scr_, int item, int lane) {
;     ...
;     const int nblk = N / 64, kb = item / nblk, nb = item % nblk, k0 = 64 * kb, n0 = 64 * nb;
;     const int sc = (mode == 1) ? (((n0 >> 7) & 1) * DFF + (n0 >> 8) * 128 + (n0 & 127)) : n0;
;     const float* src = W + (size_t)k0 * N + sc + lane;
;     float va[32], vb[32];
; #pragma unroll
;     for (int kp = 0; kp < 32; ++kp) { va[kp] = src[(size_t)(2 * kp) * N]; vb[kp] = src[(size_t)(2 * kp + 1) * N]; }
; #pragma unroll
;     for (int kp = 0; kp < 32; ++kp) {
;         float a = va[kp], b = vb[kp];
;         if (gk) { a *= gk[k0 + 2 * kp]; b *= gk[k0 + 2 * kp + 1]; }
; __device__ __forceinline__ void prep(const Params& p, LAS unsigned char* L, int wv, int vb, int nvb, int l, int mask) {
;     ...
;     PREP_CONV(PM_FFB_IN, PIN(I_WFFB_IN) + (size_t)l * DM * NFF2, DM, NFF2, WL_FFB_IN, PIN(I_NFFB) + l * DM, 1)
.LBB0_942:
	v_mov_b32_e32 v6, v161
	s_mul_i32 s18, s6, 0x1600000
	v_add_u32_e32 v6, 0, v6
	v_add_u32_e32 v6, 0x20198, v6
	s_nop 0
	s_mov_b64 s[30:31], -1
	s_waitcnt lgkmcnt(0)
	v_readlane_b32 s5, v251, 38
	v_mov_b32_e32 v6, v161
	v_readlane_b32 s4, v251, 39
	v_add_u32_e32 v6, 0, v6
	v_add_u32_e32 v6, 0x20190, v6
	s_nop 0
	s_add_u32 s21, s5, s18
	s_mul_hi_i32 s5, s6, 0x1600000
	s_addc_u32 s25, s4, s5
	s_mul_hi_i32 s18, s42, 0x2e8ba2e9
	s_waitcnt lgkmcnt(0)
	v_readlane_b32 s4, v251, 36
	v_readlane_b32 s5, v251, 37
	s_add_u32 s44, s4, s12
	s_addc_u32 s45, s5, s13
	s_lshr_b32 s19, s18, 31
	s_ashr_i32 s18, s18, 4
	s_add_i32 s26, s18, s19
	s_mul_i32 s19, s26, 0xffffea00
	s_mul_i32 s24, s26, 0xfffff500
	s_add_i32 s43, s15, s19
	s_bfe_i32 s19, s42, 0x10001
	s_add_i32 s24, s29, s24
	s_and_b32 s19, s19, 0xb00
	s_and_b32 s24, s24, 0xffffff80
	s_lshl_b32 s18, s26, 6
	s_add_i32 s19, s19, s24
	s_and_b32 s24, s43, 64
	s_or_b32 s24, s19, s24
	s_ashr_i32 s19, s18, 31
	s_mul_i32 s26, s26, 0x160000
	s_mul_hi_i32 s28, s18, 0x5800
	s_add_u32 s21, s21, s26
	s_addc_u32 s26, s25, s28
	s_ashr_i32 s25, s24, 31
	s_lshl_b64 s[24:25], s[24:25], 2
	s_add_u32 s24, s21, s24
	s_addc_u32 s25, s26, s25
	v_lshl_add_u64 v[70:71], s[24:25], 0, v[160:161]
	s_movk_i32 s21, 0x5000
	v_add_co_u32_e32 v6, vcc, s21, v70
	s_mov_b32 s21, 0xb000
	s_nop 0
	v_addc_co_u32_e32 v7, vcc, 0, v71, vcc
	global_load_dword v67, v[6:7], off offset:2048
	v_add_co_u32_e32 v6, vcc, s21, v70
	global_load_dword v66, v160, s[24:25]
	s_nop 0
	v_addc_co_u32_e32 v7, vcc, 0, v71, vcc
	global_load_dword v68, v[6:7], off
	v_add_co_u32_e32 v6, vcc, s37, v70
	s_mov_b32 s21, 0x1b000
	s_nop 0
	v_addc_co_u32_e32 v7, vcc, 0, v71, vcc
	global_load_dword v69, v[6:7], off offset:2048
	v_add_co_u32_e32 v6, vcc, s47, v70
	s_cmp_lg_u64 s[4:5], 0
	s_nop 0
	v_addc_co_u32_e32 v7, vcc, 0, v71, vcc
	global_load_dword v58, v[6:7], off
	v_add_co_u32_e32 v6, vcc, s21, v70
	s_mov_b32 s21, 0x21000
	s_nop 0
	v_addc_co_u32_e32 v7, vcc, 0, v71, vcc
	global_load_dword v59, v[6:7], off offset:2048
	v_add_co_u32_e32 v6, vcc, s21, v70
	s_mov_b32 s21, 0x31000
	s_nop 0
	v_addc_co_u32_e32 v7, vcc, 0, v71, vcc
	global_load_dword v64, v[6:7], off
	v_add_co_u32_e32 v6, vcc, s73, v70
	s_cselect_b64 s[24:25], -1, 0
	s_nop 0
	v_addc_co_u32_e32 v7, vcc, 0, v71, vcc
	global_load_dword v65, v[6:7], off offset:2048
	v_add_co_u32_e32 v6, vcc, s82, v70
	s_cmp_eq_u64 s[4:5], 0
	s_nop 0
	v_addc_co_u32_e32 v7, vcc, 0, v71, vcc
	global_load_dword v60, v[6:7], off
	v_add_co_u32_e32 v6, vcc, s21, v70
	s_mov_b32 s21, 0x37000
	s_nop 0
	v_addc_co_u32_e32 v7, vcc, 0, v71, vcc
	global_load_dword v61, v[6:7], off offset:2048
	v_add_co_u32_e32 v6, vcc, s21, v70
	s_mov_b32 s21, 0x47000
	s_nop 0
	v_addc_co_u32_e32 v7, vcc, 0, v71, vcc
	global_load_dword v62, v[6:7], off
	v_add_co_u32_e32 v6, vcc, s90, v70
	s_nop 1
	v_addc_co_u32_e32 v7, vcc, 0, v71, vcc
	global_load_dword v63, v[6:7], off offset:2048
	v_add_co_u32_e32 v6, vcc, s93, v70
	s_nop 1
	v_addc_co_u32_e32 v7, vcc, 0, v71, vcc
	global_load_dword v48, v[6:7], off
	v_add_co_u32_e32 v6, vcc, s21, v70
	s_mov_b32 s21, 0x4d000
	s_nop 0
	v_addc_co_u32_e32 v7, vcc, 0, v71, vcc
	global_load_dword v49, v[6:7], off offset:2048
	v_add_co_u32_e32 v6, vcc, s21, v70
	s_mov_b32 s21, 0x52000
	s_nop 0
	v_addc_co_u32_e32 v7, vcc, 0, v71, vcc
	global_load_dword v54, v[6:7], off
	v_add_co_u32_e32 v6, vcc, s21, v70
	s_mov_b32 s21, 0x58000
	s_nop 0
	v_addc_co_u32_e32 v7, vcc, 0, v71, vcc
	global_load_dword v55, v[6:7], off offset:2048
	v_add_co_u32_e32 v6, vcc, s21, v70
	s_mov_b32 s21, 0x5d000
	s_nop 0
	v_addc_co_u32_e32 v7, vcc, 0, v71, vcc
	global_load_dword v52, v[6:7], off
	v_add_co_u32_e32 v6, vcc, s21, v70
	s_mov_b32 s21, 0x63000
	s_nop 0
	v_addc_co_u32_e32 v7, vcc, 0, v71, vcc
	global_load_dword v53, v[6:7], off offset:2048
	v_add_co_u32_e32 v6, vcc, s21, v70
	s_mov_b32 s21, 0x68000
	s_nop 0
	v_addc_co_u32_e32 v7, vcc, 0, v71, vcc
	global_load_dword v56, v[6:7], off
	v_add_co_u32_e32 v6, vcc, s21, v70
	s_mov_b32 s21, 0x6e000
	s_nop 0
	v_addc_co_u32_e32 v7, vcc, 0, v71, vcc
	global_load_dword v57, v[6:7], off offset:2048
	v_add_co_u32_e32 v6, vcc, s21, v70
	s_mov_b32 s21, 0x73000
	s_nop 0
	v_addc_co_u32_e32 v7, vcc, 0, v71, vcc
	global_load_dword v42, v[6:7], off
	v_add_co_u32_e32 v6, vcc, s21, v70
	s_mov_b32 s21, 0x79000
	s_nop 0
	v_addc_co_u32_e32 v7, vcc, 0, v71, vcc
	global_load_dword v43, v[6:7], off offset:2048
	v_add_co_u32_e32 v6, vcc, s21, v70
	s_mov_b32 s21, 0x7e000
	s_nop 0
	v_addc_co_u32_e32 v7, vcc, 0, v71, vcc
	global_load_dword v46, v[6:7], off
	v_add_co_u32_e32 v6, vcc, s21, v70
	s_mov_b32 s21, 0x84000
	s_nop 0
	v_addc_co_u32_e32 v7, vcc, 0, v71, vcc
	global_load_dword v47, v[6:7], off offset:2048
	v_add_co_u32_e32 v6, vcc, s21, v70
	s_mov_b32 s21, 0x89000
	s_nop 0
	v_addc_co_u32_e32 v7, vcc, 0, v71, vcc
	global_load_dword v44, v[6:7], off
	v_add_co_u32_e32 v6, vcc, s21, v70
	s_mov_b32 s21, 0x8f000
	s_nop 0
	v_addc_co_u32_e32 v7, vcc, 0, v71, vcc
	global_load_dword v45, v[6:7], off offset:2048
	v_add_co_u32_e32 v6, vcc, s21, v70
	s_mov_b32 s21, 0x94000
	s_nop 0
	v_addc_co_u32_e32 v7, vcc, 0, v71, vcc
	global_load_dword v50, v[6:7], off
	v_add_co_u32_e32 v6, vcc, s21, v70
	s_mov_b32 s21, 0x9a000
	s_nop 0
	v_addc_co_u32_e32 v7, vcc, 0, v71, vcc
	global_load_dword v51, v[6:7], off offset:2048
	v_add_co_u32_e32 v6, vcc, s21, v70
	s_mov_b32 s21, 0x9f000
	s_nop 0
	v_addc_co_u32_e32 v7, vcc, 0, v71, vcc
	global_load_dword v34, v[6:7], off
; __device__ __forceinline__ void transpose_item(const float* W, int K, int N, bf16_t* WT, const float* gk, int mode, LAS float* scr_, int item, int lane) {
;     ...
;     float va[32], vb[32];
; #pragma unroll
;     for (int kp = 0; kp < 32; ++kp) { va[kp] = src[(size_t)(2 * kp) * N]; vb[kp] = src[(size_t)(2 * kp + 1) * N]; }
; #pragma unroll
;     for (int kp = 0; kp < 32; ++kp) {
;         float a = va[kp], b = vb[kp];
;         if (gk) { a *= gk[k0 + 2 * kp]; b *= gk[k0 + 2 * kp + 1]; }
	v_add_co_u32_e32 v6, vcc, s21, v70
	s_mov_b32 s21, 0xa5000
	s_nop 0
	v_addc_co_u32_e32 v7, vcc, 0, v71, vcc
	global_load_dword v35, v[6:7], off offset:2048
	v_add_co_u32_e32 v6, vcc, s21, v70
	s_mov_b32 s21, 0xaa000
	s_nop 0
	v_addc_co_u32_e32 v7, vcc, 0, v71, vcc
	global_load_dword v40, v[6:7], off
	v_add_co_u32_e32 v6, vcc, s21, v70
	s_mov_b32 s21, 0xb5000
	s_nop 0
	v_addc_co_u32_e32 v7, vcc, 0, v71, vcc
	global_load_dword v41, v[6:7], off offset:2048
	v_add_co_u32_e32 v6, vcc, s95, v70
	s_nop 1
	v_addc_co_u32_e32 v7, vcc, 0, v71, vcc
	global_load_dword v36, v[6:7], off
	v_add_co_u32_e32 v6, vcc, s21, v70
	s_mov_b32 s21, 0xbb000
	s_nop 0
	v_addc_co_u32_e32 v7, vcc, 0, v71, vcc
	global_load_dword v37, v[6:7], off offset:2048
	v_add_co_u32_e32 v6, vcc, s21, v70
	s_mov_b32 s21, 0xc0000
	s_nop 0
	v_addc_co_u32_e32 v7, vcc, 0, v71, vcc
	global_load_dword v38, v[6:7], off
	v_add_co_u32_e32 v6, vcc, s21, v70
	s_mov_b32 s21, 0xcb000
	s_nop 0
	v_addc_co_u32_e32 v7, vcc, 0, v71, vcc
	global_load_dword v39, v[6:7], off offset:2048
	v_add_co_u32_e32 v6, vcc, s89, v70
	s_nop 1
	v_addc_co_u32_e32 v7, vcc, 0, v71, vcc
	global_load_dword v24, v[6:7], off
	v_add_co_u32_e32 v6, vcc, s21, v70
	s_mov_b32 s21, 0xd1000
	s_nop 0
	v_addc_co_u32_e32 v7, vcc, 0, v71, vcc
	global_load_dword v25, v[6:7], off offset:2048
	v_add_co_u32_e32 v6, vcc, s21, v70
	s_mov_b32 s21, 0xd6000
	s_nop 0
	v_addc_co_u32_e32 v7, vcc, 0, v71, vcc
	global_load_dword v30, v[6:7], off
	v_add_co_u32_e32 v6, vcc, s21, v70
	s_mov_b32 s21, 0xdc000
	s_nop 0
	v_addc_co_u32_e32 v7, vcc, 0, v71, vcc
	global_load_dword v31, v[6:7], off offset:2048
	v_add_co_u32_e32 v6, vcc, s21, v70
	s_mov_b32 s21, 0xe1000
	s_nop 0
	v_addc_co_u32_e32 v7, vcc, 0, v71, vcc
	global_load_dword v28, v[6:7], off
	v_add_co_u32_e32 v6, vcc, s21, v70
	s_mov_b32 s21, 0xe7000
	s_nop 0
	v_addc_co_u32_e32 v7, vcc, 0, v71, vcc
	global_load_dword v29, v[6:7], off offset:2048
	v_add_co_u32_e32 v6, vcc, s21, v70
	s_mov_b32 s21, 0xec000
	s_nop 0
	v_addc_co_u32_e32 v7, vcc, 0, v71, vcc
	global_load_dword v32, v[6:7], off
	v_add_co_u32_e32 v6, vcc, s21, v70
	s_mov_b32 s21, 0xf2000
	s_nop 0
	v_addc_co_u32_e32 v7, vcc, 0, v71, vcc
	global_load_dword v33, v[6:7], off offset:2048
	v_add_co_u32_e32 v6, vcc, s21, v70
	s_mov_b32 s21, 0xf7000
	s_nop 0
	v_addc_co_u32_e32 v7, vcc, 0, v71, vcc
	global_load_dword v16, v[6:7], off
	v_add_co_u32_e32 v6, vcc, s21, v70
	s_mov_b32 s21, 0xfd000
	s_nop 0
	v_addc_co_u32_e32 v7, vcc, 0, v71, vcc
	global_load_dword v17, v[6:7], off offset:2048
	v_add_co_u32_e32 v6, vcc, s21, v70
	s_mov_b32 s21, 0x102000
	s_nop 0
	v_addc_co_u32_e32 v7, vcc, 0, v71, vcc
	global_load_dword v22, v[6:7], off
	v_add_co_u32_e32 v6, vcc, s21, v70
	s_mov_b32 s21, 0x108000
	s_nop 0
	v_addc_co_u32_e32 v7, vcc, 0, v71, vcc
	global_load_dword v23, v[6:7], off offset:2048
	v_add_co_u32_e32 v6, vcc, s21, v70
	s_mov_b32 s21, 0x10d000
	s_nop 0
	v_addc_co_u32_e32 v7, vcc, 0, v71, vcc
	global_load_dword v20, v[6:7], off
	v_add_co_u32_e32 v6, vcc, s21, v70
	s_mov_b32 s21, 0x113000
	s_nop 0
	v_addc_co_u32_e32 v7, vcc, 0, v71, vcc
	global_load_dword v21, v[6:7], off offset:2048
	v_add_co_u32_e32 v6, vcc, s21, v70
	s_mov_b32 s21, 0x118000
	s_nop 0
	v_addc_co_u32_e32 v7, vcc, 0, v71, vcc
	global_load_dword v26, v[6:7], off
	v_add_co_u32_e32 v6, vcc, s21, v70
	s_mov_b32 s21, 0x11e000
	s_nop 0
	v_addc_co_u32_e32 v7, vcc, 0, v71, vcc
	global_load_dword v27, v[6:7], off offset:2048
	v_add_co_u32_e32 v6, vcc, s21, v70
	s_mov_b32 s21, 0x123000
	s_nop 0
	v_addc_co_u32_e32 v7, vcc, 0, v71, vcc
	global_load_dword v8, v[6:7], off
	v_add_co_u32_e32 v6, vcc, s21, v70
	s_mov_b32 s21, 0x129000
	s_nop 0
	v_addc_co_u32_e32 v7, vcc, 0, v71, vcc
	global_load_dword v9, v[6:7], off offset:2048
	v_add_co_u32_e32 v6, vcc, s21, v70
	s_mov_b32 s21, 0x12e000
	s_nop 0
	v_addc_co_u32_e32 v7, vcc, 0, v71, vcc
	global_load_dword v14, v[6:7], off
	v_add_co_u32_e32 v6, vcc, s21, v70
	s_mov_b32 s21, 0x134000
	s_nop 0
	v_addc_co_u32_e32 v7, vcc, 0, v71, vcc
	global_load_dword v15, v[6:7], off offset:2048
	v_add_co_u32_e32 v6, vcc, s21, v70
	s_mov_b32 s21, 0x139000
	s_nop 0
	v_addc_co_u32_e32 v7, vcc, 0, v71, vcc
	global_load_dword v10, v[6:7], off
	v_add_co_u32_e32 v6, vcc, s21, v70
	s_mov_b32 s21, 0x13f000
	s_nop 0
	v_addc_co_u32_e32 v7, vcc, 0, v71, vcc
	global_load_dword v11, v[6:7], off offset:2048
	v_add_co_u32_e32 v6, vcc, s21, v70
	s_mov_b32 s21, 0x144000
	s_nop 0
	v_addc_co_u32_e32 v7, vcc, 0, v71, vcc
	global_load_dword v18, v[6:7], off
	v_add_co_u32_e32 v6, vcc, s21, v70
	s_mov_b32 s21, 0x14a000
	s_nop 0
	v_addc_co_u32_e32 v7, vcc, 0, v71, vcc
	global_load_dword v19, v[6:7], off offset:2048
	v_add_co_u32_e32 v6, vcc, s21, v70
	s_mov_b32 s21, 0x14f000
	s_nop 0
	v_addc_co_u32_e32 v7, vcc, 0, v71, vcc
	v_add_co_u32_e32 v12, vcc, s21, v70
	global_load_dword v6, v[6:7], off
	s_nop 0
	v_addc_co_u32_e32 v13, vcc, 0, v71, vcc
	global_load_dword v7, v[12:13], off offset:2048
	v_add_co_u32_e32 v12, vcc, 0x155000, v70
	s_nop 1
	v_addc_co_u32_e32 v13, vcc, 0, v71, vcc
	v_add_co_u32_e32 v70, vcc, 0x15a000, v70
	global_load_dword v12, v[12:13], off
	s_nop 0
	v_addc_co_u32_e32 v71, vcc, 0, v71, vcc
	global_load_dword v13, v[70:71], off offset:2048
	s_cbranch_scc1 .LBB0_944
	s_lshl_b64 s[4:5], s[18:19], 2
	s_add_u32 s4, s44, s4
	s_addc_u32 s5, s45, s5
	global_load_dwordx4 v[70:73], v161, s[4:5]
	s_mov_b64 s[30:31], 0
	s_waitcnt vmcnt(0)
	v_pk_mul_f32 v[70:71], v[66:67], v[70:71]
	v_pk_mul_f32 v[72:73], v[68:69], v[72:73]

; #define PIN(i) ((const float*)ldq_(L, (i)))
; #define PREP_CONV(bit, SRC, Kd, Nd, DST, GK, MODE) if (mask & (bit)) { for (int it = gw; it < ((Kd) / 64) * ((Nd) / 64); it += NGW) transpose_item((SRC), (Kd), (Nd), (bf16_t*)(wl + (DST)), (GK), (MODE), scr, it, lane); }
; __device__ __forceinline__ void transpose_item(const float* W, int K, int N, bf16_t* WT, const float* gk, int mode, LAS float* scr_, int item, int lane) {
;     ...
;     const int nblk = N / 64, kb = item / nblk, nb = item % nblk, k0 = 64 * kb, n0 = 64 * nb;
;     const int sc = (mode == 1) ? (((n0 >> 7) & 1) * DFF + (n0 >> 8) * 128 + (n0 & 127)) : n0;
;     const float* src = W + (size_t)k0 * N + sc + lane;
;     float va[32], vb[32];
; #pragma unroll
;     for (int kp = 0; kp < 32; ++kp) { va[kp] = src[(size_t)(2 * kp) * N]; vb[kp] = src[(size_t)(2 * kp + 1) * N]; }
; #pragma unroll
;     for (int kp = 0; kp < 32; ++kp) {
;         float a = va[kp], b = vb[kp];
;         if (gk) { a *= gk[k0 + 2 * kp]; b *= gk[k0 + 2 * kp + 1]; }
; __device__ __forceinline__ void prep(const Params& p, LAS unsigned char* L, int wv, int vb, int nvb, int l, int mask) {
;     ...
;     PREP_CONV(PM_PEG, PIN(I_WPEG) + (size_t)l * DM * DM, DM, DM, WL_PEG, PIN(I_NPE) + l * DM, 0)
.LBB0_1012:
	v_mov_b32_e32 v6, v161
	s_nop 0
	v_add_u32_e32 v6, 0, v6
	v_add_u32_e32 v6, 0x201b0, v6
	s_nop 0
	s_waitcnt lgkmcnt(0)
	v_readlane_b32 s5, v251, 44
	v_mov_b32_e32 v6, v161
	v_readlane_b32 s4, v251, 45
	v_add_u32_e32 v6, 0, v6
	v_add_u32_e32 v6, 0x201a8, v6
	s_nop 0
	s_add_u32 s21, s5, s10
	s_addc_u32 s25, s4, s11
	s_waitcnt lgkmcnt(0)
	v_readlane_b32 s4, v251, 42
	v_readlane_b32 s5, v251, 43
	s_add_u32 s43, s4, s12
	s_addc_u32 s44, s5, s13
	s_ashr_i32 s18, s29, 31
	s_lshr_b32 s18, s18, 28
	s_add_i32 s18, s29, s18
	s_ashr_i32 s19, s18, 4
	s_lshl_b32 s18, s19, 6
	s_lshl_b32 s42, s19, 10
	s_ashr_i32 s19, s18, 31
	s_sub_i32 s24, s15, s42
	s_lshl_b64 s[30:31], s[18:19], 12
	s_add_u32 s21, s21, s30
	s_addc_u32 s26, s25, s31
	s_ashr_i32 s25, s24, 31
	s_lshl_b64 s[24:25], s[24:25], 2
	s_add_u32 s24, s21, s24
	s_addc_u32 s25, s26, s25
	v_lshl_add_u64 v[70:71], s[24:25], 0, v[160:161]
	v_add_co_u32_e32 v6, vcc, s79, v70
	global_load_dword v66, v160, s[24:25]
	s_nop 0
	v_addc_co_u32_e32 v7, vcc, 0, v71, vcc
	global_load_dword v67, v[6:7], off offset:-4096
	global_load_dword v68, v[6:7], off
	v_add_co_u32_e32 v6, vcc, s88, v70
	s_mov_b32 s21, 0x3d000
	s_nop 0
	v_addc_co_u32_e32 v7, vcc, 0, v71, vcc
	global_load_dword v69, v[6:7], off offset:-4096
	global_load_dword v62, v[6:7], off
	v_add_co_u32_e32 v6, vcc, s80, v70
	s_cmp_lg_u64 s[4:5], 0
	s_nop 0
	v_addc_co_u32_e32 v7, vcc, 0, v71, vcc
	global_load_dword v63, v[6:7], off offset:-4096
	global_load_dword v64, v[6:7], off
	v_add_co_u32_e32 v6, vcc, s70, v70
	s_mov_b64 s[30:31], -1
	s_nop 0
	v_addc_co_u32_e32 v7, vcc, 0, v71, vcc
	global_load_dword v65, v[6:7], off offset:-4096
	global_load_dword v58, v[6:7], off
	v_add_co_u32_e32 v6, vcc, s71, v70
	s_cselect_b64 s[24:25], -1, 0
	s_nop 0
	v_addc_co_u32_e32 v7, vcc, 0, v71, vcc
	global_load_dword v59, v[6:7], off offset:-4096
	global_load_dword v60, v[6:7], off
	v_add_co_u32_e32 v6, vcc, s91, v70
	s_cmp_eq_u64 s[4:5], 0
	s_nop 0
	v_addc_co_u32_e32 v7, vcc, 0, v71, vcc
	global_load_dword v61, v[6:7], off offset:-4096
	global_load_dword v54, v[6:7], off
	v_add_co_u32_e32 v6, vcc, s92, v70
	s_nop 1
	v_addc_co_u32_e32 v7, vcc, 0, v71, vcc
	global_load_dword v55, v[6:7], off offset:-4096
	global_load_dword v56, v[6:7], off
	v_add_co_u32_e32 v6, vcc, s37, v70
	s_nop 1
	v_addc_co_u32_e32 v7, vcc, 0, v71, vcc
	global_load_dword v57, v[6:7], off offset:-4096
	global_load_dword v50, v[6:7], off
	v_add_co_u32_e32 v6, vcc, s94, v70
	s_nop 1
	v_addc_co_u32_e32 v7, vcc, 0, v71, vcc
	global_load_dword v51, v[6:7], off offset:-4096
	global_load_dword v52, v[6:7], off
	v_add_co_u32_e32 v6, vcc, s46, v70
	s_nop 1
	v_addc_co_u32_e32 v7, vcc, 0, v71, vcc
	global_load_dword v53, v[6:7], off offset:-4096
	global_load_dword v46, v[6:7], off
	v_add_co_u32_e32 v6, vcc, s47, v70
	s_nop 1
	v_addc_co_u32_e32 v7, vcc, 0, v71, vcc
	global_load_dword v47, v[6:7], off offset:-4096
	global_load_dword v48, v[6:7], off
	v_add_co_u32_e32 v6, vcc, s59, v70
	s_nop 1
	v_addc_co_u32_e32 v7, vcc, 0, v71, vcc
	global_load_dword v49, v[6:7], off offset:-4096
	global_load_dword v42, v[6:7], off
	v_add_co_u32_e32 v6, vcc, s81, v70
	s_nop 1
	v_addc_co_u32_e32 v7, vcc, 0, v71, vcc
	global_load_dword v43, v[6:7], off offset:-4096
	global_load_dword v44, v[6:7], off
	v_add_co_u32_e32 v6, vcc, s83, v70
	s_nop 1
	v_addc_co_u32_e32 v7, vcc, 0, v71, vcc
	global_load_dword v45, v[6:7], off offset:-4096
	global_load_dword v38, v[6:7], off
	v_add_co_u32_e32 v6, vcc, s27, v70
	s_nop 1
	v_addc_co_u32_e32 v7, vcc, 0, v71, vcc
	global_load_dword v39, v[6:7], off offset:-4096
	global_load_dword v40, v[6:7], off
	v_add_co_u32_e32 v6, vcc, s50, v70
	s_nop 1
	v_addc_co_u32_e32 v7, vcc, 0, v71, vcc
	global_load_dword v41, v[6:7], off offset:-4096
	global_load_dword v34, v[6:7], off
	v_add_co_u32_e32 v6, vcc, s53, v70
	s_nop 1
	v_addc_co_u32_e32 v7, vcc, 0, v71, vcc
	global_load_dword v35, v[6:7], off offset:-4096
	global_load_dword v36, v[6:7], off
	v_add_co_u32_e32 v6, vcc, s0, v70
	s_nop 1
	v_addc_co_u32_e32 v7, vcc, 0, v71, vcc
	global_load_dword v37, v[6:7], off offset:-4096
	global_load_dword v30, v[6:7], off
	v_add_co_u32_e32 v6, vcc, s73, v70
	s_nop 1
	v_addc_co_u32_e32 v7, vcc, 0, v71, vcc
	global_load_dword v31, v[6:7], off offset:-4096
	global_load_dword v32, v[6:7], off
	v_add_co_u32_e32 v6, vcc, s1, v70
	s_nop 1
	v_addc_co_u32_e32 v7, vcc, 0, v71, vcc
	global_load_dword v33, v[6:7], off offset:-4096
	global_load_dword v26, v[6:7], off
	v_add_co_u32_e32 v6, vcc, s72, v70
	s_nop 1
	v_addc_co_u32_e32 v7, vcc, 0, v71, vcc
	global_load_dword v27, v[6:7], off offset:-4096
	global_load_dword v28, v[6:7], off
	v_add_co_u32_e32 v6, vcc, s82, v70
	s_nop 1
	v_addc_co_u32_e32 v7, vcc, 0, v71, vcc
	global_load_dword v29, v[6:7], off offset:-4096
	global_load_dword v22, v[6:7], off
	v_add_co_u32_e32 v6, vcc, s33, v70
	s_nop 1
	v_addc_co_u32_e32 v7, vcc, 0, v71, vcc
	global_load_dword v23, v[6:7], off offset:-4096
	global_load_dword v24, v[6:7], off
	v_add_co_u32_e32 v6, vcc, s22, v70
	s_nop 1
	v_addc_co_u32_e32 v7, vcc, 0, v71, vcc
	global_load_dword v25, v[6:7], off offset:-4096
	global_load_dword v18, v[6:7], off
	v_add_co_u32_e32 v6, vcc, s38, v70
	s_nop 1
	v_addc_co_u32_e32 v7, vcc, 0, v71, vcc
	global_load_dword v19, v[6:7], off offset:-4096
	global_load_dword v20, v[6:7], off
	v_add_co_u32_e32 v6, vcc, s39, v70
	s_nop 1
	v_addc_co_u32_e32 v7, vcc, 0, v71, vcc
	global_load_dword v21, v[6:7], off offset:-4096
	global_load_dword v14, v[6:7], off
	v_add_co_u32_e32 v6, vcc, s56, v70
	s_nop 1
	v_addc_co_u32_e32 v7, vcc, 0, v71, vcc
	global_load_dword v15, v[6:7], off offset:-4096
	global_load_dword v16, v[6:7], off
	v_add_co_u32_e32 v6, vcc, s69, v70
	s_nop 1
	v_addc_co_u32_e32 v7, vcc, 0, v71, vcc
	v_add_co_u32_e32 v8, vcc, s87, v70
	global_load_dword v17, v[6:7], off offset:-4096
	s_nop 0
	global_load_dword v6, v[6:7], off
	v_addc_co_u32_e32 v9, vcc, 0, v71, vcc
	global_load_dword v7, v[8:9], off offset:-4096
	global_load_dword v12, v[8:9], off
	v_add_co_u32_e32 v8, vcc, 0x3b000, v70
	s_nop 1
	v_addc_co_u32_e32 v9, vcc, 0, v71, vcc
	v_add_co_u32_e32 v10, vcc, s21, v70
	global_load_dword v13, v[8:9], off
	s_nop 0
	v_addc_co_u32_e32 v11, vcc, 0, v71, vcc
	global_load_dword v8, v[10:11], off offset:-4096
	global_load_dword v9, v[10:11], off
	v_add_co_u32_e32 v10, vcc, 0x3e000, v70
	s_nop 1
	v_addc_co_u32_e32 v11, vcc, 0, v71, vcc
	v_add_co_u32_e32 v70, vcc, 0x3f000, v70
	global_load_dword v10, v[10:11], off
	s_nop 0
	v_addc_co_u32_e32 v71, vcc, 0, v71, vcc
	global_load_dword v11, v[70:71], off
	s_cbranch_scc1 .LBB0_1014
	s_lshl_b64 s[4:5], s[18:19], 2
	s_add_u32 s4, s43, s4
	s_addc_u32 s5, s44, s5
	global_load_dwordx4 v[70:73], v161, s[4:5]
	s_mov_b64 s[30:31], 0
	s_waitcnt vmcnt(0)
	v_pk_mul_f32 v[70:71], v[66:67], v[70:71]
	v_pk_mul_f32 v[72:73], v[68:69], v[72:73]

; #define PIN(i) ((const float*)ldq_(L, (i)))
; __device__ __forceinline__ unsigned pk2(float lo, float hi) { f32x2 v = {lo, hi}; bf16x2_t b = __builtin_convertvector(v, bf16x2_t); return __builtin_bit_cast(unsigned, b); }
; __device__ __forceinline__ void prep(const Params& p, LAS unsigned char* L, int wv, int vb, int nvb, int l, int mask) {
;     ...
;     if (mask & PM_POOL) {
;         for (int t = gt; t < 4 * 128 * 16; t += NGT) {
;             const int ko = t & 15, n = (t >> 4) & 127, g = (t >> 11) & 3;
;             const float* src = PIN(I_WPOOL) + ((size_t)(l * 4 + g) * 128 + 8 * ko) * 128 + n; const float sc = PIN(I_PSCALE)[l * 512 + g * 128 + n];
;             u32x4 o; o.x = pk2(src[0] * sc, src[128] * sc); o.y = pk2(src[256] * sc, src[384] * sc); o.z = pk2(src[512] * sc, src[640] * sc); o.w = pk2(src[768] * sc, src[896] * sc);
;             *(u32x4*)((bf16_t*)(wl + WL_POOL) + ((size_t)g * 128 + n) * 128 + 8 * ko) = o;
;         }
.LBB0_1081:
	v_mov_b32_e32 v2, v161
	v_add_u32_e32 v0, 0x1c000, v0
	v_add_u32_e32 v2, 0, v2
	v_add_u32_e32 v2, 0x20178, v2
	s_nop 0
	v_bfe_u32 v12, v0, 11, 2
	v_and_b32_e32 v13, 0x78, v1
	v_bfe_u32 v9, v0, 4, 7
	v_lshlrev_b32_e32 v160, 9, v13
	s_waitcnt lgkmcnt(0)
	v_readlane_b32 s14, v251, 30
	v_or_b32_e32 v2, s12, v12
	v_readlane_b32 s15, v251, 31
	v_ashrrev_i32_e32 v3, 31, v2
	v_lshlrev_b64 v[2:3], 16, v[2:3]
	v_lshl_add_u64 v[2:3], s[14:15], 0, v[2:3]
	v_lshl_add_u64 v[2:3], v[2:3], 0, v[160:161]
	v_lshlrev_b32_e32 v160, 2, v9
	v_lshl_add_u64 v[6:7], v[2:3], 0, v[160:161]
	v_mov_b32_e32 v2, v161
	v_lshlrev_b32_e32 v4, 7, v12
	v_add_u32_e32 v2, 0, v2
	v_add_u32_e32 v2, 0x20180, v2
	s_nop 0
	v_or3_b32 v4, v4, s13, v9
	v_ashrrev_i32_e32 v5, 31, v4
	v_cmp_lt_i32_e32 vcc, s18, v0
	v_add_u32_e32 v1, 0xe0000, v1
	s_waitcnt lgkmcnt(0)
	v_readlane_b32 s14, v251, 33
	v_readlane_b32 s15, v251, 32
	s_or_b64 s[10:11], vcc, s[10:11]
	v_mov_b32_e32 v3, s14
	v_mov_b32_e32 v2, s15
	v_lshl_add_u64 v[2:3], v[4:5], 2, v[2:3]
	global_load_dword v8, v[2:3], off
	s_nop 0
	global_load_dword v2, v[6:7], off
	global_load_dword v3, v[6:7], off offset:512
	global_load_dword v4, v[6:7], off offset:1024
	global_load_dword v5, v[6:7], off offset:1536
	s_waitcnt vmcnt(2)
	v_pk_mul_f32 v[2:3], v[8:9], v[2:3] op_sel_hi:[0,1]
	s_waitcnt vmcnt(0)
	v_pk_mul_f32 v[4:5], v[8:9], v[4:5] op_sel_hi:[0,1]
	v_cvt_pk_bf16_f32 v2, v2, v3
	v_cvt_pk_bf16_f32 v3, v4, v5
	global_load_dword v4, v[6:7], off offset:2048
	global_load_dword v5, v[6:7], off offset:2560
	global_load_dword v10, v[6:7], off offset:3072
	global_load_dword v11, v[6:7], off offset:3584
	s_waitcnt vmcnt(2)
	v_pk_mul_f32 v[4:5], v[8:9], v[4:5] op_sel_hi:[0,1]
	s_waitcnt vmcnt(0)
	v_pk_mul_f32 v[6:7], v[8:9], v[10:11] op_sel_hi:[0,1]
	v_cvt_pk_bf16_f32 v4, v4, v5
	v_cvt_pk_bf16_f32 v5, v6, v7
	v_lshlrev_b32_e32 v6, 8, v9
	v_lshl_or_b32 v160, v12, 15, v6
	v_lshl_add_u64 v[6:7], s[8:9], 0, v[160:161]
	v_lshlrev_b32_e32 v160, 1, v13
	v_lshl_add_u64 v[6:7], v[6:7], 0, v[160:161]
	global_store_dwordx4 v[6:7], v[2:5], off
	s_andn2_b64 exec, exec, s[10:11]
	s_cbranch_execnz .LBB0_1081

; #define PG8_STAGE(bufoff, gbase, voff) do { _Pragma("unroll") for (int _i = 0; _i < 2; ++_i) \
;         __builtin_amdgcn_global_load_lds((const unsigned*)((const char*)(gbase) + (voff)[_i]), (PG8_LAS unsigned*)(lds + (bufoff) + ldsw + _i * 8192), 16, 0, 0); } while (0)
; #define PG8_WAIT_V(n) asm volatile("s_waitcnt vmcnt(" #n ")" ::: "memory")
; #define PG8_BAR __builtin_amdgcn_s_barrier()
; template <class Epi, class Sched, bool ALIGN_EPI = false, bool SP2 = false>
; __device__ __forceinline__ void gemm_phase(PG8_LAS unsigned char* lds, const Gemm g, const Sched& S, const Epi& E, int wv) {
;     ...
;     const int tid = tid_, wid = __builtin_amdgcn_readfirstlane(tid >> 6), lane = tid & 63, wr = wid >> 2, wc = wid & 3, fr = lane & 15, fq = lane >> 4;
;     const int K = g.K, nt = K / BK;
;     unsigned voffA[2], voffB[2];
; #pragma unroll
;     for (int i = 0; i < 2; ++i) { int R, C; stage_rc(tid * 16 + i * 8192, R, C); const int Rb = Epi::PERM ? ((R & ~31) + perm32(R & 31)) : R;
;         voffA[i] = (unsigned)(R * K + C) * 2u; voffB[i] = (unsigned)(Rb * K + C) * 2u; }
;     const size_t kstep = (size_t)(BK * 2);
;     const size_t hstep = (size_t)HALF * K * 2;
;     const size_t tstep = 2 * hstep;
;     const unsigned ldsw = (unsigned)wid * 1024u;
;     const int aoff = lds_byte(wr * 64 + fr, fq * 8), boff = lds_byte(wc * 32 + fr, fq * 8);
;     ...
;     Unit cur, nxt; int ui = 0;
;     if (!S.next(0, cur)) return;
;     f32x4 acc[2][2][4][2];
; #pragma unroll
;     for (int a = 0; a < 2; ++a)
; #pragma unroll
;         for (int b = 0; b < 2; ++b)
; #pragma unroll
;             for (int m = 0; m < 4; ++m)
; #pragma unroll
;                 for (int n = 0; n < 2; ++n) acc[a][b][m][n] = (f32x4){0.f, 0.f, 0.f, 0.f};
;     bf16x8 At[4][2], B0[2][2], B1[2][2];
;     const char* cA = (const char*)g.A + (size_t)cur.pm * tstep; const char* cB = (const char*)g.Bt + (size_t)cur.pn * tstep;
;     S.a_ready(cur);
;     if constexpr (SP2) {
;         PG8_STAGE(PG8_SB(0, 0), cB, voffB); PG8_STAGE(PG8_SB(0, 1), cB + hstep, voffB); PG8_STAGE(PG8_SA(0, 0), cA, voffA); PG8_STAGE(PG8_SA(0, 1), cA + hstep, voffA);
;         if (wr == 1) PG8_BAR;
;         PG8_WAIT_V(2); PG8_BAR;
;         PG8_STAGE(PG8_SB(1, 0), cB + kstep, voffB); PG8_STAGE(PG8_SA(1, 0), cA + kstep, voffA); PG8_STAGE(PG8_SB(1, 1), cB + hstep + kstep, voffB);
.LBB0_1179:
	s_or_b64 exec, exec, s[4:5]
	v_readlane_b32 s8, v250, 0
	s_mov_b64 s[4:5], 0
	s_waitcnt lgkmcnt(0)
	v_mov_b32_e32 v0, v161
	s_barrier
	v_readlane_b32 s10, v250, 3
	v_add_u32_e32 v0, 0, v0
	v_add_u32_e32 v0, 0x201c0, v0
	s_nop 0
	v_mov_b32_e32 v14, v183
	v_readlane_b32 s11, v250, 4
	s_andn2_b64 vcc, exec, s[10:11]
	s_waitcnt lgkmcnt(0)
	v_readlane_b32 s6, v251, 48
	v_mov_b32_e32 v0, v161
	v_readlane_b32 s7, v251, 49
	v_add_u32_e32 v0, 0, v0
	v_add_u32_e32 v0, 0x201c8, v0
	ds_read_b64 v[0:1], v0
	s_nop 0
	v_readfirstlane_b32 s10, v14
	s_cbranch_vccnz .LBB0_1195
	s_waitcnt lgkmcnt(0)
	v_lshlrev_b32_e32 v0, 4, v14
	v_add_u32_e32 v1, 0x2000, v0
	v_ashrrev_i32_e32 v2, 31, v1
	v_lshrrev_b32_e32 v2, 22, v2
	v_add_u32_e32 v2, v1, v2
	v_ashrrev_i32_e32 v8, 10, v2
	v_mul_i32_i24_e32 v2, 0x400, v8
	v_sub_u32_e32 v1, v1, v2
	v_lshrrev_b32_e32 v2, 4, v1
	v_bitop3_b32 v1, v2, v1, 32 bitop3:0x6c
	s_add_u32 s6, s6, s4
	v_ashrrev_i32_e32 v2, 31, v1
	s_addc_u32 s7, s7, s5
	v_lshrrev_b32_e32 v2, 26, v2
	s_add_u32 s14, s6, 0x5200000
	v_add_u32_e32 v2, v1, v2
	v_lshlrev_b32_e32 v3, 3, v8
	s_addc_u32 s15, s7, 0
	s_mul_i32 s5, s8, 0x2900000
	v_ashrrev_i32_e32 v9, 6, v2
	v_and_b32_e32 v3, -16, v3
	s_mul_hi_i32 s4, s8, 0x2900000
	s_add_u32 s9, s6, s5
	v_add_u32_e32 v3, v9, v3
	s_addc_u32 s13, s7, s4
	v_and_b32_e32 v4, 3, v9
	s_mov_b32 s4, 0x1fffe0
	v_lshrrev_b32_e32 v5, 2, v3
	v_lshlrev_b32_e32 v6, 1, v3
	v_and_b32_e32 v2, 0xc0, v2
	v_and_or_b32 v4, v3, s4, v4
	v_and_b32_e32 v5, 4, v5
	v_and_b32_e32 v6, 24, v6
	v_sub_u32_e32 v1, v1, v2
	v_or3_b32 v4, v4, v5, v6
	v_lshlrev_b32_e32 v5, 5, v8
	v_ashrrev_i16_sdwa v1, v193, sext(v1) dst_sel:DWORD dst_unused:UNUSED_PAD src0_sel:DWORD src1_sel:BYTE_0
	v_and_b32_e32 v5, 32, v5
	v_bfe_i32 v10, v1, 0, 16
	v_add_lshl_u32 v1, v5, v10, 1
	v_lshl_add_u32 v128, v4, 11, v1
	v_lshl_add_u32 v130, v3, 11, v1
	v_bfe_i32 v1, v14, 27, 1
	v_lshrrev_b32_e32 v1, 22, v1
	v_add_u32_e32 v1, v0, v1
	v_and_b32_e32 v1, 0xfffffc00, v1
	v_sub_u32_e32 v0, v0, v1
	v_lshrrev_b32_e32 v1, 4, v0
	v_ashrrev_i32_e32 v2, 31, v14
	v_bitop3_b32 v0, v1, v0, 32 bitop3:0x6c
	v_lshrrev_b32_e32 v2, 26, v2
	v_ashrrev_i32_e32 v1, 31, v0
	v_add_u32_e32 v2, v14, v2
	v_lshrrev_b32_e32 v1, 26, v1
	v_ashrrev_i32_e32 v12, 6, v2
	v_add_u32_e32 v1, v0, v1
	v_lshlrev_b32_e32 v2, 3, v12
	v_ashrrev_i32_e32 v11, 6, v1
	v_and_b32_e32 v2, -16, v2
	v_add_u32_e32 v2, v11, v2
	s_add_u32 s16, s9, 0x1080000
	v_and_b32_e32 v3, 3, v11
	v_lshrrev_b32_e32 v4, 2, v2
	v_lshlrev_b32_e32 v5, 1, v2
	v_and_b32_e32 v1, 0xc0, v1
	s_addc_u32 s29, s13, 0
	s_ashr_i32 s11, s10, 6
	v_and_or_b32 v3, v2, s4, v3
	v_and_b32_e32 v4, 4, v4
	v_and_b32_e32 v5, 24, v5
	v_sub_u32_e32 v0, v0, v1
	s_ashr_i32 s12, s10, 8
	s_lshl_b32 s30, s11, 10
	v_or3_b32 v3, v3, v4, v5
	v_lshlrev_b32_e32 v4, 5, v12
	v_ashrrev_i16_sdwa v0, v193, sext(v0) dst_sel:DWORD dst_unused:UNUSED_PAD src0_sel:DWORD src1_sel:BYTE_0
	v_readlane_b32 s4, v250, 8
	v_and_b32_e32 v4, 32, v4
	v_bfe_i32 v13, v0, 0, 16
	v_readlane_b32 s5, v250, 9
	s_add_u32 s48, s16, s4
	v_add_lshl_u32 v0, v4, v13, 1
	s_addc_u32 s49, s29, s5
	s_add_i32 s31, s30, 0
	v_lshl_add_u32 v160, v3, 11, v0
	s_add_i32 m0, s31, 0x10000
	v_lshl_add_u32 v132, v2, 11, v0
	global_load_lds_dwordx4 v160, s[48:49]
	s_add_i32 m0, s31, 0x12000
	s_add_u32 s4, s48, 0x40000
	global_load_lds_dwordx4 v128, s[48:49]
	s_addc_u32 s5, s49, 0
	s_add_i32 m0, s31, 0x14000
	v_mov_b32_e32 v129, v161
	global_load_lds_dwordx4 v160, s[4:5]
	s_add_i32 m0, s31, 0x16000
	v_mov_b32_e32 v133, v161
	global_load_lds_dwordx4 v128, s[4:5]
	v_readlane_b32 s4, v250, 25
	v_readlane_b32 s5, v250, 26
	s_add_u32 s44, s14, s4
	s_addc_u32 s45, s15, s5
	s_add_i32 s52, s31, 0x2000
	s_mov_b32 m0, s31
	s_add_u32 s4, s44, 0x40000
	global_load_lds_dwordx4 v132, s[44:45]
	s_mov_b32 m0, s52
	s_addc_u32 s5, s45, 0
	s_add_i32 s53, s31, 0x4000
	global_load_lds_dwordx4 v130, s[44:45]
	s_mov_b32 m0, s53
	s_add_i32 s54, s31, 0x6000
	global_load_lds_dwordx4 v132, s[4:5]
	s_mov_b32 m0, s54
	v_mov_b32_e32 v131, v161
	global_load_lds_dwordx4 v130, s[4:5]
	s_cmp_eq_u32 s12, 1
	v_lshl_add_u64 v[6:7], s[48:49], 0, v[160:161]
	v_lshl_add_u64 v[4:5], s[48:49], 0, v[128:129]
	v_lshl_add_u64 v[0:1], s[44:45], 0, v[132:133]
	s_cselect_b64 s[4:5], -1, 0
	s_cmp_lg_u32 s12, 1
	v_lshl_add_u64 v[2:3], s[44:45], 0, v[130:131]
	s_cbranch_scc1 .LBB0_1182
	s_barrier

; #define PIN(i) ((const float*)ldq_(L, (i)))
; #define PREP_CONV(bit, SRC, Kd, Nd, DST, GK, MODE) if (mask & (bit)) { for (int it = gw; it < ((Kd) / 64) * ((Nd) / 64); it += NGW) transpose_item((SRC), (Kd), (Nd), (bf16_t*)(wl + (DST)), (GK), (MODE), scr, it, lane); }
; __device__ __forceinline__ void transpose_item(const float* W, int K, int N, bf16_t* WT, const float* gk, int mode, LAS float* scr_, int item, int lane) {
;     ...
;     const int nblk = N / 64, kb = item / nblk, nb = item % nblk, k0 = 64 * kb, n0 = 64 * nb;
;     const int sc = (mode == 1) ? (((n0 >> 7) & 1) * DFF + (n0 >> 8) * 128 + (n0 & 127)) : n0;
;     const float* src = W + (size_t)k0 * N + sc + lane;
;     float va[32], vb[32];
; #pragma unroll
;     for (int kp = 0; kp < 32; ++kp) { va[kp] = src[(size_t)(2 * kp) * N]; vb[kp] = src[(size_t)(2 * kp + 1) * N]; }
; #pragma unroll
;     for (int kp = 0; kp < 32; ++kp) {
;         float a = va[kp], b = vb[kp];
;         if (gk) { a *= gk[k0 + 2 * kp]; b *= gk[k0 + 2 * kp + 1]; }
; __device__ __forceinline__ void prep(const Params& p, LAS unsigned char* L, int wv, int vb, int nvb, int l, int mask) {
;     ...
;     PREP_CONV(PM_FFA_IN, PIN(I_WFFA_IN) + (size_t)l * DM * NFF2, DM, NFF2, WL_FFA_IN, PIN(I_NFFA) + l * DM, 1)
.LBB0_1199:
	v_mov_b32_e32 v2, v161
	s_mul_hi_i32 s8, s14, 0x2e8ba2e9
	v_add_u32_e32 v2, 0, v2
	v_add_u32_e32 v2, 0x20140, v2
	s_nop 0
	s_waitcnt lgkmcnt(0)
	v_readlane_b32 s5, v251, 16
	v_mov_b32_e32 v2, v161
	v_readlane_b32 s4, v251, 17
	v_add_u32_e32 v2, 0, v2
	v_add_u32_e32 v2, 0x20138, v2
	s_nop 0
	s_add_u32 s11, s5, s16
	s_addc_u32 s12, s4, s15
	s_waitcnt lgkmcnt(0)
	v_readlane_b32 s4, v251, 14
	v_readlane_b32 s5, v251, 15
	s_add_u32 s25, s4, s6
	s_addc_u32 s29, s5, s7
	s_lshr_b32 s9, s8, 31
	s_ashr_i32 s8, s8, 4
	s_add_i32 s13, s8, s9
	s_mul_i32 s9, s13, 0xffffea00
	s_mul_i32 s10, s13, 0xfffff500
	s_add_i32 s24, s18, s9
	s_bfe_i32 s9, s14, 0x10001
	s_add_i32 s10, s19, s10
	s_and_b32 s9, s9, 0xb00
	s_and_b32 s10, s10, 0xffffff80
	s_lshl_b32 s8, s13, 6
	s_add_i32 s9, s9, s10
	s_and_b32 s10, s24, 64
	s_or_b32 s10, s9, s10
	s_ashr_i32 s9, s8, 31
	s_mul_i32 s13, s13, 0x160000
	s_mul_hi_i32 s21, s8, 0x5800
	s_add_u32 s13, s11, s13
	s_addc_u32 s12, s12, s21
	s_ashr_i32 s11, s10, 31
	s_lshl_b64 s[10:11], s[10:11], 2
	s_add_u32 s10, s13, s10
	s_addc_u32 s11, s12, s11
	s_waitcnt vmcnt(9)
	v_lshl_add_u64 v[66:67], s[10:11], 0, v[160:161]
	global_load_dword v62, v160, s[10:11]
	s_movk_i32 s10, 0x5000
	v_add_co_u32_e32 v2, vcc, s10, v66
	s_mov_b32 s10, 0xb000
	s_nop 0
	v_addc_co_u32_e32 v3, vcc, 0, v67, vcc
	global_load_dword v63, v[2:3], off offset:2048
	v_add_co_u32_e32 v2, vcc, s10, v66
	s_mov_b32 s10, 0x1b000
	s_nop 0
	v_addc_co_u32_e32 v3, vcc, 0, v67, vcc
	global_load_dword v64, v[2:3], off
	v_add_co_u32_e32 v2, vcc, s37, v66
	s_cmp_lg_u64 s[4:5], 0
	s_nop 0
	v_addc_co_u32_e32 v3, vcc, 0, v67, vcc
	global_load_dword v65, v[2:3], off offset:2048
	v_add_co_u32_e32 v2, vcc, s47, v66
	s_mov_b64 s[12:13], -1
	s_nop 0
	v_addc_co_u32_e32 v3, vcc, 0, v67, vcc
	global_load_dword v54, v[2:3], off
	v_add_co_u32_e32 v2, vcc, s10, v66
	s_mov_b32 s10, 0x21000
	s_nop 0
	v_addc_co_u32_e32 v3, vcc, 0, v67, vcc
	global_load_dword v55, v[2:3], off offset:2048
	v_add_co_u32_e32 v2, vcc, s10, v66
	s_mov_b32 s10, 0x31000
	s_nop 0
	v_addc_co_u32_e32 v3, vcc, 0, v67, vcc
	global_load_dword v60, v[2:3], off
	v_add_co_u32_e32 v2, vcc, s73, v66
	s_nop 1
	v_addc_co_u32_e32 v3, vcc, 0, v67, vcc
	global_load_dword v61, v[2:3], off offset:2048
	v_add_co_u32_e32 v2, vcc, s82, v66
	s_nop 1
	v_addc_co_u32_e32 v3, vcc, 0, v67, vcc
	global_load_dword v56, v[2:3], off
	v_add_co_u32_e32 v2, vcc, s10, v66
	s_mov_b32 s10, 0x37000
	s_nop 0
	v_addc_co_u32_e32 v3, vcc, 0, v67, vcc
	global_load_dword v57, v[2:3], off offset:2048
	v_add_co_u32_e32 v2, vcc, s10, v66
	s_mov_b32 s10, 0x47000
	s_nop 0
	v_addc_co_u32_e32 v3, vcc, 0, v67, vcc
	global_load_dword v58, v[2:3], off
	v_add_co_u32_e32 v2, vcc, s90, v66
	s_nop 1
	v_addc_co_u32_e32 v3, vcc, 0, v67, vcc
	global_load_dword v59, v[2:3], off offset:2048
	v_add_co_u32_e32 v2, vcc, s93, v66
	s_nop 1
	v_addc_co_u32_e32 v3, vcc, 0, v67, vcc
	global_load_dword v44, v[2:3], off
	v_add_co_u32_e32 v2, vcc, s10, v66
	s_mov_b32 s10, 0x4d000
	s_nop 0
	v_addc_co_u32_e32 v3, vcc, 0, v67, vcc
	global_load_dword v45, v[2:3], off offset:2048
	v_add_co_u32_e32 v2, vcc, s10, v66
	s_mov_b32 s10, 0x52000
	s_nop 0
	v_addc_co_u32_e32 v3, vcc, 0, v67, vcc
	global_load_dword v50, v[2:3], off
	v_add_co_u32_e32 v2, vcc, s10, v66
	s_mov_b32 s10, 0x58000
	s_nop 0
	v_addc_co_u32_e32 v3, vcc, 0, v67, vcc
	global_load_dword v51, v[2:3], off offset:2048
	v_add_co_u32_e32 v2, vcc, s10, v66
	s_mov_b32 s10, 0x5d000
	s_nop 0
	v_addc_co_u32_e32 v3, vcc, 0, v67, vcc
	global_load_dword v48, v[2:3], off
	v_add_co_u32_e32 v2, vcc, s10, v66
	s_mov_b32 s10, 0x63000
	s_nop 0
	v_addc_co_u32_e32 v3, vcc, 0, v67, vcc
	global_load_dword v49, v[2:3], off offset:2048
	v_add_co_u32_e32 v2, vcc, s10, v66
	s_mov_b32 s10, 0x68000
	s_nop 0
	v_addc_co_u32_e32 v3, vcc, 0, v67, vcc
	global_load_dword v52, v[2:3], off
	v_add_co_u32_e32 v2, vcc, s10, v66
	s_mov_b32 s10, 0x6e000
	s_nop 0
	v_addc_co_u32_e32 v3, vcc, 0, v67, vcc
	global_load_dword v53, v[2:3], off offset:2048
	v_add_co_u32_e32 v2, vcc, s10, v66
	s_mov_b32 s10, 0x73000
	s_nop 0
	v_addc_co_u32_e32 v3, vcc, 0, v67, vcc
	global_load_dword v38, v[2:3], off
	v_add_co_u32_e32 v2, vcc, s10, v66
	s_mov_b32 s10, 0x79000
	s_nop 0
	v_addc_co_u32_e32 v3, vcc, 0, v67, vcc
	global_load_dword v39, v[2:3], off offset:2048
	v_add_co_u32_e32 v2, vcc, s10, v66
	s_mov_b32 s10, 0x7e000
	s_nop 0
	v_addc_co_u32_e32 v3, vcc, 0, v67, vcc
	global_load_dword v42, v[2:3], off
	v_add_co_u32_e32 v2, vcc, s10, v66
	s_mov_b32 s10, 0x84000
	s_nop 0
	v_addc_co_u32_e32 v3, vcc, 0, v67, vcc
	global_load_dword v43, v[2:3], off offset:2048
	v_add_co_u32_e32 v2, vcc, s10, v66
	s_mov_b32 s10, 0x89000
	s_nop 0
	v_addc_co_u32_e32 v3, vcc, 0, v67, vcc
	global_load_dword v40, v[2:3], off
	v_add_co_u32_e32 v2, vcc, s10, v66
	s_mov_b32 s10, 0x8f000
	s_nop 0
	v_addc_co_u32_e32 v3, vcc, 0, v67, vcc
	global_load_dword v41, v[2:3], off offset:2048
	v_add_co_u32_e32 v2, vcc, s10, v66
	s_mov_b32 s10, 0x94000
	s_nop 0
	v_addc_co_u32_e32 v3, vcc, 0, v67, vcc
	global_load_dword v46, v[2:3], off
	v_add_co_u32_e32 v2, vcc, s10, v66
	s_mov_b32 s10, 0x9a000
	s_nop 0
	v_addc_co_u32_e32 v3, vcc, 0, v67, vcc
	global_load_dword v47, v[2:3], off offset:2048
	v_add_co_u32_e32 v2, vcc, s10, v66
	s_mov_b32 s10, 0x9f000
	s_nop 0
	v_addc_co_u32_e32 v3, vcc, 0, v67, vcc
	global_load_dword v30, v[2:3], off
	v_add_co_u32_e32 v2, vcc, s10, v66
	s_mov_b32 s10, 0xa5000
	s_nop 0
; __device__ __forceinline__ void transpose_item(const float* W, int K, int N, bf16_t* WT, const float* gk, int mode, LAS float* scr_, int item, int lane) {
;     ...
;     float va[32], vb[32];
; #pragma unroll
;     for (int kp = 0; kp < 32; ++kp) { va[kp] = src[(size_t)(2 * kp) * N]; vb[kp] = src[(size_t)(2 * kp + 1) * N]; }
; #pragma unroll
;     for (int kp = 0; kp < 32; ++kp) {
;         float a = va[kp], b = vb[kp];
;         if (gk) { a *= gk[k0 + 2 * kp]; b *= gk[k0 + 2 * kp + 1]; }
	v_addc_co_u32_e32 v3, vcc, 0, v67, vcc
	global_load_dword v31, v[2:3], off offset:2048
	v_add_co_u32_e32 v2, vcc, s10, v66
	s_mov_b32 s10, 0xaa000
	s_nop 0
	v_addc_co_u32_e32 v3, vcc, 0, v67, vcc
	global_load_dword v36, v[2:3], off
	v_add_co_u32_e32 v2, vcc, s10, v66
	s_mov_b32 s10, 0xb5000
	s_nop 0
	v_addc_co_u32_e32 v3, vcc, 0, v67, vcc
	global_load_dword v37, v[2:3], off offset:2048
	v_add_co_u32_e32 v2, vcc, s95, v66
	s_nop 1
	v_addc_co_u32_e32 v3, vcc, 0, v67, vcc
	global_load_dword v32, v[2:3], off
	v_add_co_u32_e32 v2, vcc, s10, v66
	s_mov_b32 s10, 0xbb000
	s_nop 0
	v_addc_co_u32_e32 v3, vcc, 0, v67, vcc
	global_load_dword v33, v[2:3], off offset:2048
	v_add_co_u32_e32 v2, vcc, s10, v66
	s_mov_b32 s10, 0xc0000
	s_nop 0
	v_addc_co_u32_e32 v3, vcc, 0, v67, vcc
	global_load_dword v34, v[2:3], off
	v_add_co_u32_e32 v2, vcc, s10, v66
	s_mov_b32 s10, 0xcb000
	s_nop 0
	v_addc_co_u32_e32 v3, vcc, 0, v67, vcc
	global_load_dword v35, v[2:3], off offset:2048
	v_add_co_u32_e32 v2, vcc, s89, v66
	s_nop 1
	v_addc_co_u32_e32 v3, vcc, 0, v67, vcc
	global_load_dword v20, v[2:3], off
	v_add_co_u32_e32 v2, vcc, s10, v66
	s_mov_b32 s10, 0xd1000
	s_nop 0
	v_addc_co_u32_e32 v3, vcc, 0, v67, vcc
	global_load_dword v21, v[2:3], off offset:2048
	v_add_co_u32_e32 v2, vcc, s10, v66
	s_mov_b32 s10, 0xd6000
	s_nop 0
	v_addc_co_u32_e32 v3, vcc, 0, v67, vcc
	global_load_dword v26, v[2:3], off
	v_add_co_u32_e32 v2, vcc, s10, v66
	s_mov_b32 s10, 0xdc000
	s_nop 0
	v_addc_co_u32_e32 v3, vcc, 0, v67, vcc
	global_load_dword v27, v[2:3], off offset:2048
	v_add_co_u32_e32 v2, vcc, s10, v66
	s_mov_b32 s10, 0xe1000
	s_nop 0
	v_addc_co_u32_e32 v3, vcc, 0, v67, vcc
	global_load_dword v24, v[2:3], off
	v_add_co_u32_e32 v2, vcc, s10, v66
	s_mov_b32 s10, 0xe7000
	s_nop 0
	v_addc_co_u32_e32 v3, vcc, 0, v67, vcc
	global_load_dword v25, v[2:3], off offset:2048
	v_add_co_u32_e32 v2, vcc, s10, v66
	s_mov_b32 s10, 0xec000
	s_nop 0
	v_addc_co_u32_e32 v3, vcc, 0, v67, vcc
	global_load_dword v28, v[2:3], off
	v_add_co_u32_e32 v2, vcc, s10, v66
	s_mov_b32 s10, 0xf2000
	s_nop 0
	v_addc_co_u32_e32 v3, vcc, 0, v67, vcc
	global_load_dword v29, v[2:3], off offset:2048
	v_add_co_u32_e32 v2, vcc, s10, v66
	s_mov_b32 s10, 0xf7000
	s_nop 0
	v_addc_co_u32_e32 v3, vcc, 0, v67, vcc
	global_load_dword v12, v[2:3], off
	v_add_co_u32_e32 v2, vcc, s10, v66
	s_mov_b32 s10, 0xfd000
	s_nop 0
	v_addc_co_u32_e32 v3, vcc, 0, v67, vcc
	global_load_dword v13, v[2:3], off offset:2048
	v_add_co_u32_e32 v2, vcc, s10, v66
	s_mov_b32 s10, 0x102000
	s_nop 0
	v_addc_co_u32_e32 v3, vcc, 0, v67, vcc
	global_load_dword v18, v[2:3], off
	v_add_co_u32_e32 v2, vcc, s10, v66
	s_mov_b32 s10, 0x108000
	s_nop 0
	v_addc_co_u32_e32 v3, vcc, 0, v67, vcc
	global_load_dword v19, v[2:3], off offset:2048
	v_add_co_u32_e32 v2, vcc, s10, v66
	s_mov_b32 s10, 0x10d000
	s_nop 0
	v_addc_co_u32_e32 v3, vcc, 0, v67, vcc
	global_load_dword v16, v[2:3], off
	v_add_co_u32_e32 v2, vcc, s10, v66
	s_mov_b32 s10, 0x113000
	s_nop 0
	v_addc_co_u32_e32 v3, vcc, 0, v67, vcc
	global_load_dword v17, v[2:3], off offset:2048
	v_add_co_u32_e32 v2, vcc, s10, v66
	s_mov_b32 s10, 0x118000
	s_nop 0
	v_addc_co_u32_e32 v3, vcc, 0, v67, vcc
	global_load_dword v22, v[2:3], off
	v_add_co_u32_e32 v2, vcc, s10, v66
	s_mov_b32 s10, 0x11e000
	s_nop 0
	v_addc_co_u32_e32 v3, vcc, 0, v67, vcc
	global_load_dword v23, v[2:3], off offset:2048
	v_add_co_u32_e32 v2, vcc, s10, v66
	s_mov_b32 s10, 0x123000
	s_nop 0
	v_addc_co_u32_e32 v3, vcc, 0, v67, vcc
	global_load_dword v4, v[2:3], off
	v_add_co_u32_e32 v2, vcc, s10, v66
	s_mov_b32 s10, 0x129000
	s_nop 0
	v_addc_co_u32_e32 v3, vcc, 0, v67, vcc
	global_load_dword v5, v[2:3], off offset:2048
	v_add_co_u32_e32 v2, vcc, s10, v66
	s_mov_b32 s10, 0x12e000
	s_nop 0
	v_addc_co_u32_e32 v3, vcc, 0, v67, vcc
	global_load_dword v10, v[2:3], off
	v_add_co_u32_e32 v2, vcc, s10, v66
	s_mov_b32 s10, 0x134000
	s_nop 0
	v_addc_co_u32_e32 v3, vcc, 0, v67, vcc
	global_load_dword v11, v[2:3], off offset:2048
	v_add_co_u32_e32 v2, vcc, s10, v66
	s_mov_b32 s10, 0x139000
	s_nop 0
	v_addc_co_u32_e32 v3, vcc, 0, v67, vcc
	global_load_dword v6, v[2:3], off
	v_add_co_u32_e32 v2, vcc, s10, v66
	s_mov_b32 s10, 0x13f000
	s_nop 0
	v_addc_co_u32_e32 v3, vcc, 0, v67, vcc
	global_load_dword v7, v[2:3], off offset:2048
	v_add_co_u32_e32 v2, vcc, s10, v66
	s_mov_b32 s10, 0x144000
	s_nop 0
	v_addc_co_u32_e32 v3, vcc, 0, v67, vcc
	global_load_dword v14, v[2:3], off
	v_add_co_u32_e32 v2, vcc, s10, v66
	s_mov_b32 s10, 0x14a000
	s_nop 0
	v_addc_co_u32_e32 v3, vcc, 0, v67, vcc
	global_load_dword v15, v[2:3], off offset:2048
	v_add_co_u32_e32 v2, vcc, s10, v66
	s_mov_b32 s10, 0x14f000
	s_nop 0
	v_addc_co_u32_e32 v3, vcc, 0, v67, vcc
	v_add_co_u32_e32 v8, vcc, s10, v66
	global_load_dword v2, v[2:3], off
	s_nop 0
	v_addc_co_u32_e32 v9, vcc, 0, v67, vcc
	global_load_dword v3, v[8:9], off offset:2048
	v_add_co_u32_e32 v8, vcc, 0x155000, v66
	s_cselect_b64 s[10:11], -1, 0
	s_nop 0
	v_addc_co_u32_e32 v9, vcc, 0, v67, vcc
	v_add_co_u32_e32 v66, vcc, 0x15a000, v66
	global_load_dword v8, v[8:9], off
	s_nop 0
	v_addc_co_u32_e32 v67, vcc, 0, v67, vcc
	global_load_dword v9, v[66:67], off offset:2048
	s_cmp_eq_u64 s[4:5], 0
	s_cbranch_scc1 .LBB0_1201
	s_lshl_b64 s[4:5], s[8:9], 2
	s_add_u32 s4, s25, s4
	s_addc_u32 s5, s29, s5
	global_load_dwordx4 v[66:69], v161, s[4:5]
	s_mov_b64 s[12:13], 0
	s_waitcnt vmcnt(0)
	v_pk_mul_f32 v[66:67], v[62:63], v[66:67]
	v_pk_mul_f32 v[68:69], v[64:65], v[68:69]

; #define PIN(i) ((const float*)ldq_(L, (i)))
; __device__ __forceinline__ void unpack8(u32x4 w, float* v) { v[0] = bflo(w.x); v[1] = bfhi(w.x); v[2] = bflo(w.y); v[3] = bfhi(w.y); v[4] = bflo(w.z); v[5] = bfhi(w.z); v[6] = bflo(w.w); v[7] = bfhi(w.w); }
; __device__ __forceinline__ void mixer_unit(const Params& p, int layer, int cu, LAS unsigned char* L, int wv) {
;     ...
;             if (orow >= 0) {
;                 float* dst = POUT + (is_s ? O_KS : O_KP) + ((((size_t)layer * NB + b) * 128 + orow) * 2 + kv2) * 64;
;                 *(f32x4*)dst = (f32x4){o1[0], o1[1], o1[2], o1[3]}; *(f32x4*)(dst + 4) = (f32x4){o1[4], o1[5], o1[6], o1[7]};
;                 *(f32x4*)(dst + 8) = (f32x4){o2[0], o2[1], o2[2], o2[3]}; *(f32x4*)(dst + 12) = (f32x4){o2[4], o2[5], o2[6], o2[7]};
;             }
;         }
;     }
;     bf16x8 qf[4][2];
;     {
;         float gq0[8], gq1[8];
; #pragma unroll
;         for (int i = 0; i < 8; ++i) { gq0[i] = PIN(I_QN)[layer * 64 + 8 * quad + i]; gq1[i] = PIN(I_QN)[layer * 64 + 32 + 8 * quad + i]; }
;         constexpr float QS = 0.125f * LOG2E;
; #pragma unroll
;         for (int qb = 0; qb < 4; ++qb) {
;             float v0[8], v1[8]; unpack8(qraw[qb][0], v0); unpack8(qraw[qb][1], v1);
;             float ss = 0.f;
; #pragma unroll
;             for (int i = 0; i < 8; ++i) ss += v0[i] * v0[i] + v1[i] * v1[i];
;             ss += __shfl_xor(ss, 16); ss += __shfl_xor(ss, 32);
;             const float rs = __builtin_amdgcn_rsqf(ss * (1.0f / 64.0f) + EPS);
;             float pv[8];
; #pragma unroll
;             for (int i = 0; i < 8; ++i) { v0[i] = v0[i] * rs * gq0[i]; v1[i] = v1[i] * rs * gq1[i] * QS; pv[i] = __shfl_xor(v0[i], 16); }
.LBB0_1415:
	v_mov_b32_e32 v112, v161
	v_lshlrev_b32_e32 v160, 1, v113
	v_add_u32_e32 v112, 0, v112
	v_add_u32_e32 v112, 0x201c8, v112
	s_nop 0
	s_lshl_b32 s12, s12, 2
	v_lshl_add_u64 v[112:113], s[48:49], 0, v[160:161]
	s_waitcnt lgkmcnt(0)
	v_readlane_b32 s16, v251, 50
	v_cndmask_b32_e64 v114, 0, 1, s[8:9]
	v_readlane_b32 s13, v251, 51
	s_add_u32 s12, s16, s12
	v_or_b32_e32 v112, v112, v114
	s_addc_u32 s13, s13, 0
	v_lshlrev_b64 v[112:113], 8, v[112:113]
	v_lshl_add_u64 v[112:113], s[12:13], 0, v[112:113]
	global_store_dwordx4 v[112:113], v[100:103], off
	global_store_dwordx4 v[112:113], v[108:111], off offset:16
	global_store_dwordx4 v[112:113], v[96:99], off offset:32
	global_store_dwordx4 v[112:113], v[104:107], off offset:48
.LBB0_1416:
	s_or_b64 exec, exec, s[10:11]
	v_mov_b32_e32 v96, v161
	v_bfe_u32 v122, v178, 4, 2
	v_add_u32_e32 v96, s23, v96
	s_nop 0
	v_lshlrev_b32_e32 v180, 3, v122
	v_or_b32_e32 v160, s63, v180
	v_lshlrev_b64 v[100:101], 2, v[160:161]
	v_mov_b32_e32 v102, v161
	s_waitcnt lgkmcnt(0)
	v_readlane_b32 s9, v251, 25
	v_readlane_b32 s8, v251, 24
	v_mov_b32_e32 v104, v161
	v_mov_b32_e32 v106, v161
	v_lshl_add_u64 v[96:97], s[8:9], 0, v[100:101]
	global_load_dword v96, v[96:97], off
	v_mov_b32_e32 v97, v161
	s_waitcnt vmcnt(8)
	v_and_b32_e32 v108, 0xffff0000, v90
	v_add_u32_e32 v97, s23, v97
	s_nop 0
	v_mov_b32_e32 v97, v161
	v_lshlrev_b32_e32 v109, 16, v90
	v_and_b32_e32 v110, 0xffff0000, v91
	v_lshlrev_b32_e32 v111, 16, v91
	s_waitcnt lgkmcnt(0)
	v_readlane_b32 s9, v251, 25
	v_readlane_b32 s8, v251, 24
	s_waitcnt vmcnt(7)
	v_and_b32_e32 v90, 0xffff0000, v95
	v_lshlrev_b32_e32 v91, 16, v95
	v_lshl_add_u64 v[98:99], s[8:9], 0, v[100:101]
	global_load_dword v132, v[98:99], off offset:128
	v_lshlrev_b32_e32 v116, 16, v88
	v_add_u32_e32 v97, s23, v97
	s_nop 0
	v_and_b32_e32 v117, 0xffff0000, v88
	v_lshlrev_b32_e32 v118, 16, v89
	v_and_b32_e32 v119, 0xffff0000, v89
	v_cmp_gt_u32_e32 vcc, 16, v181
	s_waitcnt lgkmcnt(0)
	v_readlane_b32 s9, v251, 25
	v_readlane_b32 s8, v251, 24
	s_nop 1
	v_lshl_add_u64 v[98:99], s[8:9], 0, v[100:101]
	global_load_dword v97, v[98:99], off offset:4
	s_nop 0
	v_add_u32_e32 v98, s23, v102
	s_nop 0
	v_mov_b32_e32 v102, v161
	s_waitcnt lgkmcnt(0)
	v_readlane_b32 s9, v251, 25
	v_readlane_b32 s8, v251, 24
	s_nop 1
	v_lshl_add_u64 v[98:99], s[8:9], 0, v[100:101]
	global_load_dword v133, v[98:99], off offset:132
	s_nop 0
	v_add_u32_e32 v98, s23, v102
	s_nop 0
	v_mov_b32_e32 v102, v161
	s_waitcnt lgkmcnt(0)
	v_readlane_b32 s9, v251, 25
	v_readlane_b32 s8, v251, 24
	s_nop 1
	v_lshl_add_u64 v[98:99], s[8:9], 0, v[100:101]
	global_load_dword v98, v[98:99], off offset:8
	s_nop 0
	v_add_u32_e32 v99, s23, v102
	s_nop 0
	v_mov_b32_e32 v99, v161
	s_waitcnt lgkmcnt(0)
	v_readlane_b32 s9, v251, 25
	v_readlane_b32 s8, v251, 24
	s_nop 1
	v_lshl_add_u64 v[102:103], s[8:9], 0, v[100:101]
	global_load_dword v134, v[102:103], off offset:136
	s_nop 0
	v_add_u32_e32 v99, s23, v99
	s_nop 0
	s_waitcnt lgkmcnt(0)
	v_readlane_b32 s9, v251, 25
	v_readlane_b32 s8, v251, 24
	s_nop 1
	v_lshl_add_u64 v[102:103], s[8:9], 0, v[100:101]
	global_load_dword v99, v[102:103], off offset:12
	s_nop 0
	v_add_u32_e32 v102, s23, v104
	s_nop 0
	v_mov_b32_e32 v104, v161
	s_waitcnt lgkmcnt(0)
	v_readlane_b32 s9, v251, 25
	v_readlane_b32 s8, v251, 24
	s_nop 1
	v_lshl_add_u64 v[102:103], s[8:9], 0, v[100:101]
	global_load_dword v135, v[102:103], off offset:140
	s_nop 0
	v_add_u32_e32 v102, s23, v104
	s_nop 0
	v_mov_b32_e32 v104, v161
	s_waitcnt lgkmcnt(0)
	v_readlane_b32 s9, v251, 25
	v_readlane_b32 s8, v251, 24
	s_nop 1
	v_lshl_add_u64 v[102:103], s[8:9], 0, v[100:101]
	global_load_dword v102, v[102:103], off offset:16
	s_nop 0
	v_add_u32_e32 v103, s23, v104
	s_nop 0
	v_mov_b32_e32 v103, v161
	s_waitcnt lgkmcnt(0)
	v_readlane_b32 s9, v251, 25
	v_readlane_b32 s8, v251, 24
	s_nop 1
	v_lshl_add_u64 v[104:105], s[8:9], 0, v[100:101]
	global_load_dword v137, v[104:105], off offset:144
	s_nop 0
	v_add_u32_e32 v103, s23, v103
	s_nop 0
	s_waitcnt lgkmcnt(0)
; #define PIN(i) ((const float*)ldq_(L, (i)))
; __device__ __forceinline__ bf16x8 pack8(const float* v) { u32x4 w; w.x = pk2(v[0], v[1]); w.y = pk2(v[2], v[3]); w.z = pk2(v[4], v[5]); w.w = pk2(v[6], v[7]); return __builtin_bit_cast(bf16x8, w); }
; __device__ __forceinline__ void unpack8(u32x4 w, float* v) { v[0] = bflo(w.x); v[1] = bfhi(w.x); v[2] = bflo(w.y); v[3] = bfhi(w.y); v[4] = bflo(w.z); v[5] = bfhi(w.z); v[6] = bflo(w.w); v[7] = bfhi(w.w); }
; __device__ __forceinline__ void mixer_unit(const Params& p, int layer, int cu, LAS unsigned char* L, int wv) {
;     ...
;         for (int i = 0; i < 8; ++i) { gq0[i] = PIN(I_QN)[layer * 64 + 8 * quad + i]; gq1[i] = PIN(I_QN)[layer * 64 + 32 + 8 * quad + i]; }
;         constexpr float QS = 0.125f * LOG2E;
; #pragma unroll
;         for (int qb = 0; qb < 4; ++qb) {
;             float v0[8], v1[8]; unpack8(qraw[qb][0], v0); unpack8(qraw[qb][1], v1);
;             float ss = 0.f;
; #pragma unroll
;             for (int i = 0; i < 8; ++i) ss += v0[i] * v0[i] + v1[i] * v1[i];
;             ss += __shfl_xor(ss, 16); ss += __shfl_xor(ss, 32);
;             const float rs = __builtin_amdgcn_rsqf(ss * (1.0f / 64.0f) + EPS);
;             float pv[8];
; #pragma unroll
;             for (int i = 0; i < 8; ++i) { v0[i] = v0[i] * rs * gq0[i]; v1[i] = v1[i] * rs * gq1[i] * QS; pv[i] = __shfl_xor(v0[i], 16); }
;             if (quad < 2) {
;                 const f32x4 c0 = rq[qb][0], c1 = rq[qb][1], s0 = rq[qb][2], s1 = rq[qb][3];
; #pragma unroll
;                 for (int i = 0; i < 8; ++i) { const float cs = i < 4 ? c0[i & 3] : c1[i & 3], sn = i < 4 ? s0[i & 3] : s1[i & 3]; v0[i] = (quad == 0) ? v0[i] * cs - pv[i] * sn : v0[i] * cs + pv[i] * sn; }
;             }
; #pragma unroll
;             for (int i = 0; i < 8; ++i) v0[i] *= QS;
;             qf[qb][0] = pack8(v0); qf[qb][1] = pack8(v1);
	v_readlane_b32 s9, v251, 25
	v_readlane_b32 s8, v251, 24
	s_nop 1
	v_lshl_add_u64 v[104:105], s[8:9], 0, v[100:101]
	global_load_dword v103, v[104:105], off offset:20
	s_nop 0
	v_add_u32_e32 v104, s23, v106
	s_nop 0
	v_mov_b32_e32 v106, v161
	s_waitcnt lgkmcnt(0)
	v_readlane_b32 s9, v251, 25
	v_readlane_b32 s8, v251, 24
	s_nop 1
	v_lshl_add_u64 v[104:105], s[8:9], 0, v[100:101]
	global_load_dword v136, v[104:105], off offset:148
	s_nop 0
	v_add_u32_e32 v104, s23, v106
	s_nop 0
	v_mov_b32_e32 v106, v161
	s_waitcnt lgkmcnt(0)
	v_readlane_b32 s9, v251, 25
	v_readlane_b32 s8, v251, 24
	s_nop 1
	v_lshl_add_u64 v[104:105], s[8:9], 0, v[100:101]
	global_load_dword v112, v[104:105], off offset:24
	s_nop 0
	v_add_u32_e32 v104, s23, v106
	s_nop 0
	v_mov_b32_e32 v106, v161
	s_waitcnt lgkmcnt(0)
	v_readlane_b32 s9, v251, 25
	v_readlane_b32 s8, v251, 24
	s_nop 1
	v_lshl_add_u64 v[104:105], s[8:9], 0, v[100:101]
	global_load_dword v139, v[104:105], off offset:152
	s_nop 0
	v_add_u32_e32 v104, s23, v106
	s_nop 0
	v_mov_b32_e32 v106, v161
	s_waitcnt lgkmcnt(0)
	v_readlane_b32 s9, v251, 25
	v_readlane_b32 s8, v251, 24
	s_nop 1
	v_lshl_add_u64 v[104:105], s[8:9], 0, v[100:101]
	global_load_dword v113, v[104:105], off offset:28
	s_nop 0
	v_add_u32_e32 v104, s23, v106
	s_nop 0
	s_waitcnt lgkmcnt(0)
	v_readlane_b32 s9, v251, 25
	v_readlane_b32 s8, v251, 24
	s_nop 1
	v_lshl_add_u64 v[100:101], s[8:9], 0, v[100:101]
	global_load_dword v138, v[100:101], off offset:156
	v_and_b32_e32 v100, 0xffff0000, v94
	v_lshlrev_b32_e32 v101, 16, v94
	v_pk_mul_f32 v[104:105], v[100:101], v[100:101]
	v_pk_mul_f32 v[94:95], v[90:91], v[90:91]
	v_pk_fma_f32 v[106:107], v[108:109], v[108:109], v[104:105]
	v_lshlrev_b32_e32 v104, 16, v92
	v_and_b32_e32 v105, 0xffff0000, v92
	v_pk_fma_f32 v[114:115], v[110:111], v[110:111], v[94:95]
	v_lshlrev_b32_e32 v94, 16, v93
	v_and_b32_e32 v95, 0xffff0000, v93
	v_pk_mul_f32 v[92:93], v[104:105], v[104:105]
	v_pk_mul_f32 v[88:89], v[94:95], v[94:95]
	v_pk_fma_f32 v[92:93], v[116:117], v[116:117], v[92:93]
	v_pk_fma_f32 v[88:89], v[118:119], v[118:119], v[88:89]
	v_add_f32_e32 v92, v92, v93
	v_add_f32_e32 v88, v88, v92
	v_add_f32_e32 v88, v89, v88
	v_add_f32_e32 v88, v107, v88
	v_add_f32_e32 v88, v106, v88
	v_add_f32_e32 v88, v115, v88
	v_add_f32_e32 v88, v114, v88
	ds_bpermute_b32 v89, v184, v88
	s_waitcnt lgkmcnt(0)
	v_add_f32_e32 v88, v88, v89
	ds_bpermute_b32 v89, v185, v88
	s_waitcnt lgkmcnt(0)
	v_add_f32_e32 v88, v88, v89
	v_fmamk_f32 v88, v88, 0x3c800000, v189
	v_rsq_f32_e32 v92, v88
	s_nop 0
	v_pk_mul_f32 v[88:89], v[92:93], v[116:117] op_sel_hi:[0,1]
	v_pk_mul_f32 v[106:107], v[92:93], v[118:119] op_sel_hi:[0,1]
	v_pk_mul_f32 v[108:109], v[92:93], v[108:109] op_sel_hi:[0,1]
	v_pk_mul_f32 v[110:111], v[92:93], v[110:111] op_sel_hi:[0,1]
	s_waitcnt vmcnt(13)
	v_pk_mul_f32 v[88:89], v[96:97], v[88:89]
	s_waitcnt vmcnt(9)
	v_pk_mul_f32 v[106:107], v[98:99], v[106:107]
	s_waitcnt vmcnt(5)
	v_pk_mul_f32 v[108:109], v[102:103], v[108:109] op_sel:[0,1] op_sel_hi:[1,0]
	ds_bpermute_b32 v120, v184, v88
	ds_bpermute_b32 v121, v184, v89
	ds_bpermute_b32 v118, v184, v106
	ds_bpermute_b32 v119, v184, v107
	ds_bpermute_b32 v116, v184, v108
	ds_bpermute_b32 v117, v184, v109
	s_waitcnt vmcnt(1)
	v_pk_mul_f32 v[110:111], v[112:113], v[110:111] op_sel:[0,1] op_sel_hi:[1,0]
	ds_bpermute_b32 v114, v184, v110
	ds_bpermute_b32 v115, v184, v111
	s_and_saveexec_b64 s[8:9], s[6:7]
	s_cbranch_execz .LBB0_1418
	s_waitcnt lgkmcnt(6)
	v_pk_mul_f32 v[84:85], v[84:85], v[120:121]
	s_waitcnt lgkmcnt(4)
	v_pk_mul_f32 v[86:87], v[86:87], v[118:119]
	s_waitcnt lgkmcnt(2)
	v_pk_mul_f32 v[80:81], v[80:81], v[116:117]
	s_waitcnt lgkmcnt(0)
	v_pk_mul_f32 v[82:83], v[82:83], v[114:115]
	v_cndmask_b32_e64 v85, v85, -v85, vcc
	v_cndmask_b32_e64 v84, v84, -v84, vcc
	v_cndmask_b32_e64 v87, v87, -v87, vcc
	v_cndmask_b32_e64 v86, v86, -v86, vcc
	v_cndmask_b32_e64 v81, v81, -v81, vcc
	v_cndmask_b32_e64 v80, v80, -v80, vcc
	v_cndmask_b32_e64 v83, v83, -v83, vcc
	v_cndmask_b32_e64 v82, v82, -v82, vcc
	v_pk_fma_f32 v[88:89], v[72:73], v[88:89], v[84:85]
	v_pk_fma_f32 v[106:107], v[74:75], v[106:107], v[86:87]
	v_pk_fma_f32 v[108:109], v[76:77], v[108:109], v[80:81]
	v_pk_fma_f32 v[110:111], v[78:79], v[110:111], v[82:83]

; #define PIN(i) ((const float*)ldq_(L, (i)))
; #define PREP_CONV(bit, SRC, Kd, Nd, DST, GK, MODE) if (mask & (bit)) { for (int it = gw; it < ((Kd) / 64) * ((Nd) / 64); it += NGW) transpose_item((SRC), (Kd), (Nd), (bf16_t*)(wl + (DST)), (GK), (MODE), scr, it, lane); }
; __device__ __forceinline__ void transpose_item(const float* W, int K, int N, bf16_t* WT, const float* gk, int mode, LAS float* scr_, int item, int lane) {
;     ...
;     const int nblk = N / 64, kb = item / nblk, nb = item % nblk, k0 = 64 * kb, n0 = 64 * nb;
;     const int sc = (mode == 1) ? (((n0 >> 7) & 1) * DFF + (n0 >> 8) * 128 + (n0 & 127)) : n0;
;     const float* src = W + (size_t)k0 * N + sc + lane;
;     float va[32], vb[32];
; #pragma unroll
;     for (int kp = 0; kp < 32; ++kp) { va[kp] = src[(size_t)(2 * kp) * N]; vb[kp] = src[(size_t)(2 * kp + 1) * N]; }
; #pragma unroll
;     for (int kp = 0; kp < 32; ++kp) {
;         float a = va[kp], b = vb[kp];
;         if (gk) { a *= gk[k0 + 2 * kp]; b *= gk[k0 + 2 * kp + 1]; }
; __device__ __forceinline__ void prep(const Params& p, LAS unsigned char* L, int wv, int vb, int nvb, int l, int mask) {
;     ...
;     PREP_CONV(PM_WIN, PIN(I_WIN) + (size_t)l * DM * NIN, DM, NIN, WL_IN, PIN(I_NMIX) + l * DM, 0)
.LBB0_1808:
	v_mov_b32_e32 v2, v161
	s_mul_i32 s12, s6, 0x500000
	v_add_u32_e32 v2, 0, v2
	v_add_u32_e32 v2, 0x20158, v2
	s_nop 0
	s_mov_b64 s[30:31], -1
	s_waitcnt lgkmcnt(0)
	v_readlane_b32 s5, v251, 22
	v_mov_b32_e32 v2, v161
	v_readlane_b32 s4, v251, 23
	v_add_u32_e32 v2, 0, v2
	v_add_u32_e32 v2, 0x20150, v2
	s_nop 0
	s_add_u32 s13, s5, s12
	s_mul_hi_i32 s5, s6, 0x500000
	s_addc_u32 s21, s4, s5
	s_mul_hi_i32 s12, s34, 0x66666667
	s_waitcnt lgkmcnt(0)
	v_readlane_b32 s4, v251, 20
	v_readlane_b32 s5, v251, 21
	s_add_u32 s40, s4, s10
	s_addc_u32 s41, s5, s11
	s_lshr_b32 s18, s12, 31
	s_ashr_i32 s12, s12, 3
	s_add_i32 s24, s12, s18
	s_lshl_b32 s18, s24, 6
	s_mul_i32 s12, s24, 0xfffffb00
	s_add_i32 s12, s35, s12
	s_ashr_i32 s19, s18, 31
	s_mul_i32 s24, s24, 0x50000
	s_mul_hi_i32 s25, s18, 0x1400
	s_add_u32 s26, s13, s24
	s_addc_u32 s21, s21, s25
	s_ashr_i32 s13, s12, 31
	s_lshl_b64 s[24:25], s[12:13], 2
	s_add_u32 s24, s26, s24
	s_addc_u32 s25, s21, s25
	s_waitcnt vmcnt(9)
	v_lshl_add_u64 v[66:67], s[24:25], 0, v[160:161]
	s_movk_i32 s13, 0x1000
	v_add_co_u32_e32 v2, vcc, s13, v66
	s_movk_i32 s13, 0x3000
	s_nop 0
	v_addc_co_u32_e32 v3, vcc, 0, v67, vcc
	global_load_dword v63, v[2:3], off offset:1024
	v_add_co_u32_e32 v2, vcc, s79, v66
	global_load_dword v62, v160, s[24:25]
	s_nop 0
	v_addc_co_u32_e32 v3, vcc, 0, v67, vcc
	global_load_dword v64, v[2:3], off offset:2048
	v_add_co_u32_e32 v2, vcc, s13, v66
	s_movk_i32 s13, 0x5000
	s_nop 0
	v_addc_co_u32_e32 v3, vcc, 0, v67, vcc
	global_load_dword v65, v[2:3], off offset:3072
	v_add_co_u32_e32 v2, vcc, s13, v66
	s_movk_i32 s13, 0x7000
	s_nop 0
	v_addc_co_u32_e32 v3, vcc, 0, v67, vcc
	global_load_dword v54, v[2:3], off
	v_add_co_u32_e32 v2, vcc, s80, v66
	s_cmp_lg_u64 s[4:5], 0
	s_nop 0
	v_addc_co_u32_e32 v3, vcc, 0, v67, vcc
	global_load_dword v55, v[2:3], off offset:1024
	v_add_co_u32_e32 v2, vcc, s13, v66
	s_mov_b32 s13, 0xb000
	s_nop 0
	v_addc_co_u32_e32 v3, vcc, 0, v67, vcc
	global_load_dword v60, v[2:3], off offset:2048
	v_add_co_u32_e32 v2, vcc, s70, v66
	s_cselect_b64 s[24:25], -1, 0
	s_nop 0
	v_addc_co_u32_e32 v3, vcc, 0, v67, vcc
	global_load_dword v61, v[2:3], off offset:3072
	v_add_co_u32_e32 v2, vcc, s71, v66
	s_cmp_eq_u64 s[4:5], 0
	s_nop 0
	v_addc_co_u32_e32 v3, vcc, 0, v67, vcc
	global_load_dword v56, v[2:3], off
	v_add_co_u32_e32 v2, vcc, s13, v66
	s_mov_b32 s13, 0xd000
	s_nop 0
	v_addc_co_u32_e32 v3, vcc, 0, v67, vcc
	global_load_dword v57, v[2:3], off offset:1024
	v_add_co_u32_e32 v2, vcc, s91, v66
	s_nop 1
	v_addc_co_u32_e32 v3, vcc, 0, v67, vcc
	global_load_dword v58, v[2:3], off offset:2048
	v_add_co_u32_e32 v2, vcc, s13, v66
	s_mov_b32 s13, 0xf000
	s_nop 0
	v_addc_co_u32_e32 v3, vcc, 0, v67, vcc
	global_load_dword v59, v[2:3], off offset:3072
	v_add_co_u32_e32 v2, vcc, s13, v66
	s_mov_b32 s13, 0x11000
	s_nop 0
	v_addc_co_u32_e32 v3, vcc, 0, v67, vcc
	global_load_dword v46, v[2:3], off
	v_add_co_u32_e32 v2, vcc, s37, v66
	s_nop 1
	v_addc_co_u32_e32 v3, vcc, 0, v67, vcc
	global_load_dword v47, v[2:3], off offset:1024
	v_add_co_u32_e32 v2, vcc, s13, v66
	s_mov_b32 s13, 0x15000
	s_nop 0
	v_addc_co_u32_e32 v3, vcc, 0, v67, vcc
	global_load_dword v52, v[2:3], off offset:2048
	v_add_co_u32_e32 v2, vcc, s94, v66
	s_nop 1
	v_addc_co_u32_e32 v3, vcc, 0, v67, vcc
	global_load_dword v53, v[2:3], off offset:3072
	v_add_co_u32_e32 v2, vcc, s46, v66
	s_nop 1
	v_addc_co_u32_e32 v3, vcc, 0, v67, vcc
	global_load_dword v48, v[2:3], off
	v_add_co_u32_e32 v2, vcc, s13, v66
	s_mov_b32 s13, 0x17000
	s_nop 0
	v_addc_co_u32_e32 v3, vcc, 0, v67, vcc
	global_load_dword v49, v[2:3], off offset:1024
	v_add_co_u32_e32 v2, vcc, s47, v66
	s_nop 1
	v_addc_co_u32_e32 v3, vcc, 0, v67, vcc
	global_load_dword v50, v[2:3], off offset:2048
	v_add_co_u32_e32 v2, vcc, s13, v66
	s_mov_b32 s13, 0x19000
	s_nop 0
	v_addc_co_u32_e32 v3, vcc, 0, v67, vcc
	global_load_dword v51, v[2:3], off offset:3072
	v_add_co_u32_e32 v2, vcc, s13, v66
	s_mov_b32 s13, 0x1b000
	s_nop 0
	v_addc_co_u32_e32 v3, vcc, 0, v67, vcc
	global_load_dword v38, v[2:3], off
	v_add_co_u32_e32 v2, vcc, s81, v66
	s_nop 1
	v_addc_co_u32_e32 v3, vcc, 0, v67, vcc
	global_load_dword v39, v[2:3], off offset:1024
	v_add_co_u32_e32 v2, vcc, s13, v66
	s_mov_b32 s13, 0x1f000
	s_nop 0
	v_addc_co_u32_e32 v3, vcc, 0, v67, vcc
	global_load_dword v44, v[2:3], off offset:2048
	v_add_co_u32_e32 v2, vcc, s83, v66
	s_nop 1
	v_addc_co_u32_e32 v3, vcc, 0, v67, vcc
	global_load_dword v45, v[2:3], off offset:3072
	v_add_co_u32_e32 v2, vcc, s27, v66
	s_nop 1
	v_addc_co_u32_e32 v3, vcc, 0, v67, vcc
	global_load_dword v40, v[2:3], off
	v_add_co_u32_e32 v2, vcc, s13, v66
	s_mov_b32 s13, 0x21000
	s_nop 0
	v_addc_co_u32_e32 v3, vcc, 0, v67, vcc
	global_load_dword v41, v[2:3], off offset:1024
	v_add_co_u32_e32 v2, vcc, s50, v66
	s_nop 1
	v_addc_co_u32_e32 v3, vcc, 0, v67, vcc
	global_load_dword v42, v[2:3], off offset:2048
	v_add_co_u32_e32 v2, vcc, s13, v66
	s_mov_b32 s13, 0x23000
	s_nop 0
	v_addc_co_u32_e32 v3, vcc, 0, v67, vcc
	global_load_dword v43, v[2:3], off offset:3072
	v_add_co_u32_e32 v2, vcc, s13, v66
	s_mov_b32 s13, 0x25000
	s_nop 0
	v_addc_co_u32_e32 v3, vcc, 0, v67, vcc
	global_load_dword v30, v[2:3], off
	v_add_co_u32_e32 v2, vcc, s28, v66
	s_nop 1
; __device__ __forceinline__ void transpose_item(const float* W, int K, int N, bf16_t* WT, const float* gk, int mode, LAS float* scr_, int item, int lane) {
;     ...
;     float va[32], vb[32];
; #pragma unroll
;     for (int kp = 0; kp < 32; ++kp) { va[kp] = src[(size_t)(2 * kp) * N]; vb[kp] = src[(size_t)(2 * kp + 1) * N]; }
; #pragma unroll
;     for (int kp = 0; kp < 32; ++kp) {
;         float a = va[kp], b = vb[kp];
;         if (gk) { a *= gk[k0 + 2 * kp]; b *= gk[k0 + 2 * kp + 1]; }
	v_addc_co_u32_e32 v3, vcc, 0, v67, vcc
	global_load_dword v31, v[2:3], off offset:1024
	v_add_co_u32_e32 v2, vcc, s13, v66
	s_mov_b32 s13, 0x29000
	s_nop 0
	v_addc_co_u32_e32 v3, vcc, 0, v67, vcc
	global_load_dword v36, v[2:3], off offset:2048
	v_add_co_u32_e32 v2, vcc, s73, v66
	s_nop 1
	v_addc_co_u32_e32 v3, vcc, 0, v67, vcc
	global_load_dword v37, v[2:3], off offset:3072
	v_add_co_u32_e32 v2, vcc, s1, v66
	s_nop 1
	v_addc_co_u32_e32 v3, vcc, 0, v67, vcc
	global_load_dword v32, v[2:3], off
	v_add_co_u32_e32 v2, vcc, s13, v66
	s_mov_b32 s13, 0x2b000
	s_nop 0
	v_addc_co_u32_e32 v3, vcc, 0, v67, vcc
	global_load_dword v33, v[2:3], off offset:1024
	v_add_co_u32_e32 v2, vcc, s72, v66
	s_nop 1
	v_addc_co_u32_e32 v3, vcc, 0, v67, vcc
	global_load_dword v34, v[2:3], off offset:2048
	v_add_co_u32_e32 v2, vcc, s13, v66
	s_mov_b32 s13, 0x2d000
	s_nop 0
	v_addc_co_u32_e32 v3, vcc, 0, v67, vcc
	global_load_dword v35, v[2:3], off offset:3072
	v_add_co_u32_e32 v2, vcc, s13, v66
	s_mov_b32 s13, 0x2f000
	s_nop 0
	v_addc_co_u32_e32 v3, vcc, 0, v67, vcc
	global_load_dword v22, v[2:3], off
	v_add_co_u32_e32 v2, vcc, s33, v66
	s_nop 1
	v_addc_co_u32_e32 v3, vcc, 0, v67, vcc
	global_load_dword v23, v[2:3], off offset:1024
	v_add_co_u32_e32 v2, vcc, s13, v66
	s_mov_b32 s13, 0x33000
	s_nop 0
	v_addc_co_u32_e32 v3, vcc, 0, v67, vcc
	global_load_dword v28, v[2:3], off offset:2048
	v_add_co_u32_e32 v2, vcc, s22, v66
	s_nop 1
	v_addc_co_u32_e32 v3, vcc, 0, v67, vcc
	global_load_dword v29, v[2:3], off offset:3072
	v_add_co_u32_e32 v2, vcc, s38, v66
	s_nop 1
	v_addc_co_u32_e32 v3, vcc, 0, v67, vcc
	global_load_dword v24, v[2:3], off
	v_add_co_u32_e32 v2, vcc, s13, v66
	s_mov_b32 s13, 0x35000
	s_nop 0
	v_addc_co_u32_e32 v3, vcc, 0, v67, vcc
	global_load_dword v25, v[2:3], off offset:1024
	v_add_co_u32_e32 v2, vcc, s39, v66
	s_nop 1
	v_addc_co_u32_e32 v3, vcc, 0, v67, vcc
	global_load_dword v26, v[2:3], off offset:2048
	v_add_co_u32_e32 v2, vcc, s13, v66
	s_mov_b32 s13, 0x37000
	s_nop 0
	v_addc_co_u32_e32 v3, vcc, 0, v67, vcc
	global_load_dword v27, v[2:3], off offset:3072
	v_add_co_u32_e32 v2, vcc, s13, v66
	s_mov_b32 s13, 0x39000
	s_nop 0
	v_addc_co_u32_e32 v3, vcc, 0, v67, vcc
	global_load_dword v14, v[2:3], off
	v_add_co_u32_e32 v2, vcc, s69, v66
	s_nop 1
	v_addc_co_u32_e32 v3, vcc, 0, v67, vcc
	global_load_dword v15, v[2:3], off offset:1024
	v_add_co_u32_e32 v2, vcc, s13, v66
	s_mov_b32 s13, 0x3d000
	s_nop 0
	v_addc_co_u32_e32 v3, vcc, 0, v67, vcc
	global_load_dword v20, v[2:3], off offset:2048
	v_add_co_u32_e32 v2, vcc, s87, v66
	s_nop 1
	v_addc_co_u32_e32 v3, vcc, 0, v67, vcc
	global_load_dword v21, v[2:3], off offset:3072
	v_add_co_u32_e32 v2, vcc, s90, v66
	s_nop 1
	v_addc_co_u32_e32 v3, vcc, 0, v67, vcc
	global_load_dword v16, v[2:3], off
	v_add_co_u32_e32 v2, vcc, s13, v66
	s_mov_b32 s13, 0x41000
	s_nop 0
	v_addc_co_u32_e32 v3, vcc, 0, v67, vcc
	global_load_dword v17, v[2:3], off offset:1024
	v_add_co_u32_e32 v2, vcc, s51, v66
	s_nop 1
	v_addc_co_u32_e32 v3, vcc, 0, v67, vcc
	global_load_dword v18, v[2:3], off offset:2048
	v_add_co_u32_e32 v2, vcc, s52, v66
	s_nop 1
	v_addc_co_u32_e32 v3, vcc, 0, v67, vcc
	global_load_dword v19, v[2:3], off offset:3072
	v_add_co_u32_e32 v2, vcc, s13, v66
	s_mov_b32 s13, 0x43000
	s_nop 0
	v_addc_co_u32_e32 v3, vcc, 0, v67, vcc
	global_load_dword v4, v[2:3], off
	v_add_co_u32_e32 v2, vcc, s93, v66
	s_nop 1
	v_addc_co_u32_e32 v3, vcc, 0, v67, vcc
	global_load_dword v5, v[2:3], off offset:1024
	v_add_co_u32_e32 v2, vcc, s13, v66
	s_mov_b32 s13, 0x44000
	s_nop 0
	v_addc_co_u32_e32 v3, vcc, 0, v67, vcc
	global_load_dword v10, v[2:3], off offset:2048
	v_add_co_u32_e32 v2, vcc, s13, v66
	s_mov_b32 s13, 0x46000
	s_nop 0
	v_addc_co_u32_e32 v3, vcc, 0, v67, vcc
	global_load_dword v11, v[2:3], off offset:3072
	v_add_co_u32_e32 v2, vcc, s13, v66
	s_mov_b32 s13, 0x47000
	s_nop 0
	v_addc_co_u32_e32 v3, vcc, 0, v67, vcc
	global_load_dword v6, v[2:3], off
	v_add_co_u32_e32 v2, vcc, s13, v66
	s_mov_b32 s13, 0x48000
	s_nop 0
	v_addc_co_u32_e32 v3, vcc, 0, v67, vcc
	global_load_dword v7, v[2:3], off offset:1024
	v_add_co_u32_e32 v2, vcc, s13, v66
	s_mov_b32 s13, 0x49000
	s_nop 0
	v_addc_co_u32_e32 v3, vcc, 0, v67, vcc
	global_load_dword v12, v[2:3], off offset:2048
	v_add_co_u32_e32 v2, vcc, s13, v66
	s_mov_b32 s13, 0x4b000
	s_nop 0
	v_addc_co_u32_e32 v3, vcc, 0, v67, vcc
	global_load_dword v13, v[2:3], off offset:3072
	v_add_co_u32_e32 v2, vcc, s13, v66
	s_mov_b32 s13, 0x4c000
	s_nop 0
	v_addc_co_u32_e32 v3, vcc, 0, v67, vcc
	v_add_co_u32_e32 v8, vcc, s13, v66
	global_load_dword v2, v[2:3], off
	s_nop 0
	v_addc_co_u32_e32 v9, vcc, 0, v67, vcc
	global_load_dword v3, v[8:9], off offset:1024
	v_add_co_u32_e32 v8, vcc, 0x4d000, v66
	s_nop 1
	v_addc_co_u32_e32 v9, vcc, 0, v67, vcc
	v_add_co_u32_e32 v66, vcc, 0x4e000, v66
	global_load_dword v8, v[8:9], off offset:2048
	s_nop 0
	v_addc_co_u32_e32 v67, vcc, 0, v67, vcc
	global_load_dword v9, v[66:67], off offset:3072
	s_cbranch_scc1 .LBB0_1810
	s_lshl_b64 s[4:5], s[18:19], 2
	s_add_u32 s4, s40, s4
	s_addc_u32 s5, s41, s5
	global_load_dwordx4 v[66:69], v161, s[4:5]
	s_mov_b64 s[30:31], 0
	s_waitcnt vmcnt(0)
	v_pk_mul_f32 v[66:67], v[62:63], v[66:67]
	v_pk_mul_f32 v[68:69], v[64:65], v[68:69]

; #define PIN(i) ((const float*)ldq_(L, (i)))
; __device__ __forceinline__ unsigned pk2(float lo, float hi) { f32x2 v = {lo, hi}; bf16x2_t b = __builtin_convertvector(v, bf16x2_t); return __builtin_bit_cast(unsigned, b); }
; __device__ __forceinline__ void prep(const Params& p, LAS unsigned char* L, int wv, int vb, int nvb, int l, int mask) {
;     ...
;     if (mask & PM_POOL) {
;         for (int t = gt; t < 4 * 128 * 16; t += NGT) {
;             const int ko = t & 15, n = (t >> 4) & 127, g = (t >> 11) & 3;
;             const float* src = PIN(I_WPOOL) + ((size_t)(l * 4 + g) * 128 + 8 * ko) * 128 + n; const float sc = PIN(I_PSCALE)[l * 512 + g * 128 + n];
;             u32x4 o; o.x = pk2(src[0] * sc, src[128] * sc); o.y = pk2(src[256] * sc, src[384] * sc); o.z = pk2(src[512] * sc, src[640] * sc); o.w = pk2(src[768] * sc, src[896] * sc);
;             *(u32x4*)((bf16_t*)(wl + WL_POOL) + ((size_t)g * 128 + n) * 128 + 8 * ko) = o;
;         }
.LBB0_1874:
	v_mov_b32_e32 v4, v161
	v_add_u32_e32 v2, 0x1c000, v2
	v_add_u32_e32 v4, 0, v4
	v_add_u32_e32 v4, 0x20178, v4
	s_nop 0
	v_bfe_u32 v14, v2, 11, 2
	v_and_b32_e32 v15, 0x78, v3
	v_bfe_u32 v11, v2, 4, 7
	v_lshlrev_b32_e32 v160, 9, v15
	s_waitcnt lgkmcnt(0)
	v_readlane_b32 s18, v251, 30
	v_or_b32_e32 v4, s12, v14
	v_readlane_b32 s19, v251, 31
	v_ashrrev_i32_e32 v5, 31, v4
	v_lshlrev_b64 v[4:5], 16, v[4:5]
	v_lshl_add_u64 v[4:5], s[18:19], 0, v[4:5]
	v_lshl_add_u64 v[4:5], v[4:5], 0, v[160:161]
	v_lshlrev_b32_e32 v160, 2, v11
	v_lshl_add_u64 v[8:9], v[4:5], 0, v[160:161]
	v_mov_b32_e32 v4, v161
	v_lshlrev_b32_e32 v6, 7, v14
	v_add_u32_e32 v4, 0, v4
	v_add_u32_e32 v4, 0x20180, v4
	s_nop 0
	v_or3_b32 v6, v6, s13, v11
	v_ashrrev_i32_e32 v7, 31, v6
	v_cmp_lt_i32_e32 vcc, s21, v2
	v_add_u32_e32 v3, 0xe0000, v3
	s_waitcnt lgkmcnt(0)
	v_readlane_b32 s16, v251, 33
	v_readlane_b32 s18, v251, 32
	s_or_b64 s[10:11], vcc, s[10:11]
	v_mov_b32_e32 v5, s16
	v_mov_b32_e32 v4, s18
	v_lshl_add_u64 v[4:5], v[6:7], 2, v[4:5]
	global_load_dword v10, v[4:5], off
	s_nop 0
	global_load_dword v4, v[8:9], off
	global_load_dword v5, v[8:9], off offset:512
	global_load_dword v6, v[8:9], off offset:1024
	global_load_dword v7, v[8:9], off offset:1536
	s_waitcnt vmcnt(2)
	v_pk_mul_f32 v[4:5], v[10:11], v[4:5] op_sel_hi:[0,1]
	s_waitcnt vmcnt(0)
	v_pk_mul_f32 v[6:7], v[10:11], v[6:7] op_sel_hi:[0,1]
	v_cvt_pk_bf16_f32 v4, v4, v5
	v_cvt_pk_bf16_f32 v5, v6, v7
	global_load_dword v6, v[8:9], off offset:2048
	global_load_dword v7, v[8:9], off offset:2560
	global_load_dword v12, v[8:9], off offset:3072
	global_load_dword v13, v[8:9], off offset:3584
	s_waitcnt vmcnt(2)
	v_pk_mul_f32 v[6:7], v[10:11], v[6:7] op_sel_hi:[0,1]
	s_waitcnt vmcnt(0)
	v_pk_mul_f32 v[8:9], v[10:11], v[12:13] op_sel_hi:[0,1]
	v_cvt_pk_bf16_f32 v6, v6, v7
	v_cvt_pk_bf16_f32 v7, v8, v9
	v_lshlrev_b32_e32 v8, 8, v11
	v_lshl_or_b32 v160, v14, 15, v8
	v_lshl_add_u64 v[8:9], s[8:9], 0, v[160:161]
	v_lshlrev_b32_e32 v160, 1, v15
	v_lshl_add_u64 v[8:9], v[8:9], 0, v[160:161]
	global_store_dwordx4 v[8:9], v[4:7], off
	s_andn2_b64 exec, exec, s[10:11]
	s_cbranch_execnz .LBB0_1874

; #define PG8_STAGE(bufoff, gbase, voff) do { _Pragma("unroll") for (int _i = 0; _i < 2; ++_i) \
;         __builtin_amdgcn_global_load_lds((const unsigned*)((const char*)(gbase) + (voff)[_i]), (PG8_LAS unsigned*)(lds + (bufoff) + ldsw + _i * 8192), 16, 0, 0); } while (0)
; #define PG8_WAIT_V(n) asm volatile("s_waitcnt vmcnt(" #n ")" ::: "memory")
; #define PG8_BAR __builtin_amdgcn_s_barrier()
; template <class Epi, class Sched, bool ALIGN_EPI = false, bool SP2 = false>
; __device__ __forceinline__ void gemm_phase(PG8_LAS unsigned char* lds, const Gemm g, const Sched& S, const Epi& E, int wv) {
;     ...
;     const int tid = tid_, wid = __builtin_amdgcn_readfirstlane(tid >> 6), lane = tid & 63, wr = wid >> 2, wc = wid & 3, fr = lane & 15, fq = lane >> 4;
;     const int K = g.K, nt = K / BK;
;     unsigned voffA[2], voffB[2];
; #pragma unroll
;     for (int i = 0; i < 2; ++i) { int R, C; stage_rc(tid * 16 + i * 8192, R, C); const int Rb = Epi::PERM ? ((R & ~31) + perm32(R & 31)) : R;
;         voffA[i] = (unsigned)(R * K + C) * 2u; voffB[i] = (unsigned)(Rb * K + C) * 2u; }
;     const size_t kstep = (size_t)(BK * 2);
;     const size_t hstep = (size_t)HALF * K * 2;
;     const size_t tstep = 2 * hstep;
;     const unsigned ldsw = (unsigned)wid * 1024u;
;     const int aoff = lds_byte(wr * 64 + fr, fq * 8), boff = lds_byte(wc * 32 + fr, fq * 8);
;     ...
;     Unit cur, nxt; int ui = 0;
;     if (!S.next(0, cur)) return;
;     f32x4 acc[2][2][4][2];
; #pragma unroll
;     for (int a = 0; a < 2; ++a)
; #pragma unroll
;         for (int b = 0; b < 2; ++b)
; #pragma unroll
;             for (int m = 0; m < 4; ++m)
; #pragma unroll
;                 for (int n = 0; n < 2; ++n) acc[a][b][m][n] = (f32x4){0.f, 0.f, 0.f, 0.f};
;     bf16x8 At[4][2], B0[2][2], B1[2][2];
;     const char* cA = (const char*)g.A + (size_t)cur.pm * tstep; const char* cB = (const char*)g.Bt + (size_t)cur.pn * tstep;
;     S.a_ready(cur);
;     if constexpr (SP2) {
;         PG8_STAGE(PG8_SB(0, 0), cB, voffB); PG8_STAGE(PG8_SB(0, 1), cB + hstep, voffB); PG8_STAGE(PG8_SA(0, 0), cA, voffA); PG8_STAGE(PG8_SA(0, 1), cA + hstep, voffA);
;         if (wr == 1) PG8_BAR;
;         PG8_WAIT_V(2); PG8_BAR;
;         PG8_STAGE(PG8_SB(1, 0), cB + kstep, voffB); PG8_STAGE(PG8_SA(1, 0), cA + kstep, voffA); PG8_STAGE(PG8_SB(1, 1), cB + hstep + kstep, voffB);
.LBB0_1947:
	s_or_b64 exec, exec, s[4:5]
	v_readlane_b32 s10, v250, 0
	s_mov_b64 s[4:5], 0
	s_waitcnt lgkmcnt(0)
	v_mov_b32_e32 v0, v161
	s_barrier
	v_readlane_b32 s8, v250, 42
	v_add_u32_e32 v0, 0, v0
	v_add_u32_e32 v0, 0x201c0, v0
	s_nop 0
	v_mov_b32_e32 v14, v183
	v_readlane_b32 s9, v250, 43
	s_and_b64 vcc, exec, s[8:9]
	s_waitcnt lgkmcnt(0)
	v_readlane_b32 s7, v251, 48
	v_mov_b32_e32 v0, v161
	v_readlane_b32 s6, v251, 49
	v_add_u32_e32 v0, 0, v0
	v_add_u32_e32 v0, 0x201c8, v0
	ds_read_b64 v[0:1], v0
	s_nop 0
	v_readfirstlane_b32 s12, v14
	s_cbranch_vccnz .LBB0_1979
	s_waitcnt lgkmcnt(0)
	v_lshlrev_b32_e32 v0, 4, v14
	v_add_u32_e32 v1, 0x2000, v0
	v_ashrrev_i32_e32 v2, 31, v1
	v_lshrrev_b32_e32 v2, 22, v2
	v_add_u32_e32 v2, v1, v2
	v_ashrrev_i32_e32 v8, 10, v2
	v_mul_i32_i24_e32 v2, 0x400, v8
	v_sub_u32_e32 v1, v1, v2
	v_lshrrev_b32_e32 v2, 4, v1
	v_bitop3_b32 v1, v2, v1, 32 bitop3:0x6c
	s_add_u32 s8, s7, s4
	v_ashrrev_i32_e32 v2, 31, v1
	s_addc_u32 s9, s6, s5
	v_lshrrev_b32_e32 v2, 26, v2
	s_add_u32 s14, s8, 0x17b00000
	v_add_u32_e32 v2, v1, v2
	v_lshlrev_b32_e32 v3, 3, v8
	s_addc_u32 s15, s9, 0
	s_mul_i32 s5, s10, 0x2900000
	v_ashrrev_i32_e32 v9, 6, v2
	v_and_b32_e32 v3, -16, v3
	s_mul_hi_i32 s4, s10, 0x2900000
	s_add_u32 s11, s8, s5
	v_add_u32_e32 v3, v9, v3
	s_addc_u32 s19, s9, s4
	v_and_b32_e32 v4, 3, v9
	s_mov_b32 s4, 0x1fffe0
	v_lshrrev_b32_e32 v5, 2, v3
	v_lshlrev_b32_e32 v6, 1, v3
	v_and_b32_e32 v2, 0xc0, v2
	v_and_or_b32 v4, v3, s4, v4
	v_and_b32_e32 v5, 4, v5
	v_and_b32_e32 v6, 24, v6
	v_sub_u32_e32 v1, v1, v2
	v_or3_b32 v4, v4, v5, v6
	v_lshlrev_b32_e32 v5, 5, v8
	v_ashrrev_i16_sdwa v1, v193, sext(v1) dst_sel:DWORD dst_unused:UNUSED_PAD src0_sel:DWORD src1_sel:BYTE_0
	v_and_b32_e32 v5, 32, v5
	v_bfe_i32 v10, v1, 0, 16
	v_add_lshl_u32 v1, v5, v10, 1
	v_lshl_add_u32 v152, v4, 11, v1
	v_lshl_add_u32 v154, v3, 11, v1
	v_bfe_i32 v1, v14, 27, 1
	v_lshrrev_b32_e32 v1, 22, v1
	v_add_u32_e32 v1, v0, v1
	v_and_b32_e32 v1, 0xfffffc00, v1
	v_sub_u32_e32 v0, v0, v1
	v_lshrrev_b32_e32 v1, 4, v0
	v_ashrrev_i32_e32 v2, 31, v14
	v_bitop3_b32 v0, v1, v0, 32 bitop3:0x6c
	v_lshrrev_b32_e32 v2, 26, v2
	v_ashrrev_i32_e32 v1, 31, v0
	v_add_u32_e32 v2, v14, v2
	v_lshrrev_b32_e32 v1, 26, v1
	v_ashrrev_i32_e32 v12, 6, v2
	v_add_u32_e32 v1, v0, v1
	v_lshlrev_b32_e32 v2, 3, v12
	v_ashrrev_i32_e32 v11, 6, v1
	v_and_b32_e32 v2, -16, v2
	v_add_u32_e32 v2, v11, v2
	s_add_u32 s16, s11, 0x1300000
	v_and_b32_e32 v3, 3, v11
	v_lshrrev_b32_e32 v4, 2, v2
	v_lshlrev_b32_e32 v5, 1, v2
	v_and_b32_e32 v1, 0xc0, v1
	s_addc_u32 s29, s19, 0
	s_ashr_i32 s13, s12, 6
	v_and_or_b32 v3, v2, s4, v3
	v_and_b32_e32 v4, 4, v4
	v_and_b32_e32 v5, 24, v5
	v_sub_u32_e32 v0, v0, v1
	s_ashr_i32 s18, s12, 8
	s_lshl_b32 s30, s13, 10
	v_or3_b32 v3, v3, v4, v5
	v_lshlrev_b32_e32 v4, 5, v12
	v_ashrrev_i16_sdwa v0, v193, sext(v0) dst_sel:DWORD dst_unused:UNUSED_PAD src0_sel:DWORD src1_sel:BYTE_0
	v_readlane_b32 s4, v250, 15
	v_and_b32_e32 v4, 32, v4
	v_bfe_i32 v13, v0, 0, 16
	v_readlane_b32 s5, v250, 16
	s_add_u32 s48, s16, s4
	v_add_lshl_u32 v0, v4, v13, 1
	s_addc_u32 s49, s29, s5
	s_add_i32 s31, s30, 0
	v_lshl_add_u32 v160, v3, 11, v0
	s_add_i32 m0, s31, 0x10000
	v_lshl_add_u32 v156, v2, 11, v0
	global_load_lds_dwordx4 v160, s[48:49]
	s_add_i32 m0, s31, 0x12000
	s_add_u32 s4, s48, 0x40000
	global_load_lds_dwordx4 v152, s[48:49]
	s_addc_u32 s5, s49, 0
	s_add_i32 m0, s31, 0x14000
	v_mov_b32_e32 v153, v161
	global_load_lds_dwordx4 v160, s[4:5]
	s_add_i32 m0, s31, 0x16000
	v_mov_b32_e32 v157, v161
	global_load_lds_dwordx4 v152, s[4:5]
	v_readlane_b32 s4, v250, 29
	v_readlane_b32 s5, v250, 30
	s_add_u32 s4, s14, s4
	s_addc_u32 s5, s15, s5
	s_add_i32 s52, s31, 0x2000
	s_mov_b32 m0, s31
	s_add_u32 s6, s4, 0x40000
	global_load_lds_dwordx4 v156, s[4:5]
	s_mov_b32 m0, s52
	s_addc_u32 s7, s5, 0
	s_add_i32 s53, s31, 0x4000
	global_load_lds_dwordx4 v154, s[4:5]
	s_mov_b32 m0, s53
	s_add_i32 s54, s31, 0x6000
	global_load_lds_dwordx4 v156, s[6:7]
	s_mov_b32 m0, s54
	v_mov_b32_e32 v155, v161
	global_load_lds_dwordx4 v154, s[6:7]
	s_cmp_eq_u32 s18, 1
	v_lshl_add_u64 v[6:7], s[48:49], 0, v[160:161]
	v_lshl_add_u64 v[4:5], s[48:49], 0, v[152:153]
	v_lshl_add_u64 v[0:1], s[4:5], 0, v[156:157]
	s_cselect_b64 s[6:7], -1, 0
	s_cmp_lg_u32 s18, 1
	v_lshl_add_u64 v[2:3], s[4:5], 0, v[154:155]
	s_cbranch_scc1 .LBB0_1950
	s_barrier

; #define PIN(i) ((const float*)ldq_(L, (i)))
; #define PREP_CONV(bit, SRC, Kd, Nd, DST, GK, MODE) if (mask & (bit)) { for (int it = gw; it < ((Kd) / 64) * ((Nd) / 64); it += NGW) transpose_item((SRC), (Kd), (Nd), (bf16_t*)(wl + (DST)), (GK), (MODE), scr, it, lane); }
; __device__ __forceinline__ void transpose_item(const float* W, int K, int N, bf16_t* WT, const float* gk, int mode, LAS float* scr_, int item, int lane) {
;     ...
;     const int nblk = N / 64, kb = item / nblk, nb = item % nblk, k0 = 64 * kb, n0 = 64 * nb;
;     const int sc = (mode == 1) ? (((n0 >> 7) & 1) * DFF + (n0 >> 8) * 128 + (n0 & 127)) : n0;
;     const float* src = W + (size_t)k0 * N + sc + lane;
;     float va[32], vb[32];
; #pragma unroll
;     for (int kp = 0; kp < 32; ++kp) { va[kp] = src[(size_t)(2 * kp) * N]; vb[kp] = src[(size_t)(2 * kp + 1) * N]; }
; #pragma unroll
;     for (int kp = 0; kp < 32; ++kp) {
;         float a = va[kp], b = vb[kp];
;         if (gk) { a *= gk[k0 + 2 * kp]; b *= gk[k0 + 2 * kp + 1]; }
; __device__ __forceinline__ void prep(const Params& p, LAS unsigned char* L, int wv, int vb, int nvb, int l, int mask) {
;     ...
;     PREP_CONV(PM_FFB_IN, PIN(I_WFFB_IN) + (size_t)l * DM * NFF2, DM, NFF2, WL_FFB_IN, PIN(I_NFFB) + l * DM, 1)
.LBB0_1983:
	v_mov_b32_e32 v2, v161
	s_mul_hi_i32 s8, s14, 0x2e8ba2e9
	v_add_u32_e32 v2, 0, v2
	v_add_u32_e32 v2, 0x20198, v2
	s_nop 0
	s_waitcnt lgkmcnt(0)
	v_readlane_b32 s5, v251, 38
	v_mov_b32_e32 v2, v161
	v_readlane_b32 s4, v251, 39
	v_add_u32_e32 v2, 0, v2
	v_add_u32_e32 v2, 0x20190, v2
	s_nop 0
	s_add_u32 s11, s5, s16
	s_addc_u32 s12, s4, s15
	s_waitcnt lgkmcnt(0)
	v_readlane_b32 s4, v251, 36
	v_readlane_b32 s5, v251, 37
	s_add_u32 s25, s4, s6
	s_addc_u32 s29, s5, s7
	s_lshr_b32 s9, s8, 31
	s_ashr_i32 s8, s8, 4
	s_add_i32 s13, s8, s9
	s_mul_i32 s9, s13, 0xffffea00
	s_mul_i32 s10, s13, 0xfffff500
	s_add_i32 s24, s18, s9
	s_bfe_i32 s9, s14, 0x10001
	s_add_i32 s10, s19, s10
	s_and_b32 s9, s9, 0xb00
	s_and_b32 s10, s10, 0xffffff80
	s_lshl_b32 s8, s13, 6
	s_add_i32 s9, s9, s10
	s_and_b32 s10, s24, 64
	s_or_b32 s10, s9, s10
	s_ashr_i32 s9, s8, 31
	s_mul_i32 s13, s13, 0x160000
	s_mul_hi_i32 s21, s8, 0x5800
	s_add_u32 s13, s11, s13
	s_addc_u32 s12, s12, s21
	s_ashr_i32 s11, s10, 31
	s_lshl_b64 s[10:11], s[10:11], 2
	s_add_u32 s10, s13, s10
	s_addc_u32 s11, s12, s11
	s_waitcnt vmcnt(9)
	v_lshl_add_u64 v[66:67], s[10:11], 0, v[160:161]
	global_load_dword v62, v160, s[10:11]
	s_movk_i32 s10, 0x5000
	v_add_co_u32_e32 v2, vcc, s10, v66
	s_mov_b32 s10, 0xb000
	s_nop 0
	v_addc_co_u32_e32 v3, vcc, 0, v67, vcc
	global_load_dword v63, v[2:3], off offset:2048
	v_add_co_u32_e32 v2, vcc, s10, v66
	s_mov_b32 s10, 0x1b000
	s_nop 0
	v_addc_co_u32_e32 v3, vcc, 0, v67, vcc
	global_load_dword v64, v[2:3], off
	v_add_co_u32_e32 v2, vcc, s37, v66
	s_cmp_lg_u64 s[4:5], 0
	s_nop 0
	v_addc_co_u32_e32 v3, vcc, 0, v67, vcc
	global_load_dword v65, v[2:3], off offset:2048
	v_add_co_u32_e32 v2, vcc, s47, v66
	s_mov_b64 s[12:13], -1
	s_nop 0
	v_addc_co_u32_e32 v3, vcc, 0, v67, vcc
	global_load_dword v54, v[2:3], off
	v_add_co_u32_e32 v2, vcc, s10, v66
	s_mov_b32 s10, 0x21000
	s_nop 0
	v_addc_co_u32_e32 v3, vcc, 0, v67, vcc
	global_load_dword v55, v[2:3], off offset:2048
	v_add_co_u32_e32 v2, vcc, s10, v66
	s_mov_b32 s10, 0x31000
	s_nop 0
	v_addc_co_u32_e32 v3, vcc, 0, v67, vcc
	global_load_dword v60, v[2:3], off
	v_add_co_u32_e32 v2, vcc, s73, v66
	s_nop 1
	v_addc_co_u32_e32 v3, vcc, 0, v67, vcc
	global_load_dword v61, v[2:3], off offset:2048
	v_add_co_u32_e32 v2, vcc, s82, v66
	s_nop 1
	v_addc_co_u32_e32 v3, vcc, 0, v67, vcc
	global_load_dword v56, v[2:3], off
	v_add_co_u32_e32 v2, vcc, s10, v66
	s_mov_b32 s10, 0x37000
	s_nop 0
	v_addc_co_u32_e32 v3, vcc, 0, v67, vcc
	global_load_dword v57, v[2:3], off offset:2048
	v_add_co_u32_e32 v2, vcc, s10, v66
	s_mov_b32 s10, 0x47000
	s_nop 0
	v_addc_co_u32_e32 v3, vcc, 0, v67, vcc
	global_load_dword v58, v[2:3], off
	v_add_co_u32_e32 v2, vcc, s90, v66
	s_nop 1
	v_addc_co_u32_e32 v3, vcc, 0, v67, vcc
	global_load_dword v59, v[2:3], off offset:2048
	v_add_co_u32_e32 v2, vcc, s93, v66
	s_nop 1
	v_addc_co_u32_e32 v3, vcc, 0, v67, vcc
	global_load_dword v44, v[2:3], off
	v_add_co_u32_e32 v2, vcc, s10, v66
	s_mov_b32 s10, 0x4d000
	s_nop 0
	v_addc_co_u32_e32 v3, vcc, 0, v67, vcc
	global_load_dword v45, v[2:3], off offset:2048
	v_add_co_u32_e32 v2, vcc, s10, v66
	s_mov_b32 s10, 0x52000
	s_nop 0
	v_addc_co_u32_e32 v3, vcc, 0, v67, vcc
	global_load_dword v50, v[2:3], off
	v_add_co_u32_e32 v2, vcc, s10, v66
	s_mov_b32 s10, 0x58000
	s_nop 0
	v_addc_co_u32_e32 v3, vcc, 0, v67, vcc
	global_load_dword v51, v[2:3], off offset:2048
	v_add_co_u32_e32 v2, vcc, s10, v66
	s_mov_b32 s10, 0x5d000
	s_nop 0
	v_addc_co_u32_e32 v3, vcc, 0, v67, vcc
	global_load_dword v48, v[2:3], off
	v_add_co_u32_e32 v2, vcc, s10, v66
	s_mov_b32 s10, 0x63000
	s_nop 0
	v_addc_co_u32_e32 v3, vcc, 0, v67, vcc
	global_load_dword v49, v[2:3], off offset:2048
	v_add_co_u32_e32 v2, vcc, s10, v66
	s_mov_b32 s10, 0x68000
	s_nop 0
	v_addc_co_u32_e32 v3, vcc, 0, v67, vcc
	global_load_dword v52, v[2:3], off
	v_add_co_u32_e32 v2, vcc, s10, v66
	s_mov_b32 s10, 0x6e000
	s_nop 0
	v_addc_co_u32_e32 v3, vcc, 0, v67, vcc
	global_load_dword v53, v[2:3], off offset:2048
	v_add_co_u32_e32 v2, vcc, s10, v66
	s_mov_b32 s10, 0x73000
	s_nop 0
	v_addc_co_u32_e32 v3, vcc, 0, v67, vcc
	global_load_dword v38, v[2:3], off
	v_add_co_u32_e32 v2, vcc, s10, v66
	s_mov_b32 s10, 0x79000
	s_nop 0
	v_addc_co_u32_e32 v3, vcc, 0, v67, vcc
	global_load_dword v39, v[2:3], off offset:2048
	v_add_co_u32_e32 v2, vcc, s10, v66
	s_mov_b32 s10, 0x7e000
	s_nop 0
	v_addc_co_u32_e32 v3, vcc, 0, v67, vcc
	global_load_dword v42, v[2:3], off
	v_add_co_u32_e32 v2, vcc, s10, v66
	s_mov_b32 s10, 0x84000
	s_nop 0
	v_addc_co_u32_e32 v3, vcc, 0, v67, vcc
	global_load_dword v43, v[2:3], off offset:2048
	v_add_co_u32_e32 v2, vcc, s10, v66
	s_mov_b32 s10, 0x89000
	s_nop 0
	v_addc_co_u32_e32 v3, vcc, 0, v67, vcc
	global_load_dword v40, v[2:3], off
	v_add_co_u32_e32 v2, vcc, s10, v66
	s_mov_b32 s10, 0x8f000
	s_nop 0
	v_addc_co_u32_e32 v3, vcc, 0, v67, vcc
	global_load_dword v41, v[2:3], off offset:2048
	v_add_co_u32_e32 v2, vcc, s10, v66
	s_mov_b32 s10, 0x94000
	s_nop 0
	v_addc_co_u32_e32 v3, vcc, 0, v67, vcc
	global_load_dword v46, v[2:3], off
	v_add_co_u32_e32 v2, vcc, s10, v66
	s_mov_b32 s10, 0x9a000
	s_nop 0
	v_addc_co_u32_e32 v3, vcc, 0, v67, vcc
	global_load_dword v47, v[2:3], off offset:2048
	v_add_co_u32_e32 v2, vcc, s10, v66
	s_mov_b32 s10, 0x9f000
	s_nop 0
	v_addc_co_u32_e32 v3, vcc, 0, v67, vcc
	global_load_dword v30, v[2:3], off
	v_add_co_u32_e32 v2, vcc, s10, v66
	s_mov_b32 s10, 0xa5000
	s_nop 0
; __device__ __forceinline__ void transpose_item(const float* W, int K, int N, bf16_t* WT, const float* gk, int mode, LAS float* scr_, int item, int lane) {
;     ...
;     float va[32], vb[32];
; #pragma unroll
;     for (int kp = 0; kp < 32; ++kp) { va[kp] = src[(size_t)(2 * kp) * N]; vb[kp] = src[(size_t)(2 * kp + 1) * N]; }
; #pragma unroll
;     for (int kp = 0; kp < 32; ++kp) {
;         float a = va[kp], b = vb[kp];
;         if (gk) { a *= gk[k0 + 2 * kp]; b *= gk[k0 + 2 * kp + 1]; }
	v_addc_co_u32_e32 v3, vcc, 0, v67, vcc
	global_load_dword v31, v[2:3], off offset:2048
	v_add_co_u32_e32 v2, vcc, s10, v66
	s_mov_b32 s10, 0xaa000
	s_nop 0
	v_addc_co_u32_e32 v3, vcc, 0, v67, vcc
	global_load_dword v36, v[2:3], off
	v_add_co_u32_e32 v2, vcc, s10, v66
	s_mov_b32 s10, 0xb5000
	s_nop 0
	v_addc_co_u32_e32 v3, vcc, 0, v67, vcc
	global_load_dword v37, v[2:3], off offset:2048
	v_add_co_u32_e32 v2, vcc, s95, v66
	s_nop 1
	v_addc_co_u32_e32 v3, vcc, 0, v67, vcc
	global_load_dword v32, v[2:3], off
	v_add_co_u32_e32 v2, vcc, s10, v66
	s_mov_b32 s10, 0xbb000
	s_nop 0
	v_addc_co_u32_e32 v3, vcc, 0, v67, vcc
	global_load_dword v33, v[2:3], off offset:2048
	v_add_co_u32_e32 v2, vcc, s10, v66
	s_mov_b32 s10, 0xc0000
	s_nop 0
	v_addc_co_u32_e32 v3, vcc, 0, v67, vcc
	global_load_dword v34, v[2:3], off
	v_add_co_u32_e32 v2, vcc, s10, v66
	s_mov_b32 s10, 0xcb000
	s_nop 0
	v_addc_co_u32_e32 v3, vcc, 0, v67, vcc
	global_load_dword v35, v[2:3], off offset:2048
	v_add_co_u32_e32 v2, vcc, s89, v66
	s_nop 1
	v_addc_co_u32_e32 v3, vcc, 0, v67, vcc
	global_load_dword v20, v[2:3], off
	v_add_co_u32_e32 v2, vcc, s10, v66
	s_mov_b32 s10, 0xd1000
	s_nop 0
	v_addc_co_u32_e32 v3, vcc, 0, v67, vcc
	global_load_dword v21, v[2:3], off offset:2048
	v_add_co_u32_e32 v2, vcc, s10, v66
	s_mov_b32 s10, 0xd6000
	s_nop 0
	v_addc_co_u32_e32 v3, vcc, 0, v67, vcc
	global_load_dword v26, v[2:3], off
	v_add_co_u32_e32 v2, vcc, s10, v66
	s_mov_b32 s10, 0xdc000
	s_nop 0
	v_addc_co_u32_e32 v3, vcc, 0, v67, vcc
	global_load_dword v27, v[2:3], off offset:2048
	v_add_co_u32_e32 v2, vcc, s10, v66
	s_mov_b32 s10, 0xe1000
	s_nop 0
	v_addc_co_u32_e32 v3, vcc, 0, v67, vcc
	global_load_dword v24, v[2:3], off
	v_add_co_u32_e32 v2, vcc, s10, v66
	s_mov_b32 s10, 0xe7000
	s_nop 0
	v_addc_co_u32_e32 v3, vcc, 0, v67, vcc
	global_load_dword v25, v[2:3], off offset:2048
	v_add_co_u32_e32 v2, vcc, s10, v66
	s_mov_b32 s10, 0xec000
	s_nop 0
	v_addc_co_u32_e32 v3, vcc, 0, v67, vcc
	global_load_dword v28, v[2:3], off
	v_add_co_u32_e32 v2, vcc, s10, v66
	s_mov_b32 s10, 0xf2000
	s_nop 0
	v_addc_co_u32_e32 v3, vcc, 0, v67, vcc
	global_load_dword v29, v[2:3], off offset:2048
	v_add_co_u32_e32 v2, vcc, s10, v66
	s_mov_b32 s10, 0xf7000
	s_nop 0
	v_addc_co_u32_e32 v3, vcc, 0, v67, vcc
	global_load_dword v12, v[2:3], off
	v_add_co_u32_e32 v2, vcc, s10, v66
	s_mov_b32 s10, 0xfd000
	s_nop 0
	v_addc_co_u32_e32 v3, vcc, 0, v67, vcc
	global_load_dword v13, v[2:3], off offset:2048
	v_add_co_u32_e32 v2, vcc, s10, v66
	s_mov_b32 s10, 0x102000
	s_nop 0
	v_addc_co_u32_e32 v3, vcc, 0, v67, vcc
	global_load_dword v18, v[2:3], off
	v_add_co_u32_e32 v2, vcc, s10, v66
	s_mov_b32 s10, 0x108000
	s_nop 0
	v_addc_co_u32_e32 v3, vcc, 0, v67, vcc
	global_load_dword v19, v[2:3], off offset:2048
	v_add_co_u32_e32 v2, vcc, s10, v66
	s_mov_b32 s10, 0x10d000
	s_nop 0
	v_addc_co_u32_e32 v3, vcc, 0, v67, vcc
	global_load_dword v16, v[2:3], off
	v_add_co_u32_e32 v2, vcc, s10, v66
	s_mov_b32 s10, 0x113000
	s_nop 0
	v_addc_co_u32_e32 v3, vcc, 0, v67, vcc
	global_load_dword v17, v[2:3], off offset:2048
	v_add_co_u32_e32 v2, vcc, s10, v66
	s_mov_b32 s10, 0x118000
	s_nop 0
	v_addc_co_u32_e32 v3, vcc, 0, v67, vcc
	global_load_dword v22, v[2:3], off
	v_add_co_u32_e32 v2, vcc, s10, v66
	s_mov_b32 s10, 0x11e000
	s_nop 0
	v_addc_co_u32_e32 v3, vcc, 0, v67, vcc
	global_load_dword v23, v[2:3], off offset:2048
	v_add_co_u32_e32 v2, vcc, s10, v66
	s_mov_b32 s10, 0x123000
	s_nop 0
	v_addc_co_u32_e32 v3, vcc, 0, v67, vcc
	global_load_dword v4, v[2:3], off
	v_add_co_u32_e32 v2, vcc, s10, v66
	s_mov_b32 s10, 0x129000
	s_nop 0
	v_addc_co_u32_e32 v3, vcc, 0, v67, vcc
	global_load_dword v5, v[2:3], off offset:2048
	v_add_co_u32_e32 v2, vcc, s10, v66
	s_mov_b32 s10, 0x12e000
	s_nop 0
	v_addc_co_u32_e32 v3, vcc, 0, v67, vcc
	global_load_dword v10, v[2:3], off
	v_add_co_u32_e32 v2, vcc, s10, v66
	s_mov_b32 s10, 0x134000
	s_nop 0
	v_addc_co_u32_e32 v3, vcc, 0, v67, vcc
	global_load_dword v11, v[2:3], off offset:2048
	v_add_co_u32_e32 v2, vcc, s10, v66
	s_mov_b32 s10, 0x139000
	s_nop 0
	v_addc_co_u32_e32 v3, vcc, 0, v67, vcc
	global_load_dword v6, v[2:3], off
	v_add_co_u32_e32 v2, vcc, s10, v66
	s_mov_b32 s10, 0x13f000
	s_nop 0
	v_addc_co_u32_e32 v3, vcc, 0, v67, vcc
	global_load_dword v7, v[2:3], off offset:2048
	v_add_co_u32_e32 v2, vcc, s10, v66
	s_mov_b32 s10, 0x144000
	s_nop 0
	v_addc_co_u32_e32 v3, vcc, 0, v67, vcc
	global_load_dword v14, v[2:3], off
	v_add_co_u32_e32 v2, vcc, s10, v66
	s_mov_b32 s10, 0x14a000
	s_nop 0
	v_addc_co_u32_e32 v3, vcc, 0, v67, vcc
	global_load_dword v15, v[2:3], off offset:2048
	v_add_co_u32_e32 v2, vcc, s10, v66
	s_mov_b32 s10, 0x14f000
	s_nop 0
	v_addc_co_u32_e32 v3, vcc, 0, v67, vcc
	v_add_co_u32_e32 v8, vcc, s10, v66
	global_load_dword v2, v[2:3], off
	s_nop 0
	v_addc_co_u32_e32 v9, vcc, 0, v67, vcc
	global_load_dword v3, v[8:9], off offset:2048
	v_add_co_u32_e32 v8, vcc, 0x155000, v66
	s_cselect_b64 s[10:11], -1, 0
	s_nop 0
	v_addc_co_u32_e32 v9, vcc, 0, v67, vcc
	v_add_co_u32_e32 v66, vcc, 0x15a000, v66
	global_load_dword v8, v[8:9], off
	s_nop 0
	v_addc_co_u32_e32 v67, vcc, 0, v67, vcc
	global_load_dword v9, v[66:67], off offset:2048
	s_cmp_eq_u64 s[4:5], 0
	s_cbranch_scc1 .LBB0_1985
	s_lshl_b64 s[4:5], s[8:9], 2
	s_add_u32 s4, s25, s4
	s_addc_u32 s5, s29, s5
	global_load_dwordx4 v[66:69], v161, s[4:5]
	s_mov_b64 s[12:13], 0
	s_waitcnt vmcnt(0)
	v_pk_mul_f32 v[66:67], v[62:63], v[66:67]
	v_pk_mul_f32 v[68:69], v[64:65], v[68:69]

; #define PG8_STAGE(bufoff, gbase, voff) do { _Pragma("unroll") for (int _i = 0; _i < 2; ++_i) \
;         __builtin_amdgcn_global_load_lds((const unsigned*)((const char*)(gbase) + (voff)[_i]), (PG8_LAS unsigned*)(lds + (bufoff) + ldsw + _i * 8192), 16, 0, 0); } while (0)
; #define PG8_WAIT_V(n) asm volatile("s_waitcnt vmcnt(" #n ")" ::: "memory")
; #define PG8_BAR __builtin_amdgcn_s_barrier()
; template <class Epi, class Sched, bool ALIGN_EPI = false, bool SP2 = false>
; __device__ __forceinline__ void gemm_phase(PG8_LAS unsigned char* lds, const Gemm g, const Sched& S, const Epi& E, int wv) {
;     ...
;     const int tid = tid_, wid = __builtin_amdgcn_readfirstlane(tid >> 6), lane = tid & 63, wr = wid >> 2, wc = wid & 3, fr = lane & 15, fq = lane >> 4;
;     const int K = g.K, nt = K / BK;
;     unsigned voffA[2], voffB[2];
; #pragma unroll
;     for (int i = 0; i < 2; ++i) { int R, C; stage_rc(tid * 16 + i * 8192, R, C); const int Rb = Epi::PERM ? ((R & ~31) + perm32(R & 31)) : R;
;         voffA[i] = (unsigned)(R * K + C) * 2u; voffB[i] = (unsigned)(Rb * K + C) * 2u; }
;     const size_t kstep = (size_t)(BK * 2);
;     const size_t hstep = (size_t)HALF * K * 2;
;     const size_t tstep = 2 * hstep;
;     const unsigned ldsw = (unsigned)wid * 1024u;
;     const int aoff = lds_byte(wr * 64 + fr, fq * 8), boff = lds_byte(wc * 32 + fr, fq * 8);
;     ...
;     Unit cur, nxt; int ui = 0;
;     if (!S.next(0, cur)) return;
;     f32x4 acc[2][2][4][2];
; #pragma unroll
;     for (int a = 0; a < 2; ++a)
; #pragma unroll
;         for (int b = 0; b < 2; ++b)
; #pragma unroll
;             for (int m = 0; m < 4; ++m)
; #pragma unroll
;                 for (int n = 0; n < 2; ++n) acc[a][b][m][n] = (f32x4){0.f, 0.f, 0.f, 0.f};
;     bf16x8 At[4][2], B0[2][2], B1[2][2];
;     const char* cA = (const char*)g.A + (size_t)cur.pm * tstep; const char* cB = (const char*)g.Bt + (size_t)cur.pn * tstep;
;     S.a_ready(cur);
;     if constexpr (SP2) {
;         PG8_STAGE(PG8_SB(0, 0), cB, voffB); PG8_STAGE(PG8_SB(0, 1), cB + hstep, voffB); PG8_STAGE(PG8_SA(0, 0), cA, voffA); PG8_STAGE(PG8_SA(0, 1), cA + hstep, voffA);
;         if (wr == 1) PG8_BAR;
;         PG8_WAIT_V(2); PG8_BAR;
;         PG8_STAGE(PG8_SB(1, 0), cB + kstep, voffB); PG8_STAGE(PG8_SA(1, 0), cA + kstep, voffA); PG8_STAGE(PG8_SB(1, 1), cB + hstep + kstep, voffB);
.LBB0_2099:
	s_or_b64 exec, exec, s[4:5]
	v_readlane_b32 s8, v250, 0
	s_mov_b64 s[4:5], 0
	s_waitcnt lgkmcnt(0)
	v_mov_b32_e32 v0, v161
	s_barrier
	v_readlane_b32 s10, v250, 33
	v_add_u32_e32 v0, 0, v0
	v_add_u32_e32 v0, 0x201c0, v0
	s_nop 0
	v_mov_b32_e32 v14, v183
	v_readlane_b32 s11, v250, 34
	s_and_b64 vcc, exec, s[10:11]
	s_waitcnt lgkmcnt(0)
	v_readlane_b32 s6, v251, 48
	v_mov_b32_e32 v0, v161
	v_readlane_b32 s7, v251, 49
	v_add_u32_e32 v0, 0, v0
	v_add_u32_e32 v0, 0x201c8, v0
	ds_read_b64 v[0:1], v0
	s_nop 0
	v_readfirstlane_b32 s10, v14
	s_cbranch_vccnz .LBB0_2115
	s_waitcnt lgkmcnt(0)
	v_lshlrev_b32_e32 v0, 4, v14
	v_add_u32_e32 v1, 0x2000, v0
	v_ashrrev_i32_e32 v2, 31, v1
	v_lshrrev_b32_e32 v2, 22, v2
	v_add_u32_e32 v2, v1, v2
	v_ashrrev_i32_e32 v8, 10, v2
	v_mul_i32_i24_e32 v2, 0x400, v8
	v_sub_u32_e32 v1, v1, v2
	v_lshrrev_b32_e32 v2, 4, v1
	v_bitop3_b32 v1, v2, v1, 32 bitop3:0x6c
	s_add_u32 s6, s6, s4
	v_ashrrev_i32_e32 v2, 31, v1
	s_addc_u32 s7, s7, s5
	v_lshrrev_b32_e32 v2, 26, v2
	s_add_u32 s14, s6, 0x5200000
	v_add_u32_e32 v2, v1, v2
	v_lshlrev_b32_e32 v3, 3, v8
	s_addc_u32 s15, s7, 0
	s_mul_i32 s5, s8, 0x2900000
	v_ashrrev_i32_e32 v9, 6, v2
	v_and_b32_e32 v3, -16, v3
	s_mul_hi_i32 s4, s8, 0x2900000
	s_add_u32 s9, s6, s5
	v_add_u32_e32 v3, v9, v3
	s_addc_u32 s13, s7, s4
	v_and_b32_e32 v4, 3, v9
	s_mov_b32 s4, 0x1fffe0
	v_lshrrev_b32_e32 v5, 2, v3
	v_lshlrev_b32_e32 v6, 1, v3
	v_and_b32_e32 v2, 0xc0, v2
	v_and_or_b32 v4, v3, s4, v4
	v_and_b32_e32 v5, 4, v5
	v_and_b32_e32 v6, 24, v6
	v_sub_u32_e32 v1, v1, v2
	v_or3_b32 v4, v4, v5, v6
	v_lshlrev_b32_e32 v5, 5, v8
	v_ashrrev_i16_sdwa v1, v193, sext(v1) dst_sel:DWORD dst_unused:UNUSED_PAD src0_sel:DWORD src1_sel:BYTE_0
	v_and_b32_e32 v5, 32, v5
	v_bfe_i32 v10, v1, 0, 16
	v_add_lshl_u32 v1, v5, v10, 1
	v_lshl_add_u32 v128, v4, 11, v1
	v_lshl_add_u32 v130, v3, 11, v1
	v_bfe_i32 v1, v14, 27, 1
	v_lshrrev_b32_e32 v1, 22, v1
	v_add_u32_e32 v1, v0, v1
	v_and_b32_e32 v1, 0xfffffc00, v1
	v_sub_u32_e32 v0, v0, v1
	v_lshrrev_b32_e32 v1, 4, v0
	v_ashrrev_i32_e32 v2, 31, v14
	v_bitop3_b32 v0, v1, v0, 32 bitop3:0x6c
	v_lshrrev_b32_e32 v2, 26, v2
	v_ashrrev_i32_e32 v1, 31, v0
	v_add_u32_e32 v2, v14, v2
	v_lshrrev_b32_e32 v1, 26, v1
	v_ashrrev_i32_e32 v12, 6, v2
	v_add_u32_e32 v1, v0, v1
	v_lshlrev_b32_e32 v2, 3, v12
	v_ashrrev_i32_e32 v11, 6, v1
	v_and_b32_e32 v2, -16, v2
	v_add_u32_e32 v2, v11, v2
	s_add_u32 s16, s9, 0x1500000
	v_and_b32_e32 v3, 3, v11
	v_lshrrev_b32_e32 v4, 2, v2
	v_lshlrev_b32_e32 v5, 1, v2
	v_and_b32_e32 v1, 0xc0, v1
	s_addc_u32 s29, s13, 0
	s_ashr_i32 s11, s10, 6
	v_and_or_b32 v3, v2, s4, v3
	v_and_b32_e32 v4, 4, v4
	v_and_b32_e32 v5, 24, v5
	v_sub_u32_e32 v0, v0, v1
	s_ashr_i32 s12, s10, 8
	s_lshl_b32 s30, s11, 10
	v_or3_b32 v3, v3, v4, v5
	v_lshlrev_b32_e32 v4, 5, v12
	v_ashrrev_i16_sdwa v0, v193, sext(v0) dst_sel:DWORD dst_unused:UNUSED_PAD src0_sel:DWORD src1_sel:BYTE_0
	v_readlane_b32 s4, v250, 5
	v_and_b32_e32 v4, 32, v4
	v_bfe_i32 v13, v0, 0, 16
	v_readlane_b32 s5, v250, 6
	s_add_u32 s48, s16, s4
	v_add_lshl_u32 v0, v4, v13, 1
	s_addc_u32 s49, s29, s5
	s_add_i32 s31, s30, 0
	v_lshl_add_u32 v160, v3, 11, v0
	s_add_i32 m0, s31, 0x10000
	v_lshl_add_u32 v132, v2, 11, v0
	global_load_lds_dwordx4 v160, s[48:49]
	s_add_i32 m0, s31, 0x12000
	s_add_u32 s4, s48, 0x40000
	global_load_lds_dwordx4 v128, s[48:49]
	s_addc_u32 s5, s49, 0
	s_add_i32 m0, s31, 0x14000
	v_mov_b32_e32 v129, v161
	global_load_lds_dwordx4 v160, s[4:5]
	s_add_i32 m0, s31, 0x16000
	v_mov_b32_e32 v133, v161
	global_load_lds_dwordx4 v128, s[4:5]
	v_readlane_b32 s4, v250, 21
	v_readlane_b32 s5, v250, 22
	s_add_u32 s44, s14, s4
	s_addc_u32 s45, s15, s5
	s_add_i32 s52, s31, 0x2000
	s_mov_b32 m0, s31
	s_add_u32 s4, s44, 0x40000
	global_load_lds_dwordx4 v132, s[44:45]
	s_mov_b32 m0, s52
	s_addc_u32 s5, s45, 0
	s_add_i32 s53, s31, 0x4000
	global_load_lds_dwordx4 v130, s[44:45]
	s_mov_b32 m0, s53
	s_add_i32 s54, s31, 0x6000
	global_load_lds_dwordx4 v132, s[4:5]
	s_mov_b32 m0, s54
	v_mov_b32_e32 v131, v161
	global_load_lds_dwordx4 v130, s[4:5]
	s_cmp_eq_u32 s12, 1
	v_lshl_add_u64 v[6:7], s[48:49], 0, v[160:161]
	v_lshl_add_u64 v[4:5], s[48:49], 0, v[128:129]
	v_lshl_add_u64 v[0:1], s[44:45], 0, v[132:133]
	s_cselect_b64 s[4:5], -1, 0
	s_cmp_lg_u32 s12, 1
	v_lshl_add_u64 v[2:3], s[44:45], 0, v[130:131]
	s_cbranch_scc1 .LBB0_2102
	s_barrier

; #define PG8_STAGE(bufoff, gbase, voff) do { _Pragma("unroll") for (int _i = 0; _i < 2; ++_i) \
;         __builtin_amdgcn_global_load_lds((const unsigned*)((const char*)(gbase) + (voff)[_i]), (PG8_LAS unsigned*)(lds + (bufoff) + ldsw + _i * 8192), 16, 0, 0); } while (0)
; #define PG8_WAIT_V(n) asm volatile("s_waitcnt vmcnt(" #n ")" ::: "memory")
; #define PG8_BAR __builtin_amdgcn_s_barrier()
; template <class Epi, class Sched, bool ALIGN_EPI = false, bool SP2 = false>
; __device__ __forceinline__ void gemm_phase(PG8_LAS unsigned char* lds, const Gemm g, const Sched& S, const Epi& E, int wv) {
;     ...
;     const int tid = tid_, wid = __builtin_amdgcn_readfirstlane(tid >> 6), lane = tid & 63, wr = wid >> 2, wc = wid & 3, fr = lane & 15, fq = lane >> 4;
;     const int K = g.K, nt = K / BK;
;     unsigned voffA[2], voffB[2];
; #pragma unroll
;     for (int i = 0; i < 2; ++i) { int R, C; stage_rc(tid * 16 + i * 8192, R, C); const int Rb = Epi::PERM ? ((R & ~31) + perm32(R & 31)) : R;
;         voffA[i] = (unsigned)(R * K + C) * 2u; voffB[i] = (unsigned)(Rb * K + C) * 2u; }
;     const size_t kstep = (size_t)(BK * 2);
;     const size_t hstep = (size_t)HALF * K * 2;
;     const size_t tstep = 2 * hstep;
;     const unsigned ldsw = (unsigned)wid * 1024u;
;     const int aoff = lds_byte(wr * 64 + fr, fq * 8), boff = lds_byte(wc * 32 + fr, fq * 8);
;     ...
;     Unit cur, nxt; int ui = 0;
;     if (!S.next(0, cur)) return;
;     f32x4 acc[2][2][4][2];
; #pragma unroll
;     for (int a = 0; a < 2; ++a)
; #pragma unroll
;         for (int b = 0; b < 2; ++b)
; #pragma unroll
;             for (int m = 0; m < 4; ++m)
; #pragma unroll
;                 for (int n = 0; n < 2; ++n) acc[a][b][m][n] = (f32x4){0.f, 0.f, 0.f, 0.f};
;     bf16x8 At[4][2], B0[2][2], B1[2][2];
;     const char* cA = (const char*)g.A + (size_t)cur.pm * tstep; const char* cB = (const char*)g.Bt + (size_t)cur.pn * tstep;
;     S.a_ready(cur);
;     if constexpr (SP2) {
;         PG8_STAGE(PG8_SB(0, 0), cB, voffB); PG8_STAGE(PG8_SB(0, 1), cB + hstep, voffB); PG8_STAGE(PG8_SA(0, 0), cA, voffA); PG8_STAGE(PG8_SA(0, 1), cA + hstep, voffA);
;         if (wr == 1) PG8_BAR;
;         PG8_WAIT_V(2); PG8_BAR;
;         PG8_STAGE(PG8_SB(1, 0), cB + kstep, voffB); PG8_STAGE(PG8_SA(1, 0), cA + kstep, voffA); PG8_STAGE(PG8_SB(1, 1), cB + hstep + kstep, voffB);
.LBB0_2167:
	s_or_b64 exec, exec, s[4:5]
	v_readlane_b32 s12, v250, 0
	s_mov_b64 s[4:5], 0
	s_waitcnt lgkmcnt(0)
	v_mov_b32_e32 v0, v161
	s_barrier
	v_readlane_b32 s8, v250, 42
	v_add_u32_e32 v0, 0, v0
	v_add_u32_e32 v0, 0x201c0, v0
	s_nop 0
	v_mov_b32_e32 v16, v183
	v_readlane_b32 s9, v250, 43
	s_and_b64 vcc, exec, s[8:9]
	s_waitcnt lgkmcnt(0)
	v_readlane_b32 s7, v251, 48
	v_mov_b32_e32 v0, v161
	v_readlane_b32 s6, v251, 49
	v_add_u32_e32 v0, 0, v0
	v_add_u32_e32 v0, 0x201c8, v0
	ds_read_b64 v[0:1], v0
	s_nop 0
	v_readfirstlane_b32 s18, v16
	s_cbranch_vccnz .LBB0_2203
	s_waitcnt lgkmcnt(0)
	v_lshlrev_b32_e32 v0, 4, v16
	v_add_u32_e32 v1, 0x2000, v0
	v_ashrrev_i32_e32 v2, 31, v1
	v_lshrrev_b32_e32 v2, 22, v2
	v_add_u32_e32 v2, v1, v2
	v_ashrrev_i32_e32 v8, 10, v2
	v_mul_i32_i24_e32 v2, 0x400, v8
	v_sub_u32_e32 v1, v1, v2
	v_lshrrev_b32_e32 v2, 4, v1
	v_bitop3_b32 v1, v2, v1, 32 bitop3:0x6c
	v_ashrrev_i32_e32 v2, 31, v1
	v_lshrrev_b32_e32 v2, 26, v2
	v_add_u32_e32 v2, v1, v2
	v_lshlrev_b32_e32 v3, 3, v8
	v_ashrrev_i32_e32 v9, 6, v2
	v_and_b32_e32 v3, -16, v3
	s_add_u32 s10, s7, s4
	v_add_u32_e32 v3, v9, v3
	s_addc_u32 s11, s6, s5
	v_and_b32_e32 v4, 3, v9
	s_mov_b32 s6, 0xffffe0
	v_lshrrev_b32_e32 v5, 2, v3
	v_lshlrev_b32_e32 v6, 1, v3
	v_and_b32_e32 v2, 0xc0, v2
	v_and_or_b32 v4, v3, s6, v4
	v_and_b32_e32 v5, 4, v5
	v_and_b32_e32 v6, 24, v6
	v_sub_u32_e32 v1, v1, v2
	v_or3_b32 v4, v4, v5, v6
	v_lshlrev_b32_e32 v5, 5, v8
	v_ashrrev_i16_sdwa v1, v193, sext(v1) dst_sel:DWORD dst_unused:UNUSED_PAD src0_sel:DWORD src1_sel:BYTE_0
	v_and_b32_e32 v10, 32, v5
	v_bfe_i32 v11, v1, 0, 16
	s_movk_i32 s7, 0xb00
	v_mul_u32_u24_e32 v4, 0xb00, v4
	v_add_u32_e32 v1, v10, v11
	v_mul_lo_u32 v2, v3, s7
	v_add_lshl_u32 v152, v4, v1, 1
	v_add_lshl_u32 v154, v1, v2, 1
	v_bfe_i32 v1, v16, 27, 1
	v_lshrrev_b32_e32 v1, 22, v1
	v_add_u32_e32 v1, v0, v1
	v_and_b32_e32 v1, 0xfffffc00, v1
	v_sub_u32_e32 v0, v0, v1
	v_lshrrev_b32_e32 v1, 4, v0
	v_ashrrev_i32_e32 v2, 31, v16
	v_bitop3_b32 v0, v1, v0, 32 bitop3:0x6c
	v_lshrrev_b32_e32 v2, 26, v2
	v_ashrrev_i32_e32 v1, 31, v0
	v_add_u32_e32 v2, v16, v2
	s_add_u32 s14, s10, 0xd600000
	v_lshrrev_b32_e32 v1, 26, v1
	v_ashrrev_i32_e32 v13, 6, v2
	s_addc_u32 s15, s11, 0
	s_mul_i32 s5, s12, 0x2900000
	v_add_u32_e32 v1, v0, v1
	v_lshlrev_b32_e32 v2, 3, v13
	s_mul_hi_i32 s4, s12, 0x2900000
	s_add_u32 s13, s10, s5
	v_ashrrev_i32_e32 v12, 6, v1
	v_and_b32_e32 v2, -16, v2
	s_addc_u32 s19, s11, s4
	v_add_u32_e32 v2, v12, v2
	s_add_u32 s16, s13, 0x2000000
	v_and_b32_e32 v3, 3, v12
	v_lshrrev_b32_e32 v4, 2, v2
	v_lshlrev_b32_e32 v5, 1, v2
	v_and_b32_e32 v1, 0xc0, v1
	s_addc_u32 s29, s19, 0
	s_ashr_i32 s4, s18, 6
	v_and_or_b32 v3, v2, s6, v3
	v_and_b32_e32 v4, 4, v4
	v_and_b32_e32 v5, 24, v5
	v_sub_u32_e32 v0, v0, v1
	s_ashr_i32 s5, s18, 8
	s_lshl_b32 s30, s4, 10
	v_or3_b32 v3, v3, v4, v5
	v_lshlrev_b32_e32 v4, 5, v13
	v_ashrrev_i16_sdwa v0, v193, sext(v0) dst_sel:DWORD dst_unused:UNUSED_PAD src0_sel:DWORD src1_sel:BYTE_0
	v_readlane_b32 s6, v250, 14
	v_and_b32_e32 v14, 32, v4
	v_bfe_i32 v15, v0, 0, 16
	s_add_u32 s42, s16, s6
	v_readlane_b32 s6, v250, 12
	v_mul_u32_u24_e32 v3, 0xb00, v3
	v_add_u32_e32 v0, v14, v15
	s_addc_u32 s43, s29, s6
	s_add_i32 s31, s30, 0
	v_add_lshl_u32 v160, v3, v0, 1
	s_add_i32 m0, s31, 0x10000
	v_mul_lo_u32 v1, v2, s7
	global_load_lds_dwordx4 v160, s[42:43]
	s_add_i32 m0, s31, 0x12000
	s_add_u32 s6, s42, 0xb0000
	global_load_lds_dwordx4 v152, s[42:43]
	s_addc_u32 s7, s43, 0
	s_add_i32 m0, s31, 0x14000
	v_add_lshl_u32 v156, v0, v1, 1
	global_load_lds_dwordx4 v160, s[6:7]
	s_add_i32 m0, s31, 0x16000
	v_mov_b32_e32 v153, v161
	global_load_lds_dwordx4 v152, s[6:7]
	v_readlane_b32 s6, v250, 11
	s_add_u32 s6, s14, s6
	v_readlane_b32 s7, v250, 10
	s_addc_u32 s7, s15, s7
	s_add_i32 s50, s31, 0x2000
	s_mov_b32 m0, s31
	s_add_u32 s8, s6, 0xb0000
	s_addc_u32 s9, s7, 0
	global_load_lds_dwordx4 v156, s[6:7]
	s_mov_b32 m0, s50
	s_add_i32 s51, s31, 0x4000
	global_load_lds_dwordx4 v154, s[6:7]
	s_mov_b32 m0, s51
	s_add_i32 s52, s31, 0x6000
	global_load_lds_dwordx4 v156, s[8:9]
	s_mov_b32 m0, s52
	v_mov_b32_e32 v157, v161
	global_load_lds_dwordx4 v154, s[8:9]
	v_mov_b32_e32 v155, v161
	s_cmp_eq_u32 s5, 1
	v_lshl_add_u64 v[6:7], s[42:43], 0, v[160:161]
	v_lshl_add_u64 v[4:5], s[42:43], 0, v[152:153]
	v_lshl_add_u64 v[0:1], s[6:7], 0, v[156:157]
	s_cselect_b64 s[8:9], -1, 0
	s_cmp_lg_u32 s5, 1
	v_lshl_add_u64 v[2:3], s[6:7], 0, v[154:155]
	s_cbranch_scc1 .LBB0_2170
	s_barrier

; #define PG8_BAR __builtin_amdgcn_s_barrier()
; template <class Epi, class Sched, bool ALIGN_EPI = false, bool SP2 = false>
; __device__ __forceinline__ void gemm_phase(PG8_LAS unsigned char* lds, const Gemm g, const Sched& S, const Epi& E, int wv) {
;     ...
;     const int tid = tid_, wid = __builtin_amdgcn_readfirstlane(tid >> 6), lane = tid & 63, wr = wid >> 2, wc = wid & 3, fr = lane & 15, fq = lane >> 4;
;     const int K = g.K, nt = K / BK;
;     unsigned voffA[2], voffB[2];
; #pragma unroll
;     for (int i = 0; i < 2; ++i) { int R, C; stage_rc(tid * 16 + i * 8192, R, C); const int Rb = Epi::PERM ? ((R & ~31) + perm32(R & 31)) : R;
;         voffA[i] = (unsigned)(R * K + C) * 2u; voffB[i] = (unsigned)(Rb * K + C) * 2u; }
;     const size_t kstep = (size_t)(BK * 2);
;     const size_t hstep = (size_t)HALF * K * 2;
;     const size_t tstep = 2 * hstep;
;     const unsigned ldsw = (unsigned)wid * 1024u;
;     const int aoff = lds_byte(wr * 64 + fr, fq * 8), boff = lds_byte(wc * 32 + fr, fq * 8);
;     ...
;     Unit cur, nxt; int ui = 0;
;     if (!S.next(0, cur)) return;
;     f32x4 acc[2][2][4][2];
; #pragma unroll
;     for (int a = 0; a < 2; ++a)
; #pragma unroll
;         for (int b = 0; b < 2; ++b)
; #pragma unroll
;             for (int m = 0; m < 4; ++m)
; #pragma unroll
;                 for (int n = 0; n < 2; ++n) acc[a][b][m][n] = (f32x4){0.f, 0.f, 0.f, 0.f};
;     bf16x8 At[4][2], B0[2][2], B1[2][2];
;     const char* cA = (const char*)g.A + (size_t)cur.pm * tstep; const char* cB = (const char*)g.Bt + (size_t)cur.pn * tstep;
;     S.a_ready(cur);
;     if constexpr (SP2) {
;         PG8_STAGE(PG8_SB(0, 0), cB, voffB); PG8_STAGE(PG8_SB(0, 1), cB + hstep, voffB); PG8_STAGE(PG8_SA(0, 0), cA, voffA); PG8_STAGE(PG8_SA(0, 1), cA + hstep, voffA);
;         if (wr == 1) PG8_BAR;
;         PG8_WAIT_V(2); PG8_BAR;
; __global__ void __launch_bounds__(512, 2) hymba_fwd(Params p) {
;     ...
;         int Gf = G, cf = c; asm volatile("" : "+s"(Gf), "+s"(cf));
;         if (Gf == 256 ? cf >= 32 : true) { PHASE_VARS pg8::Gemm g{(const bf16_t*)(ws + WS_PB) + (size_t)ly * MT * PED, (const bf16_t*)(wl + WL_PEU), MT, DM, PED}; pg8::StaticOrder S;
;           if (Gf == 256) S.init(MT, DM, 224, cf - 32); else S.init(MT, DM, Gf, cf);
;           EpiStore E{(bf16_t*)(ws + WS_U2), DM, nullptr};
;           pg8::gemm_phase<EpiStore, pg8::StaticOrder, true, true>(L, g, S, E, wv); }
.LBB0_2203:
	s_mov_b32 s12, s20
	s_mov_b32 s9, s2
	s_cmpk_lg_i32 s12, 0x100
	s_cselect_b64 s[4:5], -1, 0
	s_cmp_gt_i32 s9, 31
	s_cselect_b64 s[6:7], -1, 0
	s_or_b64 s[4:5], s[4:5], s[6:7]
	s_andn2_b64 vcc, exec, s[4:5]
	s_cbranch_vccnz .LBB0_2220
	v_readlane_b32 s8, v250, 0
	s_mov_b64 s[4:5], 0
	s_waitcnt lgkmcnt(0)
	v_mov_b32_e32 v0, v161
	s_sub_i32 s13, s9, 32
	v_add_u32_e32 v0, 0, v0
	v_add_u32_e32 v0, 0x201c0, v0
	s_nop 0
	s_cmpk_eq_i32 s12, 0x100
	s_cselect_b64 s[6:7], -1, 0
	s_and_b64 s[14:15], s[6:7], exec
	s_cselect_b32 s14, s13, s9
	s_waitcnt lgkmcnt(0)
	v_readlane_b32 s11, v251, 48
	v_mov_b32_e32 v0, v161
	v_readlane_b32 s10, v251, 49
	v_add_u32_e32 v0, 0, v0
	v_add_u32_e32 v0, 0x201c8, v0
	ds_read_b64 v[0:1], v0
	v_mov_b32_e32 v8, v183
	s_cmpk_gt_i32 s14, 0x41f
	v_readfirstlane_b32 s9, v8
	s_cbranch_scc1 .LBB0_2220
	s_waitcnt lgkmcnt(0)
	v_lshlrev_b32_e32 v0, 4, v8
	v_add_u32_e32 v1, 0x2000, v0
	v_ashrrev_i32_e32 v2, 31, v1
	v_lshrrev_b32_e32 v2, 22, v2
	v_add_u32_e32 v2, v1, v2
	v_ashrrev_i32_e32 v2, 10, v2
	s_add_u32 s18, s11, s4
	v_mul_i32_i24_e32 v3, 0x400, v2
	s_addc_u32 s19, s10, s5
	s_mul_i32 s5, s8, 0x2900000
	v_sub_u32_e32 v1, v1, v3
	s_mul_hi_i32 s4, s8, 0x2900000
	s_add_u32 s5, s18, s5
	v_lshrrev_b32_e32 v3, 4, v1
	s_addc_u32 s4, s19, s4
	s_mul_hi_i32 s10, s8, 0x2100000
	s_mul_i32 s8, s8, 0x2100000
	v_bitop3_b32 v1, v3, v1, 32 bitop3:0x6c
	s_add_u32 s8, s18, s8
	v_ashrrev_i32_e32 v3, 31, v1
	s_addc_u32 s10, s19, s10
	v_lshrrev_b32_e32 v3, 26, v3
	s_add_u32 s15, s8, 0x24100000
	v_add_u32_e32 v3, v1, v3
	v_lshlrev_b32_e32 v5, 3, v2
	s_addc_u32 s16, s10, 0
	v_ashrrev_i32_e32 v4, 6, v3
	v_and_b32_e32 v5, -16, v5
	v_and_b32_e32 v3, 0xc0, v3
	s_add_u32 s24, s5, 0x2780000
	v_add_u32_e32 v5, v4, v5
	v_sub_u32_e32 v1, v1, v3
	s_addc_u32 s25, s4, 0
	v_and_b32_e32 v4, 3, v4
	s_mov_b32 s4, 0x7fffe0
	v_lshrrev_b32_e32 v6, 2, v5
	v_lshlrev_b32_e32 v7, 1, v5
	v_lshlrev_b32_e32 v2, 5, v2
	v_ashrrev_i16_sdwa v1, v193, sext(v1) dst_sel:DWORD dst_unused:UNUSED_PAD src0_sel:DWORD src1_sel:BYTE_0
	v_and_or_b32 v4, v5, s4, v4
	v_and_b32_e32 v6, 4, v6
	v_and_b32_e32 v7, 24, v7
	v_and_b32_e32 v2, 32, v2
	v_bfe_i32 v1, v1, 0, 16
	v_or3_b32 v4, v4, v6, v7
	v_add_lshl_u32 v1, v2, v1, 1
	v_lshl_add_u32 v128, v4, 9, v1
	v_lshl_add_u32 v130, v5, 9, v1
	v_bfe_i32 v1, v8, 27, 1
	v_lshrrev_b32_e32 v1, 22, v1
	v_add_u32_e32 v1, v0, v1
	v_and_b32_e32 v1, 0xfffffc00, v1
	v_sub_u32_e32 v0, v0, v1
	v_lshrrev_b32_e32 v1, 4, v0
	v_ashrrev_i32_e32 v3, 31, v8
	v_bitop3_b32 v0, v1, v0, 32 bitop3:0x6c
	v_lshrrev_b32_e32 v3, 26, v3
	v_ashrrev_i32_e32 v1, 31, v0
	v_add_u32_e32 v3, v8, v3
	v_lshrrev_b32_e32 v1, 26, v1
	v_ashrrev_i32_e32 v3, 6, v3
	v_add_u32_e32 v1, v0, v1
	v_lshlrev_b32_e32 v4, 3, v3
	v_ashrrev_i32_e32 v2, 6, v1
	v_and_b32_e32 v4, -16, v4
	v_add_u32_e32 v4, v2, v4
	v_and_b32_e32 v2, 3, v2
	v_and_or_b32 v2, v4, s4, v2
	s_ashr_i32 s4, s14, 31
	s_lshr_b32 s4, s4, 29
	s_add_i32 s4, s14, s4
	s_ashr_i32 s13, s9, 6
	s_ashr_i32 s5, s4, 3
	s_and_b32 s4, s4, -8
	s_ashr_i32 s21, s9, 8
	s_lshl_b32 s29, s13, 10
	s_sub_i32 s4, s14, s4
	s_cmp_lt_i32 s4, 0
	s_cselect_b32 s8, s55, 0x84
	s_mul_i32 s4, s4, s8
	s_add_i32 s4, s4, s5
	s_ashr_i32 s5, s4, 31
	s_lshr_b32 s5, s5, 27
	s_add_i32 s5, s4, s5
	s_ashr_i32 s8, s5, 5
	s_and_b32 s5, s5, 0xffe0
	s_sub_i32 s4, s4, s5
	s_bfe_i32 s5, s4, 0x80000
	s_bfe_u32 s5, s5, 0x3000c
	s_add_i32 s5, s4, s5
	s_lshl_b32 s10, s8, 3
	s_bfe_i32 s8, s5, 0x80000
	s_and_b32 s5, s5, 0xf8
	s_sub_i32 s4, s4, s5
	s_sext_i32_i16 s8, s8
	s_sext_i32_i8 s4, s4
	v_and_b32_e32 v1, 0xc0, v1
	s_lshr_b32 s8, s8, 3
	s_add_i32 s10, s10, s4
	v_sub_u32_e32 v0, v0, v1
	s_ashr_i32 s11, s10, 31
	s_bfe_i64 s[30:31], s[8:9], 0x100000
	v_lshrrev_b32_e32 v5, 2, v4
	v_lshlrev_b32_e32 v6, 1, v4
	v_lshlrev_b32_e32 v3, 5, v3
	v_ashrrev_i16_sdwa v0, v193, sext(v0) dst_sel:DWORD dst_unused:UNUSED_PAD src0_sel:DWORD src1_sel:BYTE_0
	s_lshl_b64 s[4:5], s[10:11], 17
	s_lshl_b64 s[30:31], s[30:31], 17
	v_and_b32_e32 v5, 4, v5
	v_and_b32_e32 v6, 24, v6
	v_and_b32_e32 v3, 32, v3
	v_bfe_i32 v0, v0, 0, 16
	s_add_u32 s34, s24, s30
	v_or3_b32 v2, v2, v5, v6
	v_add_lshl_u32 v0, v3, v0, 1
	s_addc_u32 s35, s25, s31
	s_add_i32 s80, s29, 0
	v_lshl_add_u32 v160, v2, 9, v0
	s_add_i32 m0, s80, 0x10000
	v_lshl_add_u32 v132, v4, 9, v0
	global_load_lds_dwordx4 v160, s[34:35]
	s_add_i32 m0, s80, 0x12000
	s_add_u32 s40, s34, 0x10000
	global_load_lds_dwordx4 v128, s[34:35]
	s_addc_u32 s41, s35, 0
	s_add_i32 m0, s80, 0x14000
	v_mov_b32_e32 v129, v161
	global_load_lds_dwordx4 v160, s[40:41]
	s_add_i32 m0, s80, 0x16000
	s_add_u32 s44, s15, s4
	s_addc_u32 s45, s16, s5
	s_add_i32 s31, s80, 0x2000
	global_load_lds_dwordx4 v128, s[40:41]
	s_mov_b32 m0, s80
	s_add_u32 s4, s44, 0x10000
	global_load_lds_dwordx4 v132, s[44:45]
	s_mov_b32 m0, s31
	s_addc_u32 s5, s45, 0
	s_add_i32 s54, s80, 0x4000
	global_load_lds_dwordx4 v130, s[44:45]
	s_mov_b32 m0, s54
	s_add_i32 s66, s80, 0x6000
	global_load_lds_dwordx4 v132, s[4:5]
	s_mov_b32 m0, s66
	v_mov_b32_e32 v133, v161
	global_load_lds_dwordx4 v130, s[4:5]
	v_mov_b32_e32 v131, v161
	s_cmp_eq_u32 s21, 1
	s_movk_i32 s68, 0x85
	v_lshl_add_u64 v[6:7], s[34:35], 0, v[160:161]
	v_lshl_add_u64 v[4:5], s[34:35], 0, v[128:129]
	v_lshl_add_u64 v[0:1], s[44:45], 0, v[132:133]
	s_cselect_b64 s[4:5], -1, 0
	s_cmp_lg_u32 s21, 1
	v_lshl_add_u64 v[2:3], s[44:45], 0, v[130:131]
	s_cbranch_scc1 .LBB0_2207
	s_barrier

; #define PIN(i) ((const float*)ldq_(L, (i)))
; #define PREP_CONV(bit, SRC, Kd, Nd, DST, GK, MODE) if (mask & (bit)) { for (int it = gw; it < ((Kd) / 64) * ((Nd) / 64); it += NGW) transpose_item((SRC), (Kd), (Nd), (bf16_t*)(wl + (DST)), (GK), (MODE), scr, it, lane); }
; __device__ __forceinline__ void transpose_item(const float* W, int K, int N, bf16_t* WT, const float* gk, int mode, LAS float* scr_, int item, int lane) {
;     ...
;     const int nblk = N / 64, kb = item / nblk, nb = item % nblk, k0 = 64 * kb, n0 = 64 * nb;
;     const int sc = (mode == 1) ? (((n0 >> 7) & 1) * DFF + (n0 >> 8) * 128 + (n0 & 127)) : n0;
;     const float* src = W + (size_t)k0 * N + sc + lane;
;     float va[32], vb[32];
; #pragma unroll
;     for (int kp = 0; kp < 32; ++kp) { va[kp] = src[(size_t)(2 * kp) * N]; vb[kp] = src[(size_t)(2 * kp + 1) * N]; }
; #pragma unroll
;     for (int kp = 0; kp < 32; ++kp) {
;         float a = va[kp], b = vb[kp];
;         if (gk) { a *= gk[k0 + 2 * kp]; b *= gk[k0 + 2 * kp + 1]; }
; __device__ __forceinline__ void prep(const Params& p, LAS unsigned char* L, int wv, int vb, int nvb, int l, int mask) {
;     ...
;     PREP_CONV(PM_PEG, PIN(I_WPEG) + (size_t)l * DM * DM, DM, DM, WL_PEG, PIN(I_NPE) + l * DM, 0)
.LBB0_2394:
	v_mov_b32_e32 v6, v161
	s_nop 0
	v_add_u32_e32 v6, 0, v6
	v_add_u32_e32 v6, 0x201b0, v6
	s_nop 0
	s_waitcnt lgkmcnt(0)
	v_readlane_b32 s5, v251, 44
	v_mov_b32_e32 v6, v161
	v_readlane_b32 s4, v251, 45
	v_add_u32_e32 v6, 0, v6
	v_add_u32_e32 v6, 0x201a8, v6
	s_nop 0
	s_add_u32 s15, s5, s8
	s_addc_u32 s21, s4, s9
	s_waitcnt lgkmcnt(0)
	v_readlane_b32 s4, v251, 42
	v_readlane_b32 s5, v251, 43
	s_add_u32 s30, s4, s10
	s_addc_u32 s31, s5, s11
	s_ashr_i32 s12, s28, 31
	s_lshr_b32 s12, s12, 28
	s_add_i32 s12, s28, s12
	s_ashr_i32 s13, s12, 4
	s_lshl_b32 s12, s13, 6
	s_lshl_b32 s29, s13, 10
	s_ashr_i32 s13, s12, 31
	s_sub_i32 s14, s25, s29
	s_lshl_b64 s[18:19], s[12:13], 12
	s_add_u32 s18, s15, s18
	s_addc_u32 s19, s21, s19
	s_ashr_i32 s15, s14, 31
	s_lshl_b64 s[14:15], s[14:15], 2
	s_add_u32 s14, s18, s14
	s_addc_u32 s15, s19, s15
	v_lshl_add_u64 v[70:71], s[14:15], 0, v[160:161]
	v_add_co_u32_e32 v6, vcc, s79, v70
	global_load_dword v66, v160, s[14:15]
	s_nop 0
	v_addc_co_u32_e32 v7, vcc, 0, v71, vcc
	global_load_dword v67, v[6:7], off offset:-4096
	global_load_dword v68, v[6:7], off
	v_add_co_u32_e32 v6, vcc, s88, v70
	s_mov_b32 s14, 0x3d000
	s_nop 0
	v_addc_co_u32_e32 v7, vcc, 0, v71, vcc
	global_load_dword v69, v[6:7], off offset:-4096
	global_load_dword v62, v[6:7], off
	v_add_co_u32_e32 v6, vcc, s80, v70
	s_cmp_lg_u64 s[4:5], 0
	s_nop 0
	v_addc_co_u32_e32 v7, vcc, 0, v71, vcc
	global_load_dword v63, v[6:7], off offset:-4096
	global_load_dword v64, v[6:7], off
	v_add_co_u32_e32 v6, vcc, s70, v70
	s_mov_b64 s[18:19], -1
	s_nop 0
	v_addc_co_u32_e32 v7, vcc, 0, v71, vcc
	global_load_dword v65, v[6:7], off offset:-4096
	global_load_dword v58, v[6:7], off
	v_add_co_u32_e32 v6, vcc, s71, v70
	s_nop 1
	v_addc_co_u32_e32 v7, vcc, 0, v71, vcc
	global_load_dword v59, v[6:7], off offset:-4096
	global_load_dword v60, v[6:7], off
	v_add_co_u32_e32 v6, vcc, s91, v70
	s_nop 1
	v_addc_co_u32_e32 v7, vcc, 0, v71, vcc
	global_load_dword v61, v[6:7], off offset:-4096
	global_load_dword v54, v[6:7], off
	v_add_co_u32_e32 v6, vcc, s92, v70
	s_nop 1
	v_addc_co_u32_e32 v7, vcc, 0, v71, vcc
	global_load_dword v55, v[6:7], off offset:-4096
	global_load_dword v56, v[6:7], off
	v_add_co_u32_e32 v6, vcc, s37, v70
	s_nop 1
	v_addc_co_u32_e32 v7, vcc, 0, v71, vcc
	global_load_dword v57, v[6:7], off offset:-4096
	global_load_dword v50, v[6:7], off
	v_add_co_u32_e32 v6, vcc, s94, v70
	s_nop 1
	v_addc_co_u32_e32 v7, vcc, 0, v71, vcc
	global_load_dword v51, v[6:7], off offset:-4096
	global_load_dword v52, v[6:7], off
	v_add_co_u32_e32 v6, vcc, s46, v70
	s_nop 1
	v_addc_co_u32_e32 v7, vcc, 0, v71, vcc
	global_load_dword v53, v[6:7], off offset:-4096
	global_load_dword v46, v[6:7], off
	v_add_co_u32_e32 v6, vcc, s47, v70
	s_nop 1
	v_addc_co_u32_e32 v7, vcc, 0, v71, vcc
	global_load_dword v47, v[6:7], off offset:-4096
	global_load_dword v48, v[6:7], off
	v_add_co_u32_e32 v6, vcc, s59, v70
	s_nop 1
	v_addc_co_u32_e32 v7, vcc, 0, v71, vcc
	global_load_dword v49, v[6:7], off offset:-4096
	global_load_dword v42, v[6:7], off
	v_add_co_u32_e32 v6, vcc, s81, v70
	s_nop 1
	v_addc_co_u32_e32 v7, vcc, 0, v71, vcc
	global_load_dword v43, v[6:7], off offset:-4096
	global_load_dword v44, v[6:7], off
	v_add_co_u32_e32 v6, vcc, s83, v70
	s_nop 1
	v_addc_co_u32_e32 v7, vcc, 0, v71, vcc
	global_load_dword v45, v[6:7], off offset:-4096
	global_load_dword v38, v[6:7], off
	v_add_co_u32_e32 v6, vcc, s27, v70
	s_nop 1
	v_addc_co_u32_e32 v7, vcc, 0, v71, vcc
	global_load_dword v39, v[6:7], off offset:-4096
	global_load_dword v40, v[6:7], off
	v_add_co_u32_e32 v6, vcc, s50, v70
	s_nop 1
	v_addc_co_u32_e32 v7, vcc, 0, v71, vcc
	global_load_dword v41, v[6:7], off offset:-4096
	global_load_dword v34, v[6:7], off
	v_add_co_u32_e32 v6, vcc, s53, v70
	s_nop 1
	v_addc_co_u32_e32 v7, vcc, 0, v71, vcc
	global_load_dword v35, v[6:7], off offset:-4096
	global_load_dword v36, v[6:7], off
	v_add_co_u32_e32 v6, vcc, s0, v70
	s_nop 1
	v_addc_co_u32_e32 v7, vcc, 0, v71, vcc
	global_load_dword v37, v[6:7], off offset:-4096
	global_load_dword v30, v[6:7], off
	v_add_co_u32_e32 v6, vcc, s73, v70
	s_nop 1
	v_addc_co_u32_e32 v7, vcc, 0, v71, vcc
	global_load_dword v31, v[6:7], off offset:-4096
	global_load_dword v32, v[6:7], off
	v_add_co_u32_e32 v6, vcc, s1, v70
	s_nop 1
	v_addc_co_u32_e32 v7, vcc, 0, v71, vcc
	global_load_dword v33, v[6:7], off offset:-4096
	global_load_dword v26, v[6:7], off
	v_add_co_u32_e32 v6, vcc, s72, v70
	s_nop 1
	v_addc_co_u32_e32 v7, vcc, 0, v71, vcc
	global_load_dword v27, v[6:7], off offset:-4096
	global_load_dword v28, v[6:7], off
	v_add_co_u32_e32 v6, vcc, s82, v70
	s_nop 1
	v_addc_co_u32_e32 v7, vcc, 0, v71, vcc
	global_load_dword v29, v[6:7], off offset:-4096
	global_load_dword v22, v[6:7], off
	v_add_co_u32_e32 v6, vcc, s33, v70
	s_nop 1
	v_addc_co_u32_e32 v7, vcc, 0, v71, vcc
	global_load_dword v23, v[6:7], off offset:-4096
	global_load_dword v24, v[6:7], off
	v_add_co_u32_e32 v6, vcc, s22, v70
	s_nop 1
	v_addc_co_u32_e32 v7, vcc, 0, v71, vcc
	global_load_dword v25, v[6:7], off offset:-4096
	global_load_dword v18, v[6:7], off
	v_add_co_u32_e32 v6, vcc, s38, v70
	s_nop 1
	v_addc_co_u32_e32 v7, vcc, 0, v71, vcc
	global_load_dword v19, v[6:7], off offset:-4096
	global_load_dword v20, v[6:7], off
	v_add_co_u32_e32 v6, vcc, s39, v70
	s_nop 1
	v_addc_co_u32_e32 v7, vcc, 0, v71, vcc
	global_load_dword v21, v[6:7], off offset:-4096
	global_load_dword v14, v[6:7], off
	v_add_co_u32_e32 v6, vcc, s56, v70
	s_nop 1
	v_addc_co_u32_e32 v7, vcc, 0, v71, vcc
	global_load_dword v15, v[6:7], off offset:-4096
	global_load_dword v16, v[6:7], off
	v_add_co_u32_e32 v6, vcc, s69, v70
	s_nop 1
	v_addc_co_u32_e32 v7, vcc, 0, v71, vcc
	v_add_co_u32_e32 v8, vcc, s87, v70
	global_load_dword v17, v[6:7], off offset:-4096
	s_nop 0
	global_load_dword v6, v[6:7], off
	v_addc_co_u32_e32 v9, vcc, 0, v71, vcc
	global_load_dword v7, v[8:9], off offset:-4096
	global_load_dword v12, v[8:9], off
	v_add_co_u32_e32 v8, vcc, 0x3b000, v70
	s_nop 1
	v_addc_co_u32_e32 v9, vcc, 0, v71, vcc
	v_add_co_u32_e32 v10, vcc, s14, v70
	global_load_dword v13, v[8:9], off
	s_nop 0
	v_addc_co_u32_e32 v11, vcc, 0, v71, vcc
	global_load_dword v8, v[10:11], off offset:-4096
	global_load_dword v9, v[10:11], off
	v_add_co_u32_e32 v10, vcc, 0x3e000, v70
	s_cselect_b64 s[14:15], -1, 0
	s_nop 0
	v_addc_co_u32_e32 v11, vcc, 0, v71, vcc
	v_add_co_u32_e32 v70, vcc, 0x3f000, v70
	global_load_dword v10, v[10:11], off
	s_nop 0
	v_addc_co_u32_e32 v71, vcc, 0, v71, vcc
	global_load_dword v11, v[70:71], off
	s_cmp_eq_u64 s[4:5], 0
	s_cbranch_scc1 .LBB0_2396
	s_lshl_b64 s[4:5], s[12:13], 2
	s_add_u32 s4, s30, s4
	s_addc_u32 s5, s31, s5
	global_load_dwordx4 v[70:73], v161, s[4:5]
	s_mov_b64 s[18:19], 0
	s_waitcnt vmcnt(0)
	v_pk_mul_f32 v[70:71], v[66:67], v[70:71]
	v_pk_mul_f32 v[72:73], v[68:69], v[72:73]
